# k36: non-temporal hint on the once-read streaming row loads of the row-wise phases (gain-vector loads keep the default policy)
# speedup vs baseline: 1.0276x; 1.0276x over previous
.LBB0_57:
	s_and_b32 s17, s1, 0x7ff
	s_ashr_i32 s7, s6, 31
	s_cmp_lg_u32 s17, 0
	s_cselect_b64 s[8:9], -1, 0
	v_cndmask_b32_e64 v18, 0, 1, s[8:9]
	v_mov_b32_e32 v19, s7
	s_lshl_b64 s[8:9], s[6:7], 12
	v_sub_co_u32_e32 v18, vcc, s6, v18
	s_add_u32 s8, s36, s8
	s_nop 0
	v_subbrev_co_u32_e32 v19, vcc, 0, v19, vcc
	v_lshlrev_b64 v[18:19], 12, v[18:19]
	s_addc_u32 s9, s37, s9
	global_load_dwordx4 v[50:53], v1, s[8:9] nt
	global_load_dwordx4 v[66:69], v1, s[8:9] offset:16 nt
	global_load_dwordx4 v[74:77], v1, s[8:9] offset:2064 nt
	global_load_dwordx4 v[70:73], v1, s[8:9] offset:2048 nt
	v_lshl_add_u64 v[18:19], v[116:117], 0, v[18:19]
	s_add_u32 s10, s8, 0x1000
	global_load_dwordx4 v[62:65], v[18:19], off nt
	global_load_dwordx4 v[54:57], v[18:19], off offset:16 nt
	global_load_dwordx4 v[46:49], v[18:19], off offset:2064 nt
	global_load_dwordx4 v[58:61], v[18:19], off offset:2048 nt
	s_addc_u32 s11, s9, 0
	global_load_dwordx4 v[30:33], v1, s[10:11] nt
	global_load_dwordx4 v[34:37], v1, s[10:11] offset:16 nt
	global_load_dwordx4 v[42:45], v172, s[10:11] offset:16 nt
	global_load_dwordx4 v[38:41], v172, s[10:11] nt
	s_add_u32 s10, s8, 0x2000
	s_addc_u32 s11, s9, 0
	global_load_dwordx4 v[18:21], v1, s[10:11] nt
	global_load_dwordx4 v[22:25], v1, s[10:11] offset:16 nt
	global_load_dwordx4 v[26:29], v172, s[10:11] nt
	global_load_dwordx4 v[86:89], v172, s[10:11] offset:16 nt
	s_add_u32 s8, s8, 0x3000
	s_addc_u32 s9, s9, 0
	global_load_dwordx4 v[78:81], v1, s[8:9] offset:16 nt
	global_load_dwordx4 v[82:85], v1, s[8:9] nt
	global_load_dwordx4 v[90:93], v172, s[8:9] nt
	global_load_dwordx4 v[94:97], v172, s[8:9] offset:16 nt
	s_cmp_eq_u32 s17, 0
	s_waitcnt vmcnt(19)
	v_pk_mul_f32 v[118:119], v[52:53], v[52:53]
	v_pk_mul_f32 v[120:121], v[50:51], v[50:51]
	s_waitcnt vmcnt(18)
	v_pk_mul_f32 v[122:123], v[68:69], v[68:69]
	v_pk_mul_f32 v[124:125], v[66:67], v[66:67]
	s_waitcnt vmcnt(16)
	v_mul_f32_e32 v126, v71, v71
	v_mul_f32_e32 v128, v73, v73
	v_mul_f32_e32 v141, v76, v76
	v_mul_f32_e32 v144, v77, v77
	s_waitcnt vmcnt(15)
	v_pk_mul_f32 v[130:131], v[64:65], v[64:65]
	v_pk_mul_f32 v[132:133], v[62:63], v[62:63]
	s_waitcnt vmcnt(14)
	v_pk_mul_f32 v[134:135], v[56:57], v[56:57]
	v_pk_mul_f32 v[136:137], v[54:55], v[54:55]
	v_pk_mov_b32 v[138:139], v[120:121], v[118:119] op_sel:[1,0]
	v_mov_b32_e32 v121, v119
	v_pk_mov_b32 v[118:119], v[124:125], v[122:123] op_sel:[1,0]
	v_mov_b32_e32 v125, v123
	s_waitcnt vmcnt(12)
	v_mul_f32_e32 v122, v59, v59
	v_mul_f32_e32 v140, v61, v61
	v_pk_fma_f32 v[126:127], v[70:71], v[70:71], v[126:127] op_sel_hi:[1,1,0]
	v_pk_fma_f32 v[128:129], v[72:73], v[72:73], v[128:129] op_sel_hi:[1,1,0]
	v_mul_f32_e32 v156, v48, v48
	v_mul_f32_e32 v157, v49, v49
	v_mul_f32_e32 v147, v46, v46
	v_mul_f32_e32 v149, v47, v47
	v_pk_mov_b32 v[142:143], v[132:133], v[130:131] op_sel:[1,0]
	v_mov_b32_e32 v133, v131
	v_pk_mov_b32 v[130:131], v[136:137], v[134:135] op_sel:[1,0]
	v_mov_b32_e32 v137, v135
	v_pk_add_f32 v[134:135], v[138:139], v[120:121]
	v_pk_add_f32 v[118:119], v[118:119], v[124:125]
	v_pk_fma_f32 v[122:123], v[58:59], v[58:59], v[122:123] op_sel_hi:[1,1,0]
	v_pk_fma_f32 v[138:139], v[60:61], v[60:61], v[140:141] op_sel_hi:[1,1,0]
	v_mov_b32_e32 v127, v141
	v_mov_b32_e32 v129, v144
	s_waitcnt vmcnt(11)
	v_pk_mul_f32 v[124:125], v[32:33], v[32:33]
	v_pk_mul_f32 v[140:141], v[30:31], v[30:31]
	s_waitcnt vmcnt(10)
	v_pk_mul_f32 v[144:145], v[36:37], v[36:37]
	v_pk_mul_f32 v[152:153], v[34:35], v[34:35]
	s_waitcnt vmcnt(8)
	v_mul_f32_e32 v146, v39, v39
	v_mul_f32_e32 v148, v41, v41
	v_mul_f32_e32 v158, v74, v74
	v_mul_f32_e32 v159, v75, v75
	v_mul_f32_e32 v160, v44, v44
	v_mul_f32_e32 v161, v45, v45
	v_pk_add_f32 v[142:143], v[142:143], v[132:133]
	v_pk_add_f32 v[154:155], v[130:131], v[136:137]
	v_mov_b32_e32 v123, v156
	v_mov_b32_e32 v139, v157
	v_pk_add_f32 v[120:121], v[126:127], v[128:129]
	v_pk_mov_b32 v[126:127], v[140:141], v[124:125] op_sel:[1,0]
	v_mov_b32_e32 v141, v125
	v_pk_mov_b32 v[156:157], v[152:153], v[144:145] op_sel:[1,0]
	v_mov_b32_e32 v153, v145
	v_pk_add_f32 v[124:125], v[134:135], v[134:135] op_sel:[0,1] op_sel_hi:[1,0]
	v_pk_add_f32 v[132:133], v[118:119], v[118:119] op_sel:[0,1] op_sel_hi:[1,0]
	v_pk_fma_f32 v[130:131], v[38:39], v[38:39], v[146:147] op_sel_hi:[1,1,0]
	v_pk_fma_f32 v[136:137], v[40:41], v[40:41], v[148:149] op_sel_hi:[1,1,0]
	v_pk_add_f32 v[118:119], v[122:123], v[138:139]
	v_pk_add_f32 v[128:129], v[126:127], v[140:141]
	v_mov_b32_e32 v125, v158
	v_pk_add_f32 v[134:135], v[156:157], v[152:153]
	v_mov_b32_e32 v133, v159
	v_mov_b32_e32 v131, v160
	v_mov_b32_e32 v137, v161
	v_pk_add_f32 v[122:123], v[142:143], v[142:143] op_sel:[0,1] op_sel_hi:[1,0]
	v_pk_add_f32 v[126:127], v[154:155], v[154:155] op_sel:[0,1] op_sel_hi:[1,0]
	s_waitcnt vmcnt(7)
	v_pk_mul_f32 v[142:143], v[20:21], v[20:21]
	v_pk_mul_f32 v[138:139], v[18:19], v[18:19]
	s_waitcnt vmcnt(6)
	v_pk_mul_f32 v[144:145], v[24:25], v[24:25]
	v_pk_mul_f32 v[140:141], v[22:23], v[22:23]
	v_mul_f32_e32 v150, v42, v42
	v_mul_f32_e32 v151, v43, v43
	s_waitcnt vmcnt(5)
	v_mul_f32_e32 v146, v27, v27
	v_pk_add_f32 v[124:125], v[124:125], v[132:133]
	v_pk_add_f32 v[130:131], v[130:131], v[136:137]
	v_mov_b32_e32 v123, v147
	v_mov_b32_e32 v127, v149
	v_pk_add_f32 v[128:129], v[128:129], v[128:129] op_sel:[0,1] op_sel_hi:[1,0]
	v_pk_add_f32 v[132:133], v[134:135], v[134:135] op_sel:[0,1] op_sel_hi:[1,0]
	v_pk_mov_b32 v[134:135], v[138:139], v[142:143] op_sel:[1,0]
	v_mov_b32_e32 v139, v143
	v_pk_mov_b32 v[136:137], v[140:141], v[144:145] op_sel:[1,0]
	v_mov_b32_e32 v141, v145
	s_waitcnt vmcnt(4)
	v_mul_f32_e32 v152, v88, v88
	v_mul_f32_e32 v148, v29, v29
	v_pk_fma_f32 v[142:143], v[26:27], v[26:27], v[146:147] op_sel_hi:[1,1,0]
	v_pk_add_f32 v[122:123], v[122:123], v[126:127]
	v_pk_add_f32 v[120:121], v[124:125], v[120:121]
	v_mov_b32_e32 v129, v150
	v_mov_b32_e32 v133, v151
	v_pk_add_f32 v[124:125], v[134:135], v[138:139]
	v_pk_add_f32 v[126:127], v[136:137], v[140:141]
	v_mul_f32_e32 v153, v89, v89
	v_mul_f32_e32 v154, v86, v86
	v_mul_f32_e32 v155, v87, v87
	v_pk_fma_f32 v[144:145], v[28:29], v[28:29], v[148:149] op_sel_hi:[1,1,0]
	v_mov_b32_e32 v143, v152
	s_waitcnt vmcnt(2)
	v_pk_mul_f32 v[134:135], v[84:85], v[84:85]
	v_pk_mul_f32 v[136:137], v[82:83], v[82:83]
	v_pk_mul_f32 v[138:139], v[80:81], v[80:81]
	v_pk_mul_f32 v[140:141], v[78:79], v[78:79]
	v_pk_add_f32 v[118:119], v[122:123], v[118:119]
	v_add_f32_e32 v152, v120, v121
	v_pk_add_f32 v[120:121], v[128:129], v[132:133]
	v_pk_add_f32 v[124:125], v[124:125], v[124:125] op_sel:[0,1] op_sel_hi:[1,0]
	v_pk_add_f32 v[126:127], v[126:127], v[126:127] op_sel:[0,1] op_sel_hi:[1,0]
	v_mov_b32_e32 v145, v153
	v_pk_mov_b32 v[128:129], v[136:137], v[134:135] op_sel:[1,0]
	v_mov_b32_e32 v137, v135
	v_pk_mov_b32 v[132:133], v[140:141], v[138:139] op_sel:[1,0]
	v_mov_b32_e32 v141, v139
	v_pk_add_f32 v[120:121], v[120:121], v[130:131]
	v_add_f32_e32 v130, v118, v119
	v_add_f32_dpp v131, v152, v152 quad_perm:[1,0,3,2] row_mask:0xf bank_mask:0xf bound_ctrl:1
	v_mov_b32_e32 v125, v154
	v_mov_b32_e32 v127, v155
	s_waitcnt vmcnt(1)
	v_mul_f32_e32 v146, v91, v91
	s_waitcnt vmcnt(0)
	v_mul_f32_e32 v147, v96, v96
	v_mul_f32_e32 v148, v93, v93
	v_mul_f32_e32 v149, v97, v97
	v_pk_add_f32 v[122:123], v[142:143], v[144:145]
	v_pk_add_f32 v[118:119], v[128:129], v[136:137]
	v_pk_add_f32 v[128:129], v[132:133], v[140:141]
	v_add_f32_dpp v130, v130, v130 quad_perm:[1,0,3,2] row_mask:0xf bank_mask:0xf bound_ctrl:1
	v_add_f32_dpp v131, v131, v131 quad_perm:[2,3,0,1] row_mask:0xf bank_mask:0xf bound_ctrl:1
	v_add_f32_e32 v132, v120, v121
	v_pk_add_f32 v[120:121], v[124:125], v[126:127]
	v_mul_f32_e32 v150, v94, v94
	v_mul_f32_e32 v151, v95, v95
	v_pk_fma_f32 v[134:135], v[90:91], v[90:91], v[146:147] op_sel_hi:[1,1,0]
	v_pk_fma_f32 v[138:139], v[92:93], v[92:93], v[148:149] op_sel_hi:[1,1,0]
	v_pk_add_f32 v[118:119], v[118:119], v[118:119] op_sel:[0,1] op_sel_hi:[1,0]
	v_pk_add_f32 v[126:127], v[128:129], v[128:129] op_sel:[0,1] op_sel_hi:[1,0]
	v_add_f32_dpp v128, v130, v130 quad_perm:[2,3,0,1] row_mask:0xf bank_mask:0xf bound_ctrl:1
	v_add_f32_dpp v129, v131, v131 row_half_mirror row_mask:0xf bank_mask:0xf bound_ctrl:1
	v_add_f32_dpp v130, v132, v132 quad_perm:[1,0,3,2] row_mask:0xf bank_mask:0xf bound_ctrl:1
	v_pk_add_f32 v[120:121], v[120:121], v[122:123]
	v_mov_b32_e32 v135, v147
	v_mov_b32_e32 v139, v149
	v_mov_b32_e32 v119, v150
	v_mov_b32_e32 v127, v151
	v_add_f32_dpp v122, v128, v128 row_half_mirror row_mask:0xf bank_mask:0xf bound_ctrl:1
	v_add_f32_dpp v123, v129, v129 row_mirror row_mask:0xf bank_mask:0xf bound_ctrl:1
	v_add_f32_dpp v128, v130, v130 quad_perm:[2,3,0,1] row_mask:0xf bank_mask:0xf bound_ctrl:1
	v_add_f32_e32 v120, v120, v121
	v_pk_add_f32 v[124:125], v[134:135], v[138:139]
	v_pk_add_f32 v[118:119], v[118:119], v[126:127]
	v_add_f32_dpp v121, v122, v122 row_mirror row_mask:0xf bank_mask:0xf bound_ctrl:1
	v_readlane_b32 s8, v123, 0
	v_readlane_b32 s17, v123, 16
	v_readlane_b32 s9, v123, 32
	v_readlane_b32 s18, v123, 48
	v_add_f32_dpp v122, v128, v128 row_half_mirror row_mask:0xf bank_mask:0xf bound_ctrl:1
	v_add_f32_dpp v123, v120, v120 quad_perm:[1,0,3,2] row_mask:0xf bank_mask:0xf bound_ctrl:1
	v_pk_add_f32 v[118:119], v[118:119], v[124:125]
	v_readlane_b32 s10, v121, 0
	v_readlane_b32 s19, v121, 16
	v_readlane_b32 s11, v121, 32
	v_readlane_b32 s20, v121, 48
	v_mov_b32_e32 v120, s17
	v_mov_b32_e32 v121, s18
	v_add_f32_dpp v122, v122, v122 row_mirror row_mask:0xf bank_mask:0xf bound_ctrl:1
	v_add_f32_dpp v123, v123, v123 quad_perm:[2,3,0,1] row_mask:0xf bank_mask:0xf bound_ctrl:1
	v_add_f32_e32 v124, v118, v119
	v_pk_add_f32 v[118:119], s[8:9], v[120:121]
	v_mov_b32_e32 v120, s19
	v_mov_b32_e32 v121, s20
	v_readlane_b32 s8, v122, 0
	v_readlane_b32 s17, v122, 16
	v_readlane_b32 s9, v122, 32
	v_readlane_b32 s18, v122, 48
	v_add_f32_dpp v122, v123, v123 row_half_mirror row_mask:0xf bank_mask:0xf bound_ctrl:1
	v_add_f32_dpp v123, v124, v124 quad_perm:[1,0,3,2] row_mask:0xf bank_mask:0xf bound_ctrl:1
	v_add_f32_e32 v124, v118, v119
	v_pk_add_f32 v[118:119], s[10:11], v[120:121]
	v_mov_b32_e32 v120, s17
	v_mov_b32_e32 v121, s18
	v_add_f32_dpp v122, v122, v122 row_mirror row_mask:0xf bank_mask:0xf bound_ctrl:1
	v_add_f32_dpp v123, v123, v123 quad_perm:[2,3,0,1] row_mask:0xf bank_mask:0xf bound_ctrl:1
	v_add_f32_e32 v125, v118, v119
	v_pk_add_f32 v[118:119], s[8:9], v[120:121]
	v_readlane_b32 s10, v122, 16
	v_readlane_b32 s11, v122, 48
	v_fmamk_f32 v124, v124, 0x3a800000, v173
	v_readlane_b32 s8, v122, 0
	v_readlane_b32 s9, v122, 32
	v_add_f32_dpp v121, v123, v123 row_half_mirror row_mask:0xf bank_mask:0xf bound_ctrl:1
	v_fmamk_f32 v122, v125, 0x3a800000, v173
	v_add_f32_e32 v123, v118, v119
	v_mov_b32_e32 v118, s10
	v_mov_b32_e32 v119, s11
	v_rsq_f32_e32 v120, v124
	v_add_f32_dpp v121, v121, v121 row_mirror row_mask:0xf bank_mask:0xf bound_ctrl:1
	v_rsq_f32_e32 v122, v122
	v_fmamk_f32 v123, v123, 0x3a800000, v173
	v_pk_add_f32 v[118:119], s[8:9], v[118:119]
	v_readlane_b32 s10, v121, 0
	v_readlane_b32 s17, v121, 16
	v_readlane_b32 s11, v121, 32
	v_readlane_b32 s18, v121, 48
	v_rsq_f32_e32 v124, v123
	v_add_f32_e32 v121, v118, v119
	v_fmamk_f32 v121, v121, 0x3a800000, v173
	v_mov_b32_e32 v118, s17
	v_mov_b32_e32 v119, s18
	v_rsq_f32_e32 v174, v121
	v_pk_add_f32 v[118:119], s[10:11], v[118:119]
	v_pk_mul_f32 v[168:169], v[120:121], v[68:69] op_sel_hi:[0,1]
	v_pk_mul_f32 v[66:67], v[120:121], v[66:67] op_sel_hi:[0,1]
	v_pk_mul_f32 v[52:53], v[120:121], v[52:53] op_sel_hi:[0,1]
	v_pk_mul_f32 v[50:51], v[120:121], v[50:51] op_sel_hi:[0,1]
	v_pk_mul_f32 v[64:65], v[122:123], v[64:65] op_sel_hi:[0,1]
	v_pk_mul_f32 v[62:63], v[122:123], v[62:63] op_sel_hi:[0,1]
	s_cselect_b64 s[10:11], -1, 0
	s_lshl_b64 s[8:9], s[6:7], 11
	v_pk_mul_f32 v[76:77], v[120:121], v[76:77] op_sel_hi:[0,1]
	v_pk_mul_f32 v[142:143], v[120:121], v[74:75] op_sel_hi:[0,1]
	v_pk_mul_f32 v[164:165], v[120:121], v[72:73] op_sel_hi:[0,1]
	v_pk_mul_f32 v[166:167], v[120:121], v[70:71] op_sel_hi:[0,1]
	v_pk_mul_f32 v[152:153], v[50:51], v[6:7]
	v_pk_mul_f32 v[160:161], v[52:53], v[8:9]
	v_pk_mul_f32 v[150:151], v[66:67], v[2:3]
	v_pk_mul_f32 v[158:159], v[168:169], v[4:5]
	v_pk_mul_f32 v[198:199], v[124:125], v[36:37] op_sel_hi:[0,1]
	v_pk_mul_f32 v[200:201], v[124:125], v[34:35] op_sel_hi:[0,1]
	v_pk_mul_f32 v[202:203], v[124:125], v[32:33] op_sel_hi:[0,1]
	v_pk_mul_f32 v[204:205], v[124:125], v[30:31] op_sel_hi:[0,1]
	v_pk_mul_f32 v[34:35], v[64:65], v[8:9]
	v_cvt_pk_bf16_f32 v30, v152, v153
	v_cvt_pk_bf16_f32 v31, v160, v161
	v_cvt_pk_bf16_f32 v32, v150, v151
	v_cvt_pk_bf16_f32 v33, v158, v159
	v_pk_mul_f32 v[36:37], v[62:63], v[6:7]
	v_lshl_add_u64 v[162:163], v[98:99], 0, s[8:9]
	v_pk_mul_f32 v[148:149], v[166:167], v[14:15]
	v_pk_mul_f32 v[156:157], v[164:165], v[16:17]
	v_pk_mul_f32 v[146:147], v[142:143], v[10:11]
	v_pk_mul_f32 v[154:155], v[76:77], v[12:13]
	v_cndmask_b32_e64 v35, v35, 0, s[10:11]
	v_cndmask_b32_e64 v34, v34, 0, s[10:11]
	v_cndmask_b32_e64 v37, v37, 0, s[10:11]
	v_cndmask_b32_e64 v36, v36, 0, s[10:11]
	global_store_dwordx4 v[162:163], v[30:33], off
	v_pk_fma_f32 v[208:209], v[50:51], v[6:7], v[36:37] neg_lo:[1,0,0] neg_hi:[1,0,0]
	v_pk_fma_f32 v[210:211], v[52:53], v[8:9], v[34:35] neg_lo:[1,0,0] neg_hi:[1,0,0]
	v_cvt_pk_bf16_f32 v30, v148, v149
	v_cvt_pk_bf16_f32 v31, v156, v157
	v_cvt_pk_bf16_f32 v32, v146, v147
	v_cvt_pk_bf16_f32 v33, v154, v155
	global_store_dwordx4 v[162:163], v[30:33], off offset:1024
	v_pk_mul_f32 v[36:37], v[174:175], v[86:87] op_sel_hi:[0,1]
	v_pk_mul_f32 v[34:35], v[174:175], v[88:89] op_sel_hi:[0,1]
	v_pk_mul_f32 v[26:27], v[174:175], v[26:27] op_sel_hi:[0,1]
	v_pk_mul_f32 v[28:29], v[174:175], v[28:29] op_sel_hi:[0,1]
	v_pk_mul_f32 v[22:23], v[174:175], v[22:23] op_sel_hi:[0,1]
	v_pk_mul_f32 v[24:25], v[174:175], v[24:25] op_sel_hi:[0,1]
	v_pk_mul_f32 v[18:19], v[174:175], v[18:19] op_sel_hi:[0,1]
	v_pk_mul_f32 v[20:21], v[174:175], v[20:21] op_sel_hi:[0,1]
	global_load_dwordx4 v[174:177], v[102:103], off
	global_load_dwordx4 v[178:181], v[102:103], off offset:16
	global_load_dwordx4 v[182:185], v[102:103], off offset:2048
	global_load_dwordx4 v[186:189], v[102:103], off offset:2064
	v_pk_mul_f32 v[56:57], v[122:123], v[56:57] op_sel_hi:[0,1]
	v_pk_mul_f32 v[54:55], v[122:123], v[54:55] op_sel_hi:[0,1]
	v_pk_mul_f32 v[60:61], v[122:123], v[60:61] op_sel_hi:[0,1]
	v_pk_mul_f32 v[58:59], v[122:123], v[58:59] op_sel_hi:[0,1]
	v_pk_mul_f32 v[48:49], v[122:123], v[48:49] op_sel_hi:[0,1]
	v_pk_mul_f32 v[46:47], v[122:123], v[46:47] op_sel_hi:[0,1]
	v_pk_mul_f32 v[194:195], v[124:125], v[40:41] op_sel_hi:[0,1]
	v_pk_mul_f32 v[196:197], v[124:125], v[38:39] op_sel_hi:[0,1]
	v_pk_mul_f32 v[38:39], v[56:57], v[4:5]
	v_pk_mul_f32 v[40:41], v[54:55], v[2:3]
	v_pk_mul_f32 v[190:191], v[124:125], v[44:45] op_sel_hi:[0,1]
	v_pk_mul_f32 v[192:193], v[124:125], v[42:43] op_sel_hi:[0,1]
	v_pk_mul_f32 v[42:43], v[60:61], v[16:17]
	v_pk_mul_f32 v[44:45], v[58:59], v[14:15]
	v_pk_mul_f32 v[48:49], v[48:49], v[12:13]
	v_pk_mul_f32 v[46:47], v[46:47], v[10:11]
	v_cndmask_b32_e64 v39, v39, 0, s[10:11]
	v_cndmask_b32_e64 v38, v38, 0, s[10:11]
	v_cndmask_b32_e64 v41, v41, 0, s[10:11]
	v_cndmask_b32_e64 v40, v40, 0, s[10:11]
	v_cndmask_b32_e64 v43, v43, 0, s[10:11]
	v_cndmask_b32_e64 v42, v42, 0, s[10:11]
	v_cndmask_b32_e64 v45, v45, 0, s[10:11]
	v_cndmask_b32_e64 v44, v44, 0, s[10:11]
	v_cndmask_b32_e64 v49, v49, 0, s[10:11]
	v_cndmask_b32_e64 v48, v48, 0, s[10:11]
	v_cndmask_b32_e64 v47, v47, 0, s[10:11]
	v_cndmask_b32_e64 v46, v46, 0, s[10:11]
	v_pk_fma_f32 v[212:213], v[66:67], v[2:3], v[40:41] neg_lo:[1,0,0] neg_hi:[1,0,0]
	v_pk_fma_f32 v[214:215], v[168:169], v[4:5], v[38:39] neg_lo:[1,0,0] neg_hi:[1,0,0]
	v_lshl_add_u64 v[144:145], v[100:101], 0, s[8:9]
	v_pk_fma_f32 v[216:217], v[166:167], v[14:15], v[44:45] neg_lo:[1,0,0] neg_hi:[1,0,0]
	v_pk_fma_f32 v[218:219], v[164:165], v[16:17], v[42:43] neg_lo:[1,0,0] neg_hi:[1,0,0]
	v_pk_fma_f32 v[220:221], v[142:143], v[10:11], v[46:47] neg_lo:[1,0,0] neg_hi:[1,0,0]
	v_pk_fma_f32 v[222:223], v[76:77], v[12:13], v[48:49] neg_lo:[1,0,0] neg_hi:[1,0,0]
	v_add_co_u32_e32 v170, vcc, s14, v144
	v_add_f32_e32 v68, v118, v119
	s_nop 0
	v_addc_co_u32_e32 v171, vcc, 0, v145, vcc
	v_add_co_u32_e32 v168, vcc, s15, v144
	v_pk_fma_f32 v[126:127], v[204:205], v[6:7], v[152:153] neg_lo:[1,0,0] neg_hi:[1,0,0]
	s_nop 0
	v_addc_co_u32_e32 v169, vcc, 0, v145, vcc
	v_add_co_u32_e32 v164, vcc, s16, v144
	v_pk_fma_f32 v[134:135], v[202:203], v[8:9], v[160:161] neg_lo:[1,0,0] neg_hi:[1,0,0]
	v_pk_fma_f32 v[128:129], v[200:201], v[2:3], v[150:151] neg_lo:[1,0,0] neg_hi:[1,0,0]
	v_pk_fma_f32 v[136:137], v[198:199], v[4:5], v[158:159] neg_lo:[1,0,0] neg_hi:[1,0,0]
	v_pk_fma_f32 v[130:131], v[196:197], v[14:15], v[148:149] neg_lo:[1,0,0] neg_hi:[1,0,0]
	v_pk_fma_f32 v[132:133], v[192:193], v[10:11], v[146:147] neg_lo:[1,0,0] neg_hi:[1,0,0]
	v_addc_co_u32_e32 v165, vcc, 0, v145, vcc
	v_fmamk_f32 v68, v68, 0x3a800000, v173
	v_pk_fma_f32 v[138:139], v[194:195], v[16:17], v[156:157] neg_lo:[1,0,0] neg_hi:[1,0,0]
	v_pk_fma_f32 v[140:141], v[190:191], v[12:13], v[154:155] neg_lo:[1,0,0] neg_hi:[1,0,0]
	v_rsq_f32_e32 v206, v68
	v_pk_mul_f32 v[68:69], v[200:201], v[2:3]
	v_pk_mul_f32 v[74:75], v[204:205], v[6:7]
	v_pk_mul_f32 v[124:125], v[202:203], v[8:9]
	v_pk_mul_f32 v[122:123], v[198:199], v[4:5]
	v_pk_mul_f32 v[72:73], v[196:197], v[14:15]
	v_pk_mul_f32 v[120:121], v[194:195], v[16:17]
	v_pk_mul_f32 v[70:71], v[192:193], v[10:11]
	v_pk_mul_f32 v[118:119], v[190:191], v[12:13]
	s_or_b32 s10, s8, 0x1000
	s_mov_b32 s11, s9
	v_lshl_add_u64 v[166:167], v[98:99], 0, s[10:11]
	v_pk_mul_f32 v[42:43], v[24:25], v[4:5]
	v_pk_mul_f32 v[44:45], v[22:23], v[2:3]
	v_pk_mul_f32 v[46:47], v[20:21], v[8:9]
	v_pk_mul_f32 v[48:49], v[18:19], v[6:7]
	v_pk_mul_f32 v[34:35], v[34:35], v[12:13]
	v_pk_mul_f32 v[36:37], v[36:37], v[10:11]
	v_pk_mul_f32 v[38:39], v[28:29], v[16:17]
	s_waitcnt vmcnt(3)
	v_pk_fma_f32 v[176:177], v[176:177], v[210:211], v[160:161]
	v_pk_fma_f32 v[174:175], v[174:175], v[208:209], v[152:153]
	s_waitcnt vmcnt(2)
	v_pk_fma_f32 v[180:181], v[180:181], v[214:215], v[158:159]
	v_pk_fma_f32 v[178:179], v[178:179], v[212:213], v[150:151]
	v_cvt_pk_bf16_f32 v174, v174, v175
	v_cvt_pk_bf16_f32 v175, v176, v177
	s_waitcnt vmcnt(1)
	v_pk_fma_f32 v[184:185], v[184:185], v[218:219], v[156:157]
	v_cvt_pk_bf16_f32 v176, v178, v179
	v_cvt_pk_bf16_f32 v177, v180, v181
	v_pk_fma_f32 v[182:183], v[182:183], v[216:217], v[148:149]
	s_waitcnt vmcnt(0)
	v_pk_fma_f32 v[188:189], v[188:189], v[222:223], v[154:155]
	v_pk_fma_f32 v[186:187], v[186:187], v[220:221], v[146:147]
	global_store_dwordx4 v[144:145], v[174:177], off
	v_pk_mul_f32 v[40:41], v[26:27], v[14:15]
	v_pk_mul_f32 v[58:59], v[206:207], v[90:91] op_sel_hi:[0,1]
	v_cvt_pk_bf16_f32 v174, v182, v183
	v_cvt_pk_bf16_f32 v175, v184, v185
	v_cvt_pk_bf16_f32 v176, v186, v187
	v_cvt_pk_bf16_f32 v177, v188, v189
	global_store_dwordx4 v[144:145], v[174:177], off offset:1024
	global_load_dwordx4 v[174:177], v[104:105], off
	s_nop 0
	global_load_dwordx4 v[178:181], v[104:105], off offset:16
	global_load_dwordx4 v[182:185], v[106:107], off
	global_load_dwordx4 v[186:189], v[106:107], off offset:16
	v_pk_mul_f32 v[62:63], v[206:207], v[78:79] op_sel_hi:[0,1]
	v_pk_fma_f32 v[78:79], v[204:205], v[6:7], v[48:49] neg_lo:[0,0,1] neg_hi:[0,0,1]
	v_pk_fma_f32 v[90:91], v[202:203], v[8:9], v[46:47] neg_lo:[0,0,1] neg_hi:[0,0,1]
	v_pk_mul_f32 v[54:55], v[206:207], v[92:93] op_sel_hi:[0,1]
	v_pk_mul_f32 v[60:61], v[206:207], v[80:81] op_sel_hi:[0,1]
	v_pk_fma_f32 v[80:81], v[200:201], v[2:3], v[44:45] neg_lo:[0,0,1] neg_hi:[0,0,1]
	v_pk_fma_f32 v[92:93], v[198:199], v[4:5], v[42:43] neg_lo:[0,0,1] neg_hi:[0,0,1]
	v_lshl_add_u64 v[142:143], v[100:101], 0, s[10:11]
	v_pk_mul_f32 v[50:51], v[206:207], v[96:97] op_sel_hi:[0,1]
	v_pk_mul_f32 v[52:53], v[206:207], v[94:95] op_sel_hi:[0,1]
	v_pk_mul_f32 v[64:65], v[206:207], v[84:85] op_sel_hi:[0,1]
	v_pk_mul_f32 v[66:67], v[206:207], v[82:83] op_sel_hi:[0,1]
	v_pk_fma_f32 v[82:83], v[196:197], v[14:15], v[40:41] neg_lo:[0,0,1] neg_hi:[0,0,1]
	v_pk_fma_f32 v[94:95], v[194:195], v[16:17], v[38:39] neg_lo:[0,0,1] neg_hi:[0,0,1]
	v_pk_fma_f32 v[84:85], v[192:193], v[10:11], v[36:37] neg_lo:[0,0,1] neg_hi:[0,0,1]
	v_pk_fma_f32 v[96:97], v[190:191], v[12:13], v[34:35] neg_lo:[0,0,1] neg_hi:[0,0,1]
	v_add_co_u32_e32 v88, vcc, s14, v142
	s_or_b32 s8, s8, 0x1800
	s_nop 0
	v_addc_co_u32_e32 v89, vcc, 0, v143, vcc
	v_add_co_u32_e32 v86, vcc, s15, v142
	v_lshl_add_u64 v[56:57], v[98:99], 0, s[8:9]
	s_nop 0
	v_addc_co_u32_e32 v87, vcc, 0, v143, vcc
	v_add_co_u32_e32 v76, vcc, s16, v142
	v_pk_mul_f32 v[26:27], v[62:63], v[2:3]
	s_nop 0
	v_addc_co_u32_e32 v77, vcc, 0, v143, vcc
	v_pk_mul_f32 v[28:29], v[60:61], v[4:5]
	v_pk_mul_f32 v[30:31], v[66:67], v[6:7]
	v_pk_mul_f32 v[32:33], v[64:65], v[8:9]
	v_pk_mul_f32 v[18:19], v[52:53], v[10:11]
	v_pk_mul_f32 v[20:21], v[50:51], v[12:13]
	v_pk_mul_f32 v[22:23], v[58:59], v[14:15]
	v_pk_mul_f32 v[24:25], v[54:55], v[16:17]
	s_addk_i32 s1, 0xff00
	s_addk_i32 s6, 0xfc00
	s_cmp_lt_i32 s1, s0
	s_waitcnt vmcnt(3)
	v_pk_fma_f32 v[176:177], v[176:177], v[210:211], v[160:161]
	v_pk_fma_f32 v[174:175], v[174:175], v[208:209], v[152:153]
	s_waitcnt vmcnt(2)
	v_pk_fma_f32 v[180:181], v[180:181], v[214:215], v[158:159]
	v_pk_fma_f32 v[178:179], v[178:179], v[212:213], v[150:151]
	v_cvt_pk_bf16_f32 v174, v174, v175
	v_cvt_pk_bf16_f32 v175, v176, v177
	s_waitcnt vmcnt(1)
	v_pk_fma_f32 v[184:185], v[184:185], v[218:219], v[156:157]
	v_cvt_pk_bf16_f32 v176, v178, v179
	v_cvt_pk_bf16_f32 v177, v180, v181
	v_pk_fma_f32 v[182:183], v[182:183], v[216:217], v[148:149]
	s_waitcnt vmcnt(0)
	v_pk_fma_f32 v[188:189], v[188:189], v[222:223], v[154:155]
	v_pk_fma_f32 v[186:187], v[186:187], v[220:221], v[146:147]
	global_store_dwordx4 v[170:171], v[174:177], off
	s_nop 1
	v_cvt_pk_bf16_f32 v174, v182, v183
	v_cvt_pk_bf16_f32 v175, v184, v185
	v_cvt_pk_bf16_f32 v176, v186, v187
	v_cvt_pk_bf16_f32 v177, v188, v189
	global_store_dwordx4 v[170:171], v[174:177], off offset:1024
	global_load_dwordx4 v[174:177], v[108:109], off
	s_nop 0
	global_load_dwordx4 v[178:181], v[108:109], off offset:16
	global_load_dwordx4 v[182:185], v[110:111], off
	global_load_dwordx4 v[186:189], v[110:111], off offset:16
	s_waitcnt vmcnt(3)
	v_pk_fma_f32 v[176:177], v[176:177], v[210:211], v[160:161]
	v_pk_fma_f32 v[174:175], v[174:175], v[208:209], v[152:153]
	s_waitcnt vmcnt(2)
	v_pk_fma_f32 v[180:181], v[180:181], v[214:215], v[158:159]
	v_pk_fma_f32 v[178:179], v[178:179], v[212:213], v[150:151]
	v_cvt_pk_bf16_f32 v174, v174, v175
	v_cvt_pk_bf16_f32 v175, v176, v177
	s_waitcnt vmcnt(1)
	v_pk_fma_f32 v[184:185], v[184:185], v[218:219], v[156:157]
	v_cvt_pk_bf16_f32 v176, v178, v179
	v_cvt_pk_bf16_f32 v177, v180, v181
	v_pk_fma_f32 v[182:183], v[182:183], v[216:217], v[148:149]
	s_waitcnt vmcnt(0)
	v_pk_fma_f32 v[188:189], v[188:189], v[222:223], v[154:155]
	v_pk_fma_f32 v[186:187], v[186:187], v[220:221], v[146:147]
	global_store_dwordx4 v[168:169], v[174:177], off
	s_nop 1
	v_cvt_pk_bf16_f32 v174, v182, v183
	v_cvt_pk_bf16_f32 v175, v184, v185
	v_cvt_pk_bf16_f32 v176, v186, v187
	v_cvt_pk_bf16_f32 v177, v188, v189
	global_store_dwordx4 v[168:169], v[174:177], off offset:1024
	global_load_dwordx4 v[174:177], v[112:113], off
	s_nop 0
	global_load_dwordx4 v[178:181], v[112:113], off offset:16
	global_load_dwordx4 v[182:185], v[114:115], off
	global_load_dwordx4 v[186:189], v[114:115], off offset:16
	s_waitcnt vmcnt(3)
	v_pk_fma_f32 v[160:161], v[176:177], v[210:211], v[160:161]
	v_pk_fma_f32 v[152:153], v[174:175], v[208:209], v[152:153]
	s_waitcnt vmcnt(2)
	v_pk_fma_f32 v[158:159], v[180:181], v[214:215], v[158:159]
	v_pk_fma_f32 v[150:151], v[178:179], v[212:213], v[150:151]
	s_waitcnt vmcnt(1)
	v_pk_fma_f32 v[174:175], v[182:183], v[216:217], v[148:149]
	s_waitcnt vmcnt(0)
	v_pk_fma_f32 v[176:177], v[186:187], v[220:221], v[146:147]
	v_cvt_pk_bf16_f32 v146, v152, v153
	v_cvt_pk_bf16_f32 v147, v160, v161
	v_cvt_pk_bf16_f32 v148, v150, v151
	v_cvt_pk_bf16_f32 v149, v158, v159
	v_pk_fma_f32 v[156:157], v[184:185], v[218:219], v[156:157]
	v_pk_fma_f32 v[154:155], v[188:189], v[222:223], v[154:155]
	global_store_dwordx4 v[164:165], v[146:149], off
	s_nop 1
	v_cvt_pk_bf16_f32 v146, v174, v175
	v_cvt_pk_bf16_f32 v147, v156, v157
	v_cvt_pk_bf16_f32 v148, v176, v177
	v_cvt_pk_bf16_f32 v149, v154, v155
	global_store_dwordx4 v[164:165], v[146:149], off offset:1024
	s_nop 1
	v_cvt_pk_bf16_f32 v146, v74, v75
	v_cvt_pk_bf16_f32 v147, v124, v125
	v_cvt_pk_bf16_f32 v148, v68, v69
	v_cvt_pk_bf16_f32 v149, v122, v123
	global_store_dwordx4 v[162:163], v[146:149], off offset:2048
	s_nop 1
	v_cvt_pk_bf16_f32 v146, v72, v73
	v_cvt_pk_bf16_f32 v147, v120, v121
	v_cvt_pk_bf16_f32 v148, v70, v71
	v_cvt_pk_bf16_f32 v149, v118, v119
	global_store_dwordx4 v[162:163], v[146:149], off offset:3072
	global_load_dwordx4 v[146:149], v[102:103], off
	s_nop 0
	global_load_dwordx4 v[150:153], v[102:103], off offset:16
	global_load_dwordx4 v[154:157], v[102:103], off offset:2048
	global_load_dwordx4 v[158:161], v[102:103], off offset:2064
	s_waitcnt vmcnt(3)
	v_pk_fma_f32 v[148:149], v[148:149], v[134:135], v[124:125]
	v_pk_fma_f32 v[146:147], v[146:147], v[126:127], v[74:75]
	s_waitcnt vmcnt(2)
	v_pk_fma_f32 v[152:153], v[152:153], v[136:137], v[122:123]
	v_pk_fma_f32 v[150:151], v[150:151], v[128:129], v[68:69]
	v_cvt_pk_bf16_f32 v146, v146, v147
	v_cvt_pk_bf16_f32 v147, v148, v149
	s_waitcnt vmcnt(1)
	v_pk_fma_f32 v[156:157], v[156:157], v[138:139], v[120:121]
	v_cvt_pk_bf16_f32 v148, v150, v151
	v_cvt_pk_bf16_f32 v149, v152, v153
	v_pk_fma_f32 v[154:155], v[154:155], v[130:131], v[72:73]
	s_waitcnt vmcnt(0)
	v_pk_fma_f32 v[160:161], v[160:161], v[140:141], v[118:119]
	v_pk_fma_f32 v[158:159], v[158:159], v[132:133], v[70:71]
	global_store_dwordx4 v[144:145], v[146:149], off offset:2048
	s_nop 1
	v_cvt_pk_bf16_f32 v146, v154, v155
	v_cvt_pk_bf16_f32 v147, v156, v157
	v_cvt_pk_bf16_f32 v148, v158, v159
	v_cvt_pk_bf16_f32 v149, v160, v161
	global_store_dwordx4 v[144:145], v[146:149], off offset:3072
	global_load_dwordx4 v[144:147], v[104:105], off
	s_nop 0
	global_load_dwordx4 v[148:151], v[104:105], off offset:16
	global_load_dwordx4 v[152:155], v[106:107], off
	global_load_dwordx4 v[156:159], v[106:107], off offset:16
	s_waitcnt vmcnt(3)
	v_pk_fma_f32 v[146:147], v[146:147], v[134:135], v[124:125]
	v_pk_fma_f32 v[144:145], v[144:145], v[126:127], v[74:75]
	s_waitcnt vmcnt(2)
	v_pk_fma_f32 v[150:151], v[150:151], v[136:137], v[122:123]
	v_pk_fma_f32 v[148:149], v[148:149], v[128:129], v[68:69]
	v_cvt_pk_bf16_f32 v144, v144, v145
	v_cvt_pk_bf16_f32 v145, v146, v147
	s_waitcnt vmcnt(1)
	v_pk_fma_f32 v[154:155], v[154:155], v[138:139], v[120:121]
	v_cvt_pk_bf16_f32 v146, v148, v149
	v_cvt_pk_bf16_f32 v147, v150, v151
	v_pk_fma_f32 v[152:153], v[152:153], v[130:131], v[72:73]
	s_waitcnt vmcnt(0)
	v_pk_fma_f32 v[158:159], v[158:159], v[140:141], v[118:119]
	v_pk_fma_f32 v[156:157], v[156:157], v[132:133], v[70:71]
	global_store_dwordx4 v[170:171], v[144:147], off offset:2048
	s_nop 1
	v_cvt_pk_bf16_f32 v144, v152, v153
	v_cvt_pk_bf16_f32 v145, v154, v155
	v_cvt_pk_bf16_f32 v146, v156, v157
	v_cvt_pk_bf16_f32 v147, v158, v159
	global_store_dwordx4 v[170:171], v[144:147], off offset:3072
	global_load_dwordx4 v[144:147], v[108:109], off
	s_nop 0
	global_load_dwordx4 v[148:151], v[108:109], off offset:16
	global_load_dwordx4 v[152:155], v[110:111], off
	global_load_dwordx4 v[156:159], v[110:111], off offset:16
	s_waitcnt vmcnt(3)
	v_pk_fma_f32 v[146:147], v[146:147], v[134:135], v[124:125]
	v_pk_fma_f32 v[144:145], v[144:145], v[126:127], v[74:75]
	s_waitcnt vmcnt(2)
	v_pk_fma_f32 v[150:151], v[150:151], v[136:137], v[122:123]
	v_pk_fma_f32 v[148:149], v[148:149], v[128:129], v[68:69]
	v_cvt_pk_bf16_f32 v144, v144, v145
	v_cvt_pk_bf16_f32 v145, v146, v147
	s_waitcnt vmcnt(1)
	v_pk_fma_f32 v[154:155], v[154:155], v[138:139], v[120:121]
	v_cvt_pk_bf16_f32 v146, v148, v149
	v_cvt_pk_bf16_f32 v147, v150, v151
	v_pk_fma_f32 v[152:153], v[152:153], v[130:131], v[72:73]
	s_waitcnt vmcnt(0)
	v_pk_fma_f32 v[158:159], v[158:159], v[140:141], v[118:119]
	v_pk_fma_f32 v[156:157], v[156:157], v[132:133], v[70:71]
	global_store_dwordx4 v[168:169], v[144:147], off offset:2048
	s_nop 1
	v_cvt_pk_bf16_f32 v144, v152, v153
	v_cvt_pk_bf16_f32 v145, v154, v155
	v_cvt_pk_bf16_f32 v146, v156, v157
	v_cvt_pk_bf16_f32 v147, v158, v159
	global_store_dwordx4 v[168:169], v[144:147], off offset:3072
	global_load_dwordx4 v[144:147], v[112:113], off
	s_nop 0
	global_load_dwordx4 v[148:151], v[112:113], off offset:16
	global_load_dwordx4 v[152:155], v[114:115], off
	global_load_dwordx4 v[156:159], v[114:115], off offset:16
	s_waitcnt vmcnt(3)
	v_pk_fma_f32 v[124:125], v[146:147], v[134:135], v[124:125]
	v_pk_fma_f32 v[74:75], v[144:145], v[126:127], v[74:75]
	s_waitcnt vmcnt(2)
	v_pk_fma_f32 v[122:123], v[150:151], v[136:137], v[122:123]
	v_pk_fma_f32 v[126:127], v[148:149], v[128:129], v[68:69]
	s_waitcnt vmcnt(0)
	v_pk_fma_f32 v[128:129], v[156:157], v[132:133], v[70:71]
	v_cvt_pk_bf16_f32 v68, v74, v75
	v_cvt_pk_bf16_f32 v69, v124, v125
	v_cvt_pk_bf16_f32 v70, v126, v127
	v_cvt_pk_bf16_f32 v71, v122, v123
	v_pk_fma_f32 v[120:121], v[154:155], v[138:139], v[120:121]
	v_pk_fma_f32 v[72:73], v[152:153], v[130:131], v[72:73]
	v_pk_fma_f32 v[118:119], v[158:159], v[140:141], v[118:119]
	global_store_dwordx4 v[164:165], v[68:71], off offset:2048
	s_nop 1
	v_cvt_pk_bf16_f32 v68, v72, v73
	v_cvt_pk_bf16_f32 v69, v120, v121
	v_cvt_pk_bf16_f32 v70, v128, v129
	v_cvt_pk_bf16_f32 v71, v118, v119
	global_store_dwordx4 v[164:165], v[68:71], off offset:3072
	s_nop 1
	v_cvt_pk_bf16_f32 v68, v48, v49
	v_cvt_pk_bf16_f32 v69, v46, v47
	v_cvt_pk_bf16_f32 v70, v44, v45
	v_cvt_pk_bf16_f32 v71, v42, v43
	global_store_dwordx4 v[166:167], v[68:71], off
	s_nop 1
	v_cvt_pk_bf16_f32 v68, v40, v41
	v_cvt_pk_bf16_f32 v69, v38, v39
	v_cvt_pk_bf16_f32 v70, v36, v37
	v_cvt_pk_bf16_f32 v71, v34, v35
	global_store_dwordx4 v[166:167], v[68:71], off offset:1024
	global_load_dwordx4 v[68:71], v[102:103], off
	s_nop 0
	global_load_dwordx4 v[72:75], v[102:103], off offset:16
	global_load_dwordx4 v[118:121], v[102:103], off offset:2048
	global_load_dwordx4 v[122:125], v[102:103], off offset:2064
	s_waitcnt vmcnt(3)
	v_pk_fma_f32 v[70:71], v[70:71], v[90:91], v[46:47]
	v_pk_fma_f32 v[68:69], v[68:69], v[78:79], v[48:49]
	s_waitcnt vmcnt(2)
	v_pk_fma_f32 v[74:75], v[74:75], v[92:93], v[42:43]
	v_pk_fma_f32 v[72:73], v[72:73], v[80:81], v[44:45]
	v_cvt_pk_bf16_f32 v68, v68, v69
	v_cvt_pk_bf16_f32 v69, v70, v71
	s_waitcnt vmcnt(1)
	v_pk_fma_f32 v[120:121], v[120:121], v[94:95], v[38:39]
	v_cvt_pk_bf16_f32 v70, v72, v73
	v_cvt_pk_bf16_f32 v71, v74, v75
	v_pk_fma_f32 v[118:119], v[118:119], v[82:83], v[40:41]
	s_waitcnt vmcnt(0)
	v_pk_fma_f32 v[124:125], v[124:125], v[96:97], v[34:35]
	v_pk_fma_f32 v[122:123], v[122:123], v[84:85], v[36:37]
	global_store_dwordx4 v[142:143], v[68:71], off
	s_nop 1
	v_cvt_pk_bf16_f32 v68, v118, v119
	v_cvt_pk_bf16_f32 v69, v120, v121
	v_cvt_pk_bf16_f32 v70, v122, v123
	v_cvt_pk_bf16_f32 v71, v124, v125
	global_store_dwordx4 v[142:143], v[68:71], off offset:1024
	global_load_dwordx4 v[68:71], v[104:105], off
	s_nop 0
	global_load_dwordx4 v[72:75], v[104:105], off offset:16
	global_load_dwordx4 v[118:121], v[106:107], off
	global_load_dwordx4 v[122:125], v[106:107], off offset:16
	s_waitcnt vmcnt(3)
	v_pk_fma_f32 v[70:71], v[70:71], v[90:91], v[46:47]
	v_pk_fma_f32 v[68:69], v[68:69], v[78:79], v[48:49]
	s_waitcnt vmcnt(2)
	v_pk_fma_f32 v[74:75], v[74:75], v[92:93], v[42:43]
	v_pk_fma_f32 v[72:73], v[72:73], v[80:81], v[44:45]
	v_cvt_pk_bf16_f32 v68, v68, v69
	v_cvt_pk_bf16_f32 v69, v70, v71
	s_waitcnt vmcnt(1)
	v_pk_fma_f32 v[120:121], v[120:121], v[94:95], v[38:39]
	v_cvt_pk_bf16_f32 v70, v72, v73
	v_cvt_pk_bf16_f32 v71, v74, v75
	v_pk_fma_f32 v[118:119], v[118:119], v[82:83], v[40:41]
	s_waitcnt vmcnt(0)
	v_pk_fma_f32 v[124:125], v[124:125], v[96:97], v[34:35]
	v_pk_fma_f32 v[122:123], v[122:123], v[84:85], v[36:37]
	global_store_dwordx4 v[88:89], v[68:71], off
	s_nop 1
	v_cvt_pk_bf16_f32 v68, v118, v119
	v_cvt_pk_bf16_f32 v69, v120, v121
	v_cvt_pk_bf16_f32 v70, v122, v123
	v_cvt_pk_bf16_f32 v71, v124, v125
	global_store_dwordx4 v[88:89], v[68:71], off offset:1024
	global_load_dwordx4 v[68:71], v[108:109], off
	s_nop 0
	global_load_dwordx4 v[72:75], v[108:109], off offset:16
	global_load_dwordx4 v[118:121], v[110:111], off
	global_load_dwordx4 v[122:125], v[110:111], off offset:16
	s_waitcnt vmcnt(3)
	v_pk_fma_f32 v[70:71], v[70:71], v[90:91], v[46:47]
	v_pk_fma_f32 v[68:69], v[68:69], v[78:79], v[48:49]
	s_waitcnt vmcnt(2)
	v_pk_fma_f32 v[74:75], v[74:75], v[92:93], v[42:43]
	v_pk_fma_f32 v[72:73], v[72:73], v[80:81], v[44:45]
	v_cvt_pk_bf16_f32 v68, v68, v69
	v_cvt_pk_bf16_f32 v69, v70, v71
	s_waitcnt vmcnt(1)
	v_pk_fma_f32 v[88:89], v[120:121], v[94:95], v[38:39]
	v_cvt_pk_bf16_f32 v70, v72, v73
	v_cvt_pk_bf16_f32 v71, v74, v75
	v_pk_fma_f32 v[118:119], v[118:119], v[82:83], v[40:41]
	s_waitcnt vmcnt(0)
	v_pk_fma_f32 v[120:121], v[124:125], v[96:97], v[34:35]
	v_pk_fma_f32 v[122:123], v[122:123], v[84:85], v[36:37]
	global_store_dwordx4 v[86:87], v[68:71], off
	s_nop 1
	v_cvt_pk_bf16_f32 v68, v118, v119
	v_cvt_pk_bf16_f32 v69, v88, v89
	v_cvt_pk_bf16_f32 v70, v122, v123
	v_cvt_pk_bf16_f32 v71, v120, v121
	global_store_dwordx4 v[86:87], v[68:71], off offset:1024
	global_load_dwordx4 v[68:71], v[112:113], off
	s_nop 0
	global_load_dwordx4 v[72:75], v[112:113], off offset:16
	global_load_dwordx4 v[86:89], v[114:115], off
	global_load_dwordx4 v[118:121], v[114:115], off offset:16
	s_waitcnt vmcnt(3)
	v_pk_fma_f32 v[70:71], v[70:71], v[90:91], v[46:47]
	v_pk_fma_f32 v[68:69], v[68:69], v[78:79], v[48:49]
	s_waitcnt vmcnt(2)
	v_pk_fma_f32 v[74:75], v[74:75], v[92:93], v[42:43]
	v_pk_fma_f32 v[72:73], v[72:73], v[80:81], v[44:45]
	v_cvt_pk_bf16_f32 v68, v68, v69
	v_cvt_pk_bf16_f32 v69, v70, v71
	s_waitcnt vmcnt(1)
	v_pk_fma_f32 v[78:79], v[88:89], v[94:95], v[38:39]
	v_cvt_pk_bf16_f32 v70, v72, v73
	v_cvt_pk_bf16_f32 v71, v74, v75
	v_pk_fma_f32 v[80:81], v[86:87], v[82:83], v[40:41]
	s_waitcnt vmcnt(0)
	v_pk_fma_f32 v[82:83], v[120:121], v[96:97], v[34:35]
	v_pk_fma_f32 v[84:85], v[118:119], v[84:85], v[36:37]
	global_store_dwordx4 v[76:77], v[68:71], off
	v_pk_fma_f32 v[48:49], v[66:67], v[6:7], v[48:49] neg_lo:[1,0,0] neg_hi:[1,0,0]
	v_pk_fma_f32 v[46:47], v[64:65], v[8:9], v[46:47] neg_lo:[1,0,0] neg_hi:[1,0,0]
	v_cvt_pk_bf16_f32 v68, v80, v81
	v_cvt_pk_bf16_f32 v69, v78, v79
	v_cvt_pk_bf16_f32 v70, v84, v85
	v_cvt_pk_bf16_f32 v71, v82, v83
	global_store_dwordx4 v[76:77], v[68:71], off offset:1024
	v_pk_fma_f32 v[44:45], v[62:63], v[2:3], v[44:45] neg_lo:[1,0,0] neg_hi:[1,0,0]
	v_pk_fma_f32 v[42:43], v[60:61], v[4:5], v[42:43] neg_lo:[1,0,0] neg_hi:[1,0,0]
	v_cvt_pk_bf16_f32 v68, v30, v31
	v_cvt_pk_bf16_f32 v69, v32, v33
	v_cvt_pk_bf16_f32 v70, v26, v27
	v_cvt_pk_bf16_f32 v71, v28, v29
	global_store_dwordx4 v[56:57], v[68:71], off
	v_pk_fma_f32 v[38:39], v[54:55], v[16:17], v[38:39] neg_lo:[1,0,0] neg_hi:[1,0,0]
	v_pk_fma_f32 v[54:55], v[52:53], v[10:11], v[36:37] neg_lo:[1,0,0] neg_hi:[1,0,0]
	v_cvt_pk_bf16_f32 v68, v22, v23
	v_cvt_pk_bf16_f32 v69, v24, v25
	v_cvt_pk_bf16_f32 v70, v18, v19
	v_cvt_pk_bf16_f32 v71, v20, v21
	global_store_dwordx4 v[56:57], v[68:71], off offset:1024
	global_load_dwordx4 v[68:71], v[102:103], off
	s_nop 0
	global_load_dwordx4 v[72:75], v[102:103], off offset:16
	global_load_dwordx4 v[76:79], v[102:103], off offset:2048
	global_load_dwordx4 v[80:83], v[102:103], off offset:2064
	v_pk_fma_f32 v[66:67], v[50:51], v[12:13], v[34:35] neg_lo:[1,0,0] neg_hi:[1,0,0]
	v_lshl_add_u64 v[56:57], v[100:101], 0, s[8:9]
	v_pk_fma_f32 v[40:41], v[58:59], v[14:15], v[40:41] neg_lo:[1,0,0] neg_hi:[1,0,0]
	s_waitcnt vmcnt(3)
	v_pk_fma_f32 v[36:37], v[70:71], v[46:47], v[32:33]
	v_pk_fma_f32 v[34:35], v[68:69], v[48:49], v[30:31]
	s_waitcnt vmcnt(2)
	v_pk_fma_f32 v[50:51], v[74:75], v[42:43], v[28:29]
	v_pk_fma_f32 v[52:53], v[72:73], v[44:45], v[26:27]
	v_cvt_pk_bf16_f32 v34, v34, v35
	v_cvt_pk_bf16_f32 v35, v36, v37
	s_waitcnt vmcnt(1)
	v_pk_fma_f32 v[58:59], v[78:79], v[38:39], v[24:25]
	v_cvt_pk_bf16_f32 v36, v52, v53
	v_cvt_pk_bf16_f32 v37, v50, v51
	v_pk_fma_f32 v[60:61], v[76:77], v[40:41], v[22:23]
	s_waitcnt vmcnt(0)
	v_pk_fma_f32 v[62:63], v[82:83], v[66:67], v[20:21]
	v_pk_fma_f32 v[64:65], v[80:81], v[54:55], v[18:19]
	global_store_dwordx4 v[56:57], v[34:37], off
	v_add_co_u32_e32 v68, vcc, s14, v56
	s_nop 0
	v_cvt_pk_bf16_f32 v34, v60, v61
	v_cvt_pk_bf16_f32 v35, v58, v59
	v_cvt_pk_bf16_f32 v36, v64, v65
	v_cvt_pk_bf16_f32 v37, v62, v63
	global_store_dwordx4 v[56:57], v[34:37], off offset:1024
	global_load_dwordx4 v[34:37], v[104:105], off
	s_nop 0
	global_load_dwordx4 v[50:53], v[104:105], off offset:16
	global_load_dwordx4 v[58:61], v[106:107], off
	global_load_dwordx4 v[62:65], v[106:107], off offset:16
	v_addc_co_u32_e32 v69, vcc, 0, v57, vcc
	s_waitcnt vmcnt(3)
	v_pk_fma_f32 v[36:37], v[36:37], v[46:47], v[32:33]
	v_pk_fma_f32 v[34:35], v[34:35], v[48:49], v[30:31]
	s_waitcnt vmcnt(2)
	v_pk_fma_f32 v[52:53], v[52:53], v[42:43], v[28:29]
	v_pk_fma_f32 v[50:51], v[50:51], v[44:45], v[26:27]
	v_cvt_pk_bf16_f32 v34, v34, v35
	v_cvt_pk_bf16_f32 v35, v36, v37
	s_waitcnt vmcnt(1)
	v_pk_fma_f32 v[60:61], v[60:61], v[38:39], v[24:25]
	v_cvt_pk_bf16_f32 v36, v50, v51
	v_cvt_pk_bf16_f32 v37, v52, v53
	v_pk_fma_f32 v[58:59], v[58:59], v[40:41], v[22:23]
	s_waitcnt vmcnt(0)
	v_pk_fma_f32 v[64:65], v[64:65], v[66:67], v[20:21]
	v_pk_fma_f32 v[62:63], v[62:63], v[54:55], v[18:19]
	global_store_dwordx4 v[68:69], v[34:37], off
	s_nop 1
	v_cvt_pk_bf16_f32 v34, v58, v59
	v_cvt_pk_bf16_f32 v35, v60, v61
	v_cvt_pk_bf16_f32 v36, v62, v63
	v_cvt_pk_bf16_f32 v37, v64, v65
	global_store_dwordx4 v[68:69], v[34:37], off offset:1024
	global_load_dwordx4 v[34:37], v[108:109], off
	s_nop 0
	global_load_dwordx4 v[50:53], v[108:109], off offset:16
	global_load_dwordx4 v[58:61], v[110:111], off
	global_load_dwordx4 v[62:65], v[110:111], off offset:16
	v_add_co_u32_e32 v68, vcc, s15, v56
	s_waitcnt vmcnt(3)
	v_pk_fma_f32 v[36:37], v[36:37], v[46:47], v[32:33]
	v_pk_fma_f32 v[34:35], v[34:35], v[48:49], v[30:31]
	v_addc_co_u32_e32 v69, vcc, 0, v57, vcc
	s_waitcnt vmcnt(2)
	v_pk_fma_f32 v[52:53], v[52:53], v[42:43], v[28:29]
	v_pk_fma_f32 v[50:51], v[50:51], v[44:45], v[26:27]
	v_cvt_pk_bf16_f32 v34, v34, v35
	v_cvt_pk_bf16_f32 v35, v36, v37
	s_waitcnt vmcnt(1)
	v_pk_fma_f32 v[60:61], v[60:61], v[38:39], v[24:25]
	v_cvt_pk_bf16_f32 v36, v50, v51
	v_cvt_pk_bf16_f32 v37, v52, v53
	v_pk_fma_f32 v[58:59], v[58:59], v[40:41], v[22:23]
	s_waitcnt vmcnt(0)
	v_pk_fma_f32 v[64:65], v[64:65], v[66:67], v[20:21]
	v_pk_fma_f32 v[62:63], v[62:63], v[54:55], v[18:19]
	global_store_dwordx4 v[68:69], v[34:37], off
	v_add_co_u32_e32 v56, vcc, s16, v56
	s_nop 0
	v_cvt_pk_bf16_f32 v34, v58, v59
	v_cvt_pk_bf16_f32 v35, v60, v61
	v_cvt_pk_bf16_f32 v36, v62, v63
	v_cvt_pk_bf16_f32 v37, v64, v65
	global_store_dwordx4 v[68:69], v[34:37], off offset:1024
	global_load_dwordx4 v[34:37], v[112:113], off
	s_nop 0
	global_load_dwordx4 v[50:53], v[112:113], off offset:16
	global_load_dwordx4 v[58:61], v[114:115], off
	global_load_dwordx4 v[62:65], v[114:115], off offset:16
	v_addc_co_u32_e32 v57, vcc, 0, v57, vcc
	s_waitcnt vmcnt(3)
	v_pk_fma_f32 v[32:33], v[36:37], v[46:47], v[32:33]
	v_pk_fma_f32 v[30:31], v[34:35], v[48:49], v[30:31]
	s_waitcnt vmcnt(2)
	v_pk_fma_f32 v[28:29], v[52:53], v[42:43], v[28:29]
	v_pk_fma_f32 v[26:27], v[50:51], v[44:45], v[26:27]
	s_waitcnt vmcnt(0)
	v_pk_fma_f32 v[34:35], v[64:65], v[66:67], v[20:21]
	v_pk_fma_f32 v[36:37], v[62:63], v[54:55], v[18:19]
	v_cvt_pk_bf16_f32 v18, v30, v31
	v_cvt_pk_bf16_f32 v19, v32, v33
	v_cvt_pk_bf16_f32 v20, v26, v27
	v_cvt_pk_bf16_f32 v21, v28, v29
	v_pk_fma_f32 v[24:25], v[60:61], v[38:39], v[24:25]
	v_pk_fma_f32 v[22:23], v[58:59], v[40:41], v[22:23]
	global_store_dwordx4 v[56:57], v[18:21], off
	s_nop 1
	v_cvt_pk_bf16_f32 v18, v22, v23
	v_cvt_pk_bf16_f32 v19, v24, v25
	v_cvt_pk_bf16_f32 v20, v36, v37
	v_cvt_pk_bf16_f32 v21, v34, v35
	global_store_dwordx4 v[56:57], v[18:21], off offset:1024
	s_cbranch_scc0 .LBB0_57

.LBB0_455:
	global_load_dwordx4 v[84:87], v[82:83], off nt
	global_load_dwordx4 v[76:79], v[82:83], off offset:1024 nt
	v_lshl_add_u64 v[18:19], v[82:83], 0, s[0:1]
	global_load_dwordx4 v[72:75], v[18:19], off nt
	global_load_dwordx4 v[68:71], v[18:19], off offset:1024 nt
	v_lshl_add_u64 v[18:19], v[18:19], 0, s[0:1]
	global_load_dwordx4 v[64:67], v[18:19], off nt
	global_load_dwordx4 v[60:63], v[18:19], off offset:1024 nt
	v_lshl_add_u64 v[18:19], v[18:19], 0, s[0:1]
	global_load_dwordx4 v[56:59], v[18:19], off nt
	global_load_dwordx4 v[52:55], v[18:19], off offset:1024 nt
	v_lshl_add_u64 v[18:19], v[18:19], 0, s[0:1]
	global_load_dwordx4 v[48:51], v[18:19], off nt
	global_load_dwordx4 v[44:47], v[18:19], off offset:1024 nt
	v_lshl_add_u64 v[18:19], v[18:19], 0, s[0:1]
	global_load_dwordx4 v[40:43], v[18:19], off nt
	global_load_dwordx4 v[36:39], v[18:19], off offset:1024 nt
	v_lshl_add_u64 v[18:19], v[18:19], 0, s[0:1]
	global_load_dwordx4 v[32:35], v[18:19], off nt
	global_load_dwordx4 v[28:31], v[18:19], off offset:1024 nt
	v_lshl_add_u64 v[18:19], v[18:19], 0, s[0:1]
	global_load_dwordx4 v[24:27], v[18:19], off nt
	global_load_dwordx4 v[20:23], v[18:19], off offset:1024 nt
	s_waitcnt vmcnt(15)
	v_lshlrev_b32_e32 v18, 16, v84
	v_and_b32_e32 v19, 0xffff0000, v84
	v_lshlrev_b32_e32 v84, 16, v85
	v_and_b32_e32 v85, 0xffff0000, v85
	v_lshlrev_b32_e32 v88, 16, v86
	v_and_b32_e32 v89, 0xffff0000, v86
	v_lshlrev_b32_e32 v86, 16, v87
	v_and_b32_e32 v87, 0xffff0000, v87
	v_pk_mul_f32 v[84:85], v[6:7], v[84:85]
	v_pk_mul_f32 v[18:19], v[4:5], v[18:19]
	v_pk_mul_f32 v[86:87], v[2:3], v[86:87]
	v_pk_mul_f32 v[88:89], v[0:1], v[88:89]
	v_mul_f32_e32 v16, v19, v19
	v_mul_f32_e32 v19, v85, v85
	v_mul_f32_e32 v85, v89, v89
	v_mul_f32_e32 v87, v87, v87
	v_fmac_f32_e32 v16, v18, v18
	v_fmac_f32_e32 v19, v84, v84
	v_fmac_f32_e32 v85, v88, v88
	v_fmac_f32_e32 v87, v86, v86
	v_add_f32_e32 v16, v16, v19
	v_add_f32_e32 v18, v85, v87
	v_add_f32_e32 v16, v16, v18
	v_lshl_add_u64 v[84:85], s[10:11], 0, v[80:81]
	s_nop 0
	v_add_f32_dpp v16, v16, v16 quad_perm:[1,0,3,2] row_mask:0xf bank_mask:0xf bound_ctrl:1
	s_nop 1
	v_add_f32_dpp v16, v16, v16 quad_perm:[2,3,0,1] row_mask:0xf bank_mask:0xf bound_ctrl:1
	s_nop 1
	v_mov_b32_dpp v18, v16 row_half_mirror row_mask:0xf bank_mask:0xf bound_ctrl:1
	s_and_saveexec_b64 s[4:5], s[6:7]
	s_cbranch_execz .LBB0_457
	v_add_f32_e32 v16, v16, v18
	v_max_f32_e32 v16, 0x179abe15, v16
	v_rsq_f32_e32 v16, v16
	v_add_co_u32_e32 v86, vcc, 0x2200000, v84
	v_mov_b32_e32 v18, v17
	s_nop 0
	v_addc_co_u32_e32 v87, vcc, 0, v85, vcc
	v_mov_b32_e32 v19, v17
	global_store_dwordx4 v[86:87], v[16:19], off

.LBB0_904:
	v_lshl_add_u64 v[100:101], s[6:7], 0, v[92:93]
	v_add_co_u32_e32 v0, vcc, 0x27d00000, v100
	s_addk_i32 s0, 0xfc00
	s_nop 0
	v_addc_co_u32_e32 v1, vcc, 0, v101, vcc
	global_load_dwordx4 v[118:121], v[0:1], off nt
	global_load_dwordx4 v[80:83], v[0:1], off offset:1024 nt
	v_lshl_add_u64 v[0:1], s[8:9], 0, v[92:93]
	v_add_co_u32_e32 v2, vcc, 0x8000000, v0
	s_add_u32 s6, s6, 0xffe00000
	s_nop 0
	v_addc_co_u32_e32 v3, vcc, 0, v1, vcc
	global_load_dwordx4 v[88:91], v[2:3], off nt
	global_load_dwordx4 v[76:79], v[2:3], off offset:1024 nt
	v_add_co_u32_e32 v2, vcc, 0x7900000, v100
	s_addc_u32 s7, s7, -1
	s_nop 0
	v_addc_co_u32_e32 v3, vcc, 0, v101, vcc
	global_load_dwordx4 v[84:87], v[2:3], off nt
	global_load_dwordx4 v[72:75], v[2:3], off offset:1024 nt
	global_load_dword v116, v[98:99], off
	global_load_dword v114, v[98:99], off offset:32
	v_add_co_u32_e32 v2, vcc, 0x27d80000, v100
	s_add_u32 s8, s8, 0xffe00000
	s_nop 0
	v_addc_co_u32_e32 v3, vcc, 0, v101, vcc
	global_load_dwordx4 v[68:71], v[2:3], off nt
	global_load_dwordx4 v[56:59], v[2:3], off offset:1024 nt
	v_add_co_u32_e32 v2, vcc, 0x8080000, v0
	s_addc_u32 s9, s9, -1
	s_nop 0
	v_addc_co_u32_e32 v3, vcc, 0, v1, vcc
	global_load_dwordx4 v[64:67], v[2:3], off nt
	global_load_dwordx4 v[52:55], v[2:3], off offset:1024 nt
	v_add_co_u32_e32 v2, vcc, 0x7980000, v100
	s_cmp_lt_i32 s0, s73
	s_nop 0
	v_addc_co_u32_e32 v3, vcc, 0, v101, vcc
	global_load_dwordx4 v[60:63], v[2:3], off nt
	global_load_dwordx4 v[48:51], v[2:3], off offset:1024 nt
	v_add_co_u32_e32 v2, vcc, 0x4000, v98
	s_waitcnt vmcnt(13)
	v_and_b32_e32 v127, 0xffff0000, v120
	v_addc_co_u32_e32 v3, vcc, 0, v99, vcc
	global_load_dword v112, v[2:3], off
	global_load_dword v110, v[2:3], off offset:32
	v_add_co_u32_e32 v2, vcc, 0x27e00000, v100
	v_and_b32_e32 v126, 0xffff0000, v118
	s_nop 0
	v_addc_co_u32_e32 v3, vcc, 0, v101, vcc
	global_load_dwordx4 v[44:47], v[2:3], off nt
	global_load_dwordx4 v[32:35], v[2:3], off offset:1024 nt
	v_add_co_u32_e32 v2, vcc, 0x8100000, v0
	v_lshlrev_b32_e32 v129, 16, v121
	s_nop 0
	v_addc_co_u32_e32 v3, vcc, 0, v1, vcc
	global_load_dwordx4 v[40:43], v[2:3], off nt
	global_load_dwordx4 v[28:31], v[2:3], off offset:1024 nt
	v_add_co_u32_e32 v2, vcc, 0x7a00000, v100
	v_lshlrev_b32_e32 v128, 16, v119
	s_nop 0
	v_addc_co_u32_e32 v3, vcc, 0, v101, vcc
	global_load_dwordx4 v[36:39], v[2:3], off nt
	global_load_dwordx4 v[24:27], v[2:3], off offset:1024 nt
	v_add_co_u32_e32 v2, vcc, 0x8000, v98
	v_and_b32_e32 v131, 0xffff0000, v121
	s_nop 0
	v_addc_co_u32_e32 v3, vcc, 0, v99, vcc
	global_load_dword v108, v[2:3], off
	global_load_dword v106, v[2:3], off offset:32
	v_add_co_u32_e32 v2, vcc, 0x27e80000, v100
	v_and_b32_e32 v130, 0xffff0000, v119
	s_nop 0
	v_addc_co_u32_e32 v3, vcc, 0, v101, vcc
	v_add_co_u32_e32 v0, vcc, 0x8180000, v0
	global_load_dwordx4 v[20:23], v[2:3], off nt
	global_load_dwordx4 v[8:11], v[2:3], off offset:1024 nt
	v_addc_co_u32_e32 v1, vcc, 0, v1, vcc
	global_load_dwordx4 v[16:19], v[0:1], off nt
	global_load_dwordx4 v[4:7], v[0:1], off offset:1024 nt
	v_add_co_u32_e32 v0, vcc, 0x7a80000, v100
	s_waitcnt vmcnt(25)
	v_lshlrev_b32_e32 v144, 16, v88
	v_addc_co_u32_e32 v1, vcc, 0, v101, vcc
	v_add_co_u32_e32 v122, vcc, 0xc000, v98
	global_load_dwordx4 v[12:15], v[0:1], off nt
	s_nop 0
	global_load_dwordx4 v[0:3], v[0:1], off offset:1024 nt
	v_addc_co_u32_e32 v123, vcc, 0, v99, vcc
	global_load_dword v104, v[122:123], off
	global_load_dword v102, v[122:123], off offset:32
	v_lshlrev_b32_e32 v123, 16, v120
	v_lshlrev_b32_e32 v122, 16, v118
	v_pk_add_f32 v[118:119], v[122:123], v[126:127]
	v_pk_add_f32 v[120:121], v[128:129], v[130:131]
	v_and_b32_e32 v145, 0xffff0000, v88
	v_pk_add_f32 v[118:119], v[118:119], v[120:121]
	v_lshlrev_b32_e32 v88, 16, v89
	v_add_f32_e32 v105, v118, v119
	v_and_b32_e32 v89, 0xffff0000, v89
	s_waitcnt vmcnt(27)
	v_and_b32_e32 v107, 0xffff0000, v84
	v_add_f32_dpp v105, v105, v105 quad_perm:[1,0,3,2] row_mask:0xf bank_mask:0xf bound_ctrl:1
	v_lshlrev_b32_e32 v109, 16, v85
	v_and_b32_e32 v111, 0xffff0000, v85
	v_add_f32_dpp v105, v105, v105 quad_perm:[2,3,0,1] row_mask:0xf bank_mask:0xf bound_ctrl:1
	v_mul_f32_e32 v85, 0xbfb8aa3b, v111
	v_exp_f32_e32 v85, v85
	v_add_f32_dpp v105, v105, v105 row_half_mirror row_mask:0xf bank_mask:0xf bound_ctrl:1
	v_fmac_f32_e32 v126, 0xbc800000, v105
	v_fmac_f32_e32 v127, 0xbc800000, v105
	v_fmac_f32_e32 v130, 0xbc800000, v105
	v_fmac_f32_e32 v122, 0xbc800000, v105
	v_fmac_f32_e32 v131, 0xbc800000, v105
	v_fmac_f32_e32 v123, 0xbc800000, v105
	v_pk_mul_f32 v[120:121], v[126:127], v[126:127]
	v_fmac_f32_e32 v128, 0xbc800000, v105
	v_fmac_f32_e32 v129, 0xbc800000, v105
	v_mov_b32_e32 v118, v123
	v_mov_b32_e32 v119, v127
	v_mov_b32_e32 v124, v122
	v_pk_fma_f32 v[122:123], v[122:123], v[122:123], v[120:121]
	v_mov_b32_e32 v121, v131
	v_mov_b32_e32 v127, v130
	v_pk_mul_f32 v[130:131], v[130:131], v[130:131]
	v_mov_b32_e32 v125, v126
	v_mov_b32_e32 v120, v129
	v_mov_b32_e32 v126, v128
	v_pk_fma_f32 v[128:129], v[128:129], v[128:129], v[130:131]
	v_lshl_add_u64 v[98:99], v[98:99], 0, s[10:11]
	v_pk_add_f32 v[122:123], v[122:123], v[128:129]
	global_load_dwordx4 v[128:131], v[94:95], off offset:16
	global_load_dwordx4 v[132:135], v[94:95], off
	global_load_dwordx4 v[136:139], v[96:97], off offset:16
	global_load_dwordx4 v[140:143], v[96:97], off
	v_add_f32_e32 v105, v122, v123
	s_nop 1
	v_add_f32_dpp v105, v105, v105 quad_perm:[1,0,3,2] row_mask:0xf bank_mask:0xf bound_ctrl:1
	s_nop 1
	v_add_f32_dpp v105, v105, v105 quad_perm:[2,3,0,1] row_mask:0xf bank_mask:0xf bound_ctrl:1
	s_nop 1
	v_add_f32_dpp v105, v105, v105 row_half_mirror row_mask:0xf bank_mask:0xf bound_ctrl:1
	v_fmamk_f32 v105, v105, 0x3c800000, v103
	v_rsq_f32_e32 v122, v105
	v_lshlrev_b32_e32 v105, 16, v84
	v_mul_f32_e32 v84, 0xbfb8aa3b, v105
	v_pk_mul_f32 v[126:127], v[122:123], v[126:127] op_sel_hi:[0,1]
	v_pk_mul_f32 v[124:125], v[122:123], v[124:125] op_sel_hi:[0,1]
	s_waitcnt vmcnt(0)
	v_pk_fma_f32 v[126:127], v[126:127], v[134:135], v[142:143]
	s_nop 0
	v_pk_fma_f32 v[88:89], v[116:117], v[88:89], v[126:127] op_sel_hi:[0,1,1]
	v_exp_f32_e32 v126, v84
	v_mul_f32_e32 v84, 0xbfb8aa3b, v107
	v_exp_f32_e32 v127, v84
	v_mul_f32_e32 v84, 0xbfb8aa3b, v109
	v_exp_f32_e32 v84, v84
	v_pk_fma_f32 v[124:125], v[124:125], v[132:133], v[140:141]
	v_pk_add_f32 v[126:127], v[126:127], 1.0 op_sel_hi:[1,0]
	v_pk_fma_f32 v[124:125], v[116:117], v[144:145], v[124:125] op_sel_hi:[0,1,1]
	v_pk_add_f32 v[84:85], v[84:85], 1.0 op_sel_hi:[1,0]
	s_nop 0
	v_rcp_f32_e32 v113, v85
	s_nop 0
	v_mul_f32_e32 v85, v111, v113
	v_rcp_f32_e32 v111, v84
	s_nop 0
	v_mul_f32_e32 v84, v109, v111
	v_pk_mul_f32 v[118:119], v[122:123], v[118:119] op_sel_hi:[0,1]
	v_pk_mul_f32 v[120:121], v[122:123], v[120:121] op_sel_hi:[0,1]
	v_pk_mul_f32 v[84:85], v[88:89], v[84:85]
	v_rcp_f32_e32 v109, v127
	s_nop 0
	v_mul_f32_e32 v127, v107, v109
	v_pk_fma_f32 v[120:121], v[120:121], v[130:131], v[138:139]
	v_pk_fma_f32 v[118:119], v[118:119], v[128:129], v[136:137]
	v_lshlrev_b32_e32 v123, 16, v83
	v_rcp_f32_e32 v107, v126
	s_nop 0
	v_mul_f32_e32 v126, v105, v107
	v_lshlrev_b32_e32 v105, 16, v86
	v_pk_mul_f32 v[88:89], v[124:125], v[126:127]
	v_lshlrev_b32_e32 v124, 16, v90
	v_and_b32_e32 v125, 0xffff0000, v90
	v_lshlrev_b32_e32 v90, 16, v91
	v_and_b32_e32 v91, 0xffff0000, v91
	v_and_b32_e32 v107, 0xffff0000, v86
	v_mul_f32_e32 v86, 0xbfb8aa3b, v105
	v_pk_fma_f32 v[118:119], v[116:117], v[124:125], v[118:119] op_sel_hi:[0,1,1]
	v_pk_fma_f32 v[90:91], v[116:117], v[90:91], v[120:121] op_sel_hi:[0,1,1]
	v_exp_f32_e32 v116, v86
	v_mul_f32_e32 v86, 0xbfb8aa3b, v107
	v_lshlrev_b32_e32 v109, 16, v87
	v_and_b32_e32 v111, 0xffff0000, v87
	v_exp_f32_e32 v117, v86
	v_mul_f32_e32 v86, 0xbfb8aa3b, v109
	v_mul_f32_e32 v87, 0xbfb8aa3b, v111
	v_exp_f32_e32 v86, v86
	v_exp_f32_e32 v87, v87
	v_pk_add_f32 v[116:117], v[116:117], 1.0 op_sel_hi:[1,0]
	v_and_b32_e32 v125, 0xffff0000, v83
	v_and_b32_e32 v124, 0xffff0000, v81
	v_pk_add_f32 v[86:87], v[86:87], 1.0 op_sel_hi:[1,0]
	v_lshlrev_b32_e32 v138, 16, v76
	v_and_b32_e32 v139, 0xffff0000, v76
	v_lshlrev_b32_e32 v76, 16, v77
	v_and_b32_e32 v77, 0xffff0000, v77
	v_rcp_f32_e32 v113, v87
	s_nop 0
	v_mul_f32_e32 v87, v111, v113
	v_lshlrev_b32_e32 v122, 16, v81
	v_rcp_f32_e32 v111, v86
	s_nop 0
	v_mul_f32_e32 v86, v109, v111
	v_pk_mul_f32 v[86:87], v[90:91], v[86:87]
	v_and_b32_e32 v121, 0xffff0000, v82
	v_rcp_f32_e32 v109, v117
	s_nop 0
	v_mul_f32_e32 v117, v107, v109
	v_and_b32_e32 v120, 0xffff0000, v80
	v_rcp_f32_e32 v107, v116
	s_nop 0
	v_mul_f32_e32 v116, v105, v107
	v_pk_mul_f32 v[90:91], v[118:119], v[116:117]
	v_lshlrev_b32_e32 v117, 16, v82
	v_lshlrev_b32_e32 v116, 16, v80
	v_pk_add_f32 v[80:81], v[116:117], v[120:121]
	v_pk_add_f32 v[82:83], v[122:123], v[124:125]
	v_and_b32_e32 v107, 0xffff0000, v72
	v_pk_add_f32 v[80:81], v[80:81], v[82:83]
	v_lshlrev_b32_e32 v109, 16, v73
	v_add_f32_e32 v80, v80, v81
	v_and_b32_e32 v111, 0xffff0000, v73
	v_mul_f32_e32 v73, 0xbfb8aa3b, v111
	v_add_f32_dpp v80, v80, v80 quad_perm:[1,0,3,2] row_mask:0xf bank_mask:0xf bound_ctrl:1
	v_exp_f32_e32 v73, v73
	s_nop 0
	v_add_f32_dpp v80, v80, v80 quad_perm:[2,3,0,1] row_mask:0xf bank_mask:0xf bound_ctrl:1
	s_nop 1
	v_add_f32_dpp v80, v80, v80 row_half_mirror row_mask:0xf bank_mask:0xf bound_ctrl:1
	v_fmac_f32_e32 v120, 0xbc800000, v80
	v_fmac_f32_e32 v121, 0xbc800000, v80
	v_fmac_f32_e32 v124, 0xbc800000, v80
	v_fmac_f32_e32 v116, 0xbc800000, v80
	v_fmac_f32_e32 v125, 0xbc800000, v80
	v_fmac_f32_e32 v117, 0xbc800000, v80
	v_pk_mul_f32 v[82:83], v[120:121], v[120:121]
	v_fmac_f32_e32 v122, 0xbc800000, v80
	v_fmac_f32_e32 v123, 0xbc800000, v80
	v_mov_b32_e32 v80, v117
	v_mov_b32_e32 v81, v121
	v_mov_b32_e32 v118, v116
	v_pk_fma_f32 v[116:117], v[116:117], v[116:117], v[82:83]
	v_mov_b32_e32 v83, v125
	v_mov_b32_e32 v121, v124
	v_pk_mul_f32 v[124:125], v[124:125], v[124:125]
	v_mov_b32_e32 v119, v120
	v_mov_b32_e32 v82, v123
	v_mov_b32_e32 v120, v122
	v_pk_fma_f32 v[122:123], v[122:123], v[122:123], v[124:125]
	s_nop 0
	v_pk_add_f32 v[116:117], v[116:117], v[122:123]
	global_load_dwordx4 v[122:125], v[94:95], off offset:2064
	global_load_dwordx4 v[126:129], v[94:95], off offset:2048
	global_load_dwordx4 v[130:133], v[96:97], off offset:2064
	global_load_dwordx4 v[134:137], v[96:97], off offset:2048
	v_add_f32_e32 v105, v116, v117
	s_nop 1
	v_add_f32_dpp v105, v105, v105 quad_perm:[1,0,3,2] row_mask:0xf bank_mask:0xf bound_ctrl:1
	s_nop 1
	v_add_f32_dpp v105, v105, v105 quad_perm:[2,3,0,1] row_mask:0xf bank_mask:0xf bound_ctrl:1
	s_nop 1
	v_add_f32_dpp v105, v105, v105 row_half_mirror row_mask:0xf bank_mask:0xf bound_ctrl:1
	v_fmamk_f32 v105, v105, 0x3c800000, v103
	v_rsq_f32_e32 v116, v105
	v_lshlrev_b32_e32 v105, 16, v72
	v_mul_f32_e32 v72, 0xbfb8aa3b, v105
	v_pk_mul_f32 v[120:121], v[116:117], v[120:121] op_sel_hi:[0,1]
	v_pk_mul_f32 v[118:119], v[116:117], v[118:119] op_sel_hi:[0,1]
	s_waitcnt vmcnt(0)
	v_pk_fma_f32 v[120:121], v[120:121], v[128:129], v[136:137]
	s_nop 0
	v_pk_fma_f32 v[76:77], v[114:115], v[76:77], v[120:121] op_sel_hi:[0,1,1]
	v_exp_f32_e32 v120, v72
	v_mul_f32_e32 v72, 0xbfb8aa3b, v107
	v_exp_f32_e32 v121, v72
	v_mul_f32_e32 v72, 0xbfb8aa3b, v109
	v_exp_f32_e32 v72, v72
	v_pk_fma_f32 v[118:119], v[118:119], v[126:127], v[134:135]
	v_pk_add_f32 v[120:121], v[120:121], 1.0 op_sel_hi:[1,0]
	v_pk_fma_f32 v[118:119], v[114:115], v[138:139], v[118:119] op_sel_hi:[0,1,1]
	v_pk_add_f32 v[72:73], v[72:73], 1.0 op_sel_hi:[1,0]
	s_nop 0
	v_rcp_f32_e32 v113, v73
	s_nop 0
	v_mul_f32_e32 v73, v111, v113
	v_rcp_f32_e32 v111, v72
	s_nop 0
	v_mul_f32_e32 v72, v109, v111
	v_pk_mul_f32 v[76:77], v[76:77], v[72:73]
	v_lshlrev_b32_e32 v72, 16, v78
	v_and_b32_e32 v73, 0xffff0000, v78
	v_rcp_f32_e32 v109, v121
	s_nop 0
	v_mul_f32_e32 v121, v107, v109
	v_pk_mul_f32 v[82:83], v[116:117], v[82:83] op_sel_hi:[0,1]
	v_lshlrev_b32_e32 v78, 16, v79
	v_and_b32_e32 v79, 0xffff0000, v79
	v_pk_fma_f32 v[82:83], v[82:83], v[124:125], v[132:133]
	v_pk_mul_f32 v[80:81], v[116:117], v[80:81] op_sel_hi:[0,1]
	v_pk_fma_f32 v[78:79], v[114:115], v[78:79], v[82:83] op_sel_hi:[0,1,1]
	v_lshlrev_b32_e32 v82, 16, v74
	v_pk_fma_f32 v[80:81], v[80:81], v[122:123], v[130:131]
	v_and_b32_e32 v83, 0xffff0000, v74
	v_mul_f32_e32 v74, 0xbfb8aa3b, v82
	v_rcp_f32_e32 v107, v120
	s_nop 0
	v_mul_f32_e32 v120, v105, v107
	v_pk_fma_f32 v[72:73], v[114:115], v[72:73], v[80:81] op_sel_hi:[0,1,1]
	v_exp_f32_e32 v80, v74
	v_mul_f32_e32 v74, 0xbfb8aa3b, v83
	v_lshlrev_b32_e32 v105, 16, v75
	v_and_b32_e32 v107, 0xffff0000, v75
	v_exp_f32_e32 v81, v74
	v_mul_f32_e32 v74, 0xbfb8aa3b, v105
	v_mul_f32_e32 v75, 0xbfb8aa3b, v107
	v_exp_f32_e32 v74, v74
	v_exp_f32_e32 v75, v75
	v_pk_add_f32 v[80:81], v[80:81], 1.0 op_sel_hi:[1,0]
	v_pk_mul_f32 v[118:119], v[118:119], v[120:121]
	v_lshlrev_b32_e32 v116, 16, v64
	v_pk_add_f32 v[74:75], v[74:75], 1.0 op_sel_hi:[1,0]
	v_and_b32_e32 v117, 0xffff0000, v64
	v_lshlrev_b32_e32 v64, 16, v65
	v_and_b32_e32 v65, 0xffff0000, v65
	v_rcp_f32_e32 v109, v75
	s_nop 0
	v_mul_f32_e32 v75, v107, v109
	v_rcp_f32_e32 v107, v74
	s_nop 0
	v_mul_f32_e32 v74, v105, v107
	v_pk_mul_f32 v[78:79], v[78:79], v[74:75]
	v_rcp_f32_e32 v105, v81
	s_nop 0
	v_mul_f32_e32 v81, v83, v105
	v_rcp_f32_e32 v83, v80
	s_nop 0
	v_mul_f32_e32 v80, v82, v83
	v_add_co_u32_e32 v82, vcc, s1, v100
	v_pk_mul_f32 v[80:81], v[72:73], v[80:81]
	v_cvt_pk_bf16_f32 v72, v88, v89
	v_cvt_pk_bf16_f32 v73, v84, v85
	v_cvt_pk_bf16_f32 v74, v90, v91
	v_cvt_pk_bf16_f32 v75, v86, v87
	s_nop 0
	v_addc_co_u32_e32 v83, vcc, 0, v101, vcc
	global_store_dwordx4 v[82:83], v[72:75], off
	s_nop 1
	v_cvt_pk_bf16_f32 v72, v118, v119
	v_cvt_pk_bf16_f32 v73, v76, v77
	v_cvt_pk_bf16_f32 v74, v80, v81
	v_cvt_pk_bf16_f32 v75, v78, v79
	global_store_dwordx4 v[82:83], v[72:75], off offset:1024
	v_lshlrev_b32_e32 v77, 16, v71
	v_lshlrev_b32_e32 v76, 16, v69
	v_lshlrev_b32_e32 v73, 16, v70
	v_lshlrev_b32_e32 v72, 16, v68
	v_and_b32_e32 v75, 0xffff0000, v70
	v_and_b32_e32 v74, 0xffff0000, v68
	v_and_b32_e32 v71, 0xffff0000, v71
	v_and_b32_e32 v70, 0xffff0000, v69
	v_pk_add_f32 v[68:69], v[72:73], v[74:75]
	v_pk_add_f32 v[78:79], v[76:77], v[70:71]
	s_nop 0
	v_pk_add_f32 v[68:69], v[68:69], v[78:79]
	s_nop 0
	v_add_f32_e32 v68, v68, v69
	s_nop 1
	v_add_f32_dpp v68, v68, v68 quad_perm:[1,0,3,2] row_mask:0xf bank_mask:0xf bound_ctrl:1
	s_nop 1
	v_add_f32_dpp v68, v68, v68 quad_perm:[2,3,0,1] row_mask:0xf bank_mask:0xf bound_ctrl:1
	s_nop 1
	v_add_f32_dpp v68, v68, v68 row_half_mirror row_mask:0xf bank_mask:0xf bound_ctrl:1
	v_fmac_f32_e32 v70, 0xbc800000, v68
	v_fmac_f32_e32 v74, 0xbc800000, v68
	v_fmac_f32_e32 v71, 0xbc800000, v68
	v_fmac_f32_e32 v75, 0xbc800000, v68
	v_fmac_f32_e32 v76, 0xbc800000, v68
	v_fmac_f32_e32 v72, 0xbc800000, v68
	v_fmac_f32_e32 v77, 0xbc800000, v68
	v_fmac_f32_e32 v73, 0xbc800000, v68
	v_pk_mul_f32 v[68:69], v[74:75], v[74:75]
	v_mov_b32_e32 v89, v71
	v_mov_b32_e32 v91, v70
	v_pk_mul_f32 v[70:71], v[70:71], v[70:71]
	v_pk_fma_f32 v[68:69], v[72:73], v[72:73], v[68:69]
	v_pk_fma_f32 v[70:71], v[76:77], v[76:77], v[70:71]
	v_mov_b32_e32 v84, v73
	v_pk_add_f32 v[68:69], v[68:69], v[70:71]
	v_mov_b32_e32 v85, v75
	v_add_f32_e32 v68, v68, v69
	v_mov_b32_e32 v86, v72
	v_mov_b32_e32 v87, v74
	v_add_f32_dpp v68, v68, v68 quad_perm:[1,0,3,2] row_mask:0xf bank_mask:0xf bound_ctrl:1
	v_mov_b32_e32 v88, v77
	v_mov_b32_e32 v90, v76
	v_add_f32_dpp v68, v68, v68 quad_perm:[2,3,0,1] row_mask:0xf bank_mask:0xf bound_ctrl:1
	s_nop 1
	v_add_f32_dpp v68, v68, v68 row_half_mirror row_mask:0xf bank_mask:0xf bound_ctrl:1
	v_fmamk_f32 v68, v68, 0x3c800000, v103
	v_rsq_f32_e32 v114, v68
	global_load_dwordx4 v[68:71], v[94:95], off offset:16
	global_load_dwordx4 v[72:75], v[94:95], off
	global_load_dwordx4 v[76:79], v[96:97], off offset:16
	global_load_dwordx4 v[80:83], v[96:97], off
	v_pk_mul_f32 v[86:87], v[114:115], v[86:87] op_sel_hi:[0,1]
	v_pk_mul_f32 v[90:91], v[114:115], v[90:91] op_sel_hi:[0,1]
	s_waitcnt vmcnt(0)
	v_pk_fma_f32 v[72:73], v[86:87], v[72:73], v[80:81]
	v_lshlrev_b32_e32 v80, 16, v60
	v_pk_fma_f32 v[74:75], v[90:91], v[74:75], v[82:83]
	v_and_b32_e32 v81, 0xffff0000, v60
	v_mul_f32_e32 v60, 0xbfb8aa3b, v80
	v_pk_fma_f32 v[64:65], v[112:113], v[64:65], v[74:75] op_sel_hi:[0,1,1]
	v_exp_f32_e32 v74, v60
	v_mul_f32_e32 v60, 0xbfb8aa3b, v81
	v_lshlrev_b32_e32 v82, 16, v61
	v_and_b32_e32 v83, 0xffff0000, v61
	v_exp_f32_e32 v75, v60
	v_mul_f32_e32 v60, 0xbfb8aa3b, v82
	v_mul_f32_e32 v61, 0xbfb8aa3b, v83
	v_exp_f32_e32 v60, v60
	v_exp_f32_e32 v61, v61
	v_pk_add_f32 v[74:75], v[74:75], 1.0 op_sel_hi:[1,0]
	v_pk_fma_f32 v[72:73], v[112:113], v[116:117], v[72:73] op_sel_hi:[0,1,1]
	v_pk_add_f32 v[60:61], v[60:61], 1.0 op_sel_hi:[1,0]
	s_nop 0
	v_rcp_f32_e32 v86, v61
	s_nop 0
	v_mul_f32_e32 v61, v83, v86
	v_rcp_f32_e32 v83, v60
	s_nop 0
	v_mul_f32_e32 v60, v82, v83
	v_pk_mul_f32 v[60:61], v[64:65], v[60:61]
	v_and_b32_e32 v91, 0xffff0000, v52
	v_rcp_f32_e32 v82, v75
	s_nop 0
	v_mul_f32_e32 v75, v81, v82
	v_lshlrev_b32_e32 v90, 16, v52
	v_lshlrev_b32_e32 v52, 16, v53
	v_and_b32_e32 v53, 0xffff0000, v53
	v_rcp_f32_e32 v81, v74
	s_nop 0
	v_mul_f32_e32 v74, v80, v81
	v_pk_mul_f32 v[64:65], v[72:73], v[74:75]
	v_pk_mul_f32 v[74:75], v[114:115], v[84:85] op_sel_hi:[0,1]
	v_lshlrev_b32_e32 v72, 16, v66
	v_and_b32_e32 v73, 0xffff0000, v66
	v_pk_fma_f32 v[68:69], v[74:75], v[68:69], v[76:77]
	v_pk_mul_f32 v[80:81], v[114:115], v[88:89] op_sel_hi:[0,1]
	v_pk_fma_f32 v[68:69], v[112:113], v[72:73], v[68:69] op_sel_hi:[0,1,1]
	v_lshlrev_b32_e32 v72, 16, v62
	v_lshlrev_b32_e32 v66, 16, v67
	v_and_b32_e32 v67, 0xffff0000, v67
	v_pk_fma_f32 v[70:71], v[80:81], v[70:71], v[78:79]
	v_and_b32_e32 v73, 0xffff0000, v62
	v_mul_f32_e32 v62, 0xbfb8aa3b, v72
	v_pk_fma_f32 v[66:67], v[112:113], v[66:67], v[70:71] op_sel_hi:[0,1,1]
	v_exp_f32_e32 v70, v62
	v_mul_f32_e32 v62, 0xbfb8aa3b, v73
	v_lshlrev_b32_e32 v74, 16, v63
	v_and_b32_e32 v75, 0xffff0000, v63
	v_exp_f32_e32 v71, v62
	v_mul_f32_e32 v62, 0xbfb8aa3b, v74
	v_mul_f32_e32 v63, 0xbfb8aa3b, v75
	v_exp_f32_e32 v62, v62
	v_exp_f32_e32 v63, v63
	v_pk_add_f32 v[70:71], v[70:71], 1.0 op_sel_hi:[1,0]
	v_pk_add_f32 v[62:63], v[62:63], 1.0 op_sel_hi:[1,0]
	s_nop 0
	v_rcp_f32_e32 v76, v63
	s_nop 0
	v_mul_f32_e32 v63, v75, v76
	v_rcp_f32_e32 v75, v62
	s_nop 0
	v_mul_f32_e32 v62, v74, v75
	v_pk_mul_f32 v[62:63], v[66:67], v[62:63]
	v_lshlrev_b32_e32 v67, 16, v58
	v_lshlrev_b32_e32 v66, 16, v56
	v_rcp_f32_e32 v74, v71
	s_nop 0
	v_mul_f32_e32 v71, v73, v74
	v_rcp_f32_e32 v73, v70
	s_nop 0
	v_mul_f32_e32 v70, v72, v73
	v_pk_mul_f32 v[78:79], v[68:69], v[70:71]
	v_and_b32_e32 v69, 0xffff0000, v58
	v_and_b32_e32 v68, 0xffff0000, v56
	v_lshlrev_b32_e32 v71, 16, v59
	v_lshlrev_b32_e32 v70, 16, v57
	v_and_b32_e32 v59, 0xffff0000, v59
	v_and_b32_e32 v58, 0xffff0000, v57
	v_pk_add_f32 v[56:57], v[66:67], v[68:69]
	v_pk_add_f32 v[72:73], v[70:71], v[58:59]
	s_nop 0
	v_pk_add_f32 v[56:57], v[56:57], v[72:73]
	s_nop 0
	v_add_f32_e32 v56, v56, v57
	s_nop 1
	v_add_f32_dpp v56, v56, v56 quad_perm:[1,0,3,2] row_mask:0xf bank_mask:0xf bound_ctrl:1
	s_nop 1
	v_add_f32_dpp v56, v56, v56 quad_perm:[2,3,0,1] row_mask:0xf bank_mask:0xf bound_ctrl:1
	s_nop 1
	v_add_f32_dpp v56, v56, v56 row_half_mirror row_mask:0xf bank_mask:0xf bound_ctrl:1
	v_fmac_f32_e32 v58, 0xbc800000, v56
	v_fmac_f32_e32 v68, 0xbc800000, v56
	v_fmac_f32_e32 v59, 0xbc800000, v56
	v_fmac_f32_e32 v69, 0xbc800000, v56
	v_fmac_f32_e32 v70, 0xbc800000, v56
	v_fmac_f32_e32 v66, 0xbc800000, v56
	v_fmac_f32_e32 v71, 0xbc800000, v56
	v_fmac_f32_e32 v67, 0xbc800000, v56
	v_pk_mul_f32 v[56:57], v[68:69], v[68:69]
	v_mov_b32_e32 v85, v59
	v_mov_b32_e32 v87, v58
	v_pk_mul_f32 v[58:59], v[58:59], v[58:59]
	v_pk_fma_f32 v[56:57], v[66:67], v[66:67], v[56:57]
	v_pk_fma_f32 v[58:59], v[70:71], v[70:71], v[58:59]
	v_mov_b32_e32 v80, v67
	v_pk_add_f32 v[56:57], v[56:57], v[58:59]
	v_mov_b32_e32 v81, v69
	v_add_f32_e32 v56, v56, v57
	v_mov_b32_e32 v82, v66
	v_mov_b32_e32 v83, v68
	v_add_f32_dpp v56, v56, v56 quad_perm:[1,0,3,2] row_mask:0xf bank_mask:0xf bound_ctrl:1
	v_mov_b32_e32 v84, v71
	v_mov_b32_e32 v86, v70
	v_add_f32_dpp v56, v56, v56 quad_perm:[2,3,0,1] row_mask:0xf bank_mask:0xf bound_ctrl:1
	s_nop 1
	v_add_f32_dpp v56, v56, v56 row_half_mirror row_mask:0xf bank_mask:0xf bound_ctrl:1
	v_fmamk_f32 v56, v56, 0x3c800000, v103
	v_rsq_f32_e32 v88, v56
	global_load_dwordx4 v[66:69], v[94:95], off offset:2064
	global_load_dwordx4 v[56:59], v[94:95], off offset:2048
	global_load_dwordx4 v[70:73], v[96:97], off offset:2064
	global_load_dwordx4 v[74:77], v[96:97], off offset:2048
	v_pk_mul_f32 v[82:83], v[88:89], v[82:83] op_sel_hi:[0,1]
	v_pk_mul_f32 v[86:87], v[88:89], v[86:87] op_sel_hi:[0,1]
	s_waitcnt vmcnt(0)
	v_pk_fma_f32 v[56:57], v[82:83], v[56:57], v[74:75]
	v_lshlrev_b32_e32 v74, 16, v48
	v_pk_fma_f32 v[58:59], v[86:87], v[58:59], v[76:77]
	v_and_b32_e32 v75, 0xffff0000, v48
	v_mul_f32_e32 v48, 0xbfb8aa3b, v74
	v_pk_fma_f32 v[52:53], v[110:111], v[52:53], v[58:59] op_sel_hi:[0,1,1]
	v_exp_f32_e32 v58, v48
	v_mul_f32_e32 v48, 0xbfb8aa3b, v75
	v_lshlrev_b32_e32 v76, 16, v49
	v_and_b32_e32 v77, 0xffff0000, v49
	v_exp_f32_e32 v59, v48
	v_mul_f32_e32 v48, 0xbfb8aa3b, v76
	v_mul_f32_e32 v49, 0xbfb8aa3b, v77
	v_exp_f32_e32 v48, v48
	v_exp_f32_e32 v49, v49
	v_pk_add_f32 v[58:59], v[58:59], 1.0 op_sel_hi:[1,0]
	v_pk_fma_f32 v[56:57], v[110:111], v[90:91], v[56:57] op_sel_hi:[0,1,1]
	v_pk_add_f32 v[48:49], v[48:49], 1.0 op_sel_hi:[1,0]
	s_nop 0
	v_rcp_f32_e32 v82, v49
	s_nop 0
	v_mul_f32_e32 v49, v77, v82
	v_rcp_f32_e32 v77, v48
	s_nop 0
	v_mul_f32_e32 v48, v76, v77
	v_pk_mul_f32 v[52:53], v[52:53], v[48:49]
	v_lshlrev_b32_e32 v48, 16, v54
	v_and_b32_e32 v49, 0xffff0000, v54
	v_rcp_f32_e32 v76, v59
	s_nop 0
	v_mul_f32_e32 v59, v75, v76
	v_lshlrev_b32_e32 v54, 16, v55
	v_and_b32_e32 v55, 0xffff0000, v55
	v_rcp_f32_e32 v75, v58
	s_nop 0
	v_mul_f32_e32 v58, v74, v75
	v_pk_mul_f32 v[56:57], v[56:57], v[58:59]
	v_pk_mul_f32 v[58:59], v[88:89], v[80:81] op_sel_hi:[0,1]
	v_pk_mul_f32 v[74:75], v[88:89], v[84:85] op_sel_hi:[0,1]
	v_pk_fma_f32 v[58:59], v[58:59], v[66:67], v[70:71]
	v_lshlrev_b32_e32 v66, 16, v50
	v_pk_fma_f32 v[68:69], v[74:75], v[68:69], v[72:73]
	v_and_b32_e32 v67, 0xffff0000, v50
	v_mul_f32_e32 v50, 0xbfb8aa3b, v66
	v_pk_fma_f32 v[48:49], v[110:111], v[48:49], v[58:59] op_sel_hi:[0,1,1]
	v_pk_fma_f32 v[54:55], v[110:111], v[54:55], v[68:69] op_sel_hi:[0,1,1]
	v_exp_f32_e32 v58, v50
	v_mul_f32_e32 v50, 0xbfb8aa3b, v67
	v_lshlrev_b32_e32 v68, 16, v51
	v_and_b32_e32 v69, 0xffff0000, v51
	v_exp_f32_e32 v59, v50
	v_mul_f32_e32 v50, 0xbfb8aa3b, v68
	v_mul_f32_e32 v51, 0xbfb8aa3b, v69
	v_exp_f32_e32 v50, v50
	v_exp_f32_e32 v51, v51
	v_pk_add_f32 v[58:59], v[58:59], 1.0 op_sel_hi:[1,0]
	v_pk_add_f32 v[50:51], v[50:51], 1.0 op_sel_hi:[1,0]
	s_nop 0
	v_rcp_f32_e32 v70, v51
	s_nop 0
	v_mul_f32_e32 v51, v69, v70
	v_rcp_f32_e32 v69, v50
	s_nop 0
	v_mul_f32_e32 v50, v68, v69
	v_pk_mul_f32 v[54:55], v[54:55], v[50:51]
	v_rcp_f32_e32 v68, v59
	s_nop 0
	v_mul_f32_e32 v59, v67, v68
	v_rcp_f32_e32 v67, v58
	s_nop 0
	v_mul_f32_e32 v58, v66, v67
	v_pk_mul_f32 v[58:59], v[48:49], v[58:59]
	v_cvt_pk_bf16_f32 v48, v64, v65
	v_cvt_pk_bf16_f32 v49, v60, v61
	v_add_co_u32_e32 v60, vcc, s4, v100
	v_cvt_pk_bf16_f32 v50, v78, v79
	v_cvt_pk_bf16_f32 v51, v62, v63
	v_lshlrev_b32_e32 v70, 16, v40
	s_nop 0
	v_addc_co_u32_e32 v61, vcc, 0, v101, vcc
	global_store_dwordx4 v[60:61], v[48:51], off
	v_and_b32_e32 v71, 0xffff0000, v40
	v_lshlrev_b32_e32 v40, 16, v41
	v_cvt_pk_bf16_f32 v48, v56, v57
	v_cvt_pk_bf16_f32 v49, v52, v53
	v_cvt_pk_bf16_f32 v50, v58, v59
	v_cvt_pk_bf16_f32 v51, v54, v55
	global_store_dwordx4 v[60:61], v[48:51], off offset:1024
	v_lshlrev_b32_e32 v53, 16, v47
	v_lshlrev_b32_e32 v52, 16, v45
	v_lshlrev_b32_e32 v49, 16, v46
	v_lshlrev_b32_e32 v48, 16, v44
	v_and_b32_e32 v51, 0xffff0000, v46
	v_and_b32_e32 v50, 0xffff0000, v44
	v_and_b32_e32 v47, 0xffff0000, v47
	v_and_b32_e32 v46, 0xffff0000, v45
	v_pk_add_f32 v[44:45], v[48:49], v[50:51]
	v_pk_add_f32 v[54:55], v[52:53], v[46:47]
	v_and_b32_e32 v41, 0xffff0000, v41
	v_pk_add_f32 v[44:45], v[44:45], v[54:55]
	s_nop 0
	v_add_f32_e32 v44, v44, v45
	s_nop 1
	v_add_f32_dpp v44, v44, v44 quad_perm:[1,0,3,2] row_mask:0xf bank_mask:0xf bound_ctrl:1
	s_nop 1
	v_add_f32_dpp v44, v44, v44 quad_perm:[2,3,0,1] row_mask:0xf bank_mask:0xf bound_ctrl:1
	s_nop 1
	v_add_f32_dpp v44, v44, v44 row_half_mirror row_mask:0xf bank_mask:0xf bound_ctrl:1
	v_fmac_f32_e32 v46, 0xbc800000, v44
	v_fmac_f32_e32 v50, 0xbc800000, v44
	v_fmac_f32_e32 v47, 0xbc800000, v44
	v_fmac_f32_e32 v51, 0xbc800000, v44
	v_fmac_f32_e32 v52, 0xbc800000, v44
	v_fmac_f32_e32 v48, 0xbc800000, v44
	v_fmac_f32_e32 v53, 0xbc800000, v44
	v_fmac_f32_e32 v49, 0xbc800000, v44
	v_pk_mul_f32 v[44:45], v[50:51], v[50:51]
	v_mov_b32_e32 v65, v47
	v_mov_b32_e32 v67, v46
	v_pk_mul_f32 v[46:47], v[46:47], v[46:47]
	v_pk_fma_f32 v[44:45], v[48:49], v[48:49], v[44:45]
	v_pk_fma_f32 v[46:47], v[52:53], v[52:53], v[46:47]
	v_mov_b32_e32 v60, v49
	v_pk_add_f32 v[44:45], v[44:45], v[46:47]
	v_mov_b32_e32 v61, v51
	v_add_f32_e32 v44, v44, v45
	v_mov_b32_e32 v62, v48
	v_mov_b32_e32 v63, v50
	v_add_f32_dpp v44, v44, v44 quad_perm:[1,0,3,2] row_mask:0xf bank_mask:0xf bound_ctrl:1
	v_mov_b32_e32 v64, v53
	v_mov_b32_e32 v66, v52
	v_add_f32_dpp v44, v44, v44 quad_perm:[2,3,0,1] row_mask:0xf bank_mask:0xf bound_ctrl:1
	s_nop 1
	v_add_f32_dpp v44, v44, v44 row_half_mirror row_mask:0xf bank_mask:0xf bound_ctrl:1
	v_fmamk_f32 v44, v44, 0x3c800000, v103
	v_rsq_f32_e32 v68, v44
	global_load_dwordx4 v[44:47], v[94:95], off offset:16
	global_load_dwordx4 v[48:51], v[94:95], off
	global_load_dwordx4 v[52:55], v[96:97], off offset:16
	global_load_dwordx4 v[56:59], v[96:97], off
	v_pk_mul_f32 v[62:63], v[68:69], v[62:63] op_sel_hi:[0,1]
	v_pk_mul_f32 v[66:67], v[68:69], v[66:67] op_sel_hi:[0,1]
	s_waitcnt vmcnt(0)
	v_pk_fma_f32 v[48:49], v[62:63], v[48:49], v[56:57]
	v_lshlrev_b32_e32 v56, 16, v36
	v_pk_fma_f32 v[50:51], v[66:67], v[50:51], v[58:59]
	v_and_b32_e32 v57, 0xffff0000, v36
	v_mul_f32_e32 v36, 0xbfb8aa3b, v56
	v_pk_fma_f32 v[40:41], v[108:109], v[40:41], v[50:51] op_sel_hi:[0,1,1]
	v_exp_f32_e32 v50, v36
	v_mul_f32_e32 v36, 0xbfb8aa3b, v57
	v_lshlrev_b32_e32 v58, 16, v37
	v_and_b32_e32 v59, 0xffff0000, v37
	v_exp_f32_e32 v51, v36
	v_mul_f32_e32 v36, 0xbfb8aa3b, v58
	v_mul_f32_e32 v37, 0xbfb8aa3b, v59
	v_exp_f32_e32 v36, v36
	v_exp_f32_e32 v37, v37
	v_pk_add_f32 v[50:51], v[50:51], 1.0 op_sel_hi:[1,0]
	v_pk_fma_f32 v[48:49], v[108:109], v[70:71], v[48:49] op_sel_hi:[0,1,1]
	v_pk_add_f32 v[36:37], v[36:37], 1.0 op_sel_hi:[1,0]
	s_nop 0
	v_rcp_f32_e32 v62, v37
	s_nop 0
	v_mul_f32_e32 v37, v59, v62
	v_rcp_f32_e32 v59, v36
	s_nop 0
	v_mul_f32_e32 v36, v58, v59
	v_pk_mul_f32 v[36:37], v[40:41], v[36:37]
	v_and_b32_e32 v67, 0xffff0000, v28
	v_rcp_f32_e32 v58, v51
	s_nop 0
	v_mul_f32_e32 v51, v57, v58
	v_lshlrev_b32_e32 v66, 16, v28
	v_lshlrev_b32_e32 v28, 16, v29
	v_and_b32_e32 v29, 0xffff0000, v29
	v_rcp_f32_e32 v57, v50
	s_nop 0
	v_mul_f32_e32 v50, v56, v57
	v_pk_mul_f32 v[40:41], v[48:49], v[50:51]
	v_pk_mul_f32 v[50:51], v[68:69], v[60:61] op_sel_hi:[0,1]
	v_lshlrev_b32_e32 v48, 16, v42
	v_and_b32_e32 v49, 0xffff0000, v42
	v_pk_fma_f32 v[44:45], v[50:51], v[44:45], v[52:53]
	v_pk_mul_f32 v[56:57], v[68:69], v[64:65] op_sel_hi:[0,1]
	v_pk_fma_f32 v[44:45], v[108:109], v[48:49], v[44:45] op_sel_hi:[0,1,1]
	v_lshlrev_b32_e32 v48, 16, v38
	v_lshlrev_b32_e32 v42, 16, v43
	v_and_b32_e32 v43, 0xffff0000, v43
	v_pk_fma_f32 v[46:47], v[56:57], v[46:47], v[54:55]
	v_and_b32_e32 v49, 0xffff0000, v38
	v_mul_f32_e32 v38, 0xbfb8aa3b, v48
	v_pk_fma_f32 v[42:43], v[108:109], v[42:43], v[46:47] op_sel_hi:[0,1,1]
	v_exp_f32_e32 v46, v38
	v_mul_f32_e32 v38, 0xbfb8aa3b, v49
	v_lshlrev_b32_e32 v50, 16, v39
	v_and_b32_e32 v51, 0xffff0000, v39
	v_exp_f32_e32 v47, v38
	v_mul_f32_e32 v38, 0xbfb8aa3b, v50
	v_mul_f32_e32 v39, 0xbfb8aa3b, v51
	v_exp_f32_e32 v38, v38
	v_exp_f32_e32 v39, v39
	v_pk_add_f32 v[46:47], v[46:47], 1.0 op_sel_hi:[1,0]
	v_pk_add_f32 v[38:39], v[38:39], 1.0 op_sel_hi:[1,0]
	s_nop 0
	v_rcp_f32_e32 v52, v39
	s_nop 0
	v_mul_f32_e32 v39, v51, v52
	v_rcp_f32_e32 v51, v38
	s_nop 0
	v_mul_f32_e32 v38, v50, v51
	v_pk_mul_f32 v[38:39], v[42:43], v[38:39]
	v_lshlrev_b32_e32 v43, 16, v34
	v_lshlrev_b32_e32 v42, 16, v32
	v_rcp_f32_e32 v50, v47
	s_nop 0
	v_mul_f32_e32 v47, v49, v50
	v_rcp_f32_e32 v49, v46
	s_nop 0
	v_mul_f32_e32 v46, v48, v49
	v_pk_mul_f32 v[54:55], v[44:45], v[46:47]
	v_and_b32_e32 v45, 0xffff0000, v34
	v_and_b32_e32 v44, 0xffff0000, v32
	v_lshlrev_b32_e32 v47, 16, v35
	v_lshlrev_b32_e32 v46, 16, v33
	v_and_b32_e32 v35, 0xffff0000, v35
	v_and_b32_e32 v34, 0xffff0000, v33
	v_pk_add_f32 v[32:33], v[42:43], v[44:45]
	v_pk_add_f32 v[48:49], v[46:47], v[34:35]
	s_nop 0
	v_pk_add_f32 v[32:33], v[32:33], v[48:49]
	s_nop 0
	v_add_f32_e32 v32, v32, v33
	s_nop 1
	v_add_f32_dpp v32, v32, v32 quad_perm:[1,0,3,2] row_mask:0xf bank_mask:0xf bound_ctrl:1
	s_nop 1
	v_add_f32_dpp v32, v32, v32 quad_perm:[2,3,0,1] row_mask:0xf bank_mask:0xf bound_ctrl:1
	s_nop 1
	v_add_f32_dpp v32, v32, v32 row_half_mirror row_mask:0xf bank_mask:0xf bound_ctrl:1
	v_fmac_f32_e32 v34, 0xbc800000, v32
	v_fmac_f32_e32 v44, 0xbc800000, v32
	v_fmac_f32_e32 v35, 0xbc800000, v32
	v_fmac_f32_e32 v45, 0xbc800000, v32
	v_fmac_f32_e32 v46, 0xbc800000, v32
	v_fmac_f32_e32 v42, 0xbc800000, v32
	v_fmac_f32_e32 v47, 0xbc800000, v32
	v_fmac_f32_e32 v43, 0xbc800000, v32
	v_pk_mul_f32 v[32:33], v[44:45], v[44:45]
	v_mov_b32_e32 v61, v35
	v_mov_b32_e32 v63, v34
	v_pk_mul_f32 v[34:35], v[34:35], v[34:35]
	v_pk_fma_f32 v[32:33], v[42:43], v[42:43], v[32:33]
	v_pk_fma_f32 v[34:35], v[46:47], v[46:47], v[34:35]
	v_mov_b32_e32 v56, v43
	v_pk_add_f32 v[32:33], v[32:33], v[34:35]
	v_mov_b32_e32 v57, v45
	v_add_f32_e32 v32, v32, v33
	v_mov_b32_e32 v58, v42
	v_mov_b32_e32 v59, v44
	v_add_f32_dpp v32, v32, v32 quad_perm:[1,0,3,2] row_mask:0xf bank_mask:0xf bound_ctrl:1
	v_mov_b32_e32 v60, v47
	v_mov_b32_e32 v62, v46
	v_add_f32_dpp v32, v32, v32 quad_perm:[2,3,0,1] row_mask:0xf bank_mask:0xf bound_ctrl:1
	s_nop 1
	v_add_f32_dpp v32, v32, v32 row_half_mirror row_mask:0xf bank_mask:0xf bound_ctrl:1
	v_fmamk_f32 v32, v32, 0x3c800000, v103
	v_rsq_f32_e32 v64, v32
	global_load_dwordx4 v[42:45], v[94:95], off offset:2064
	global_load_dwordx4 v[32:35], v[94:95], off offset:2048
	global_load_dwordx4 v[46:49], v[96:97], off offset:2064
	global_load_dwordx4 v[50:53], v[96:97], off offset:2048
	v_pk_mul_f32 v[58:59], v[64:65], v[58:59] op_sel_hi:[0,1]
	v_pk_mul_f32 v[62:63], v[64:65], v[62:63] op_sel_hi:[0,1]
	s_waitcnt vmcnt(0)
	v_pk_fma_f32 v[32:33], v[58:59], v[32:33], v[50:51]
	v_lshlrev_b32_e32 v50, 16, v24
	v_pk_fma_f32 v[34:35], v[62:63], v[34:35], v[52:53]
	v_and_b32_e32 v51, 0xffff0000, v24
	v_mul_f32_e32 v24, 0xbfb8aa3b, v50
	v_pk_fma_f32 v[28:29], v[106:107], v[28:29], v[34:35] op_sel_hi:[0,1,1]
	v_exp_f32_e32 v34, v24
	v_mul_f32_e32 v24, 0xbfb8aa3b, v51
	v_lshlrev_b32_e32 v52, 16, v25
	v_and_b32_e32 v53, 0xffff0000, v25
	v_exp_f32_e32 v35, v24
	v_mul_f32_e32 v24, 0xbfb8aa3b, v52
	v_mul_f32_e32 v25, 0xbfb8aa3b, v53
	v_exp_f32_e32 v24, v24
	v_exp_f32_e32 v25, v25
	v_pk_add_f32 v[34:35], v[34:35], 1.0 op_sel_hi:[1,0]
	v_pk_fma_f32 v[32:33], v[106:107], v[66:67], v[32:33] op_sel_hi:[0,1,1]
	v_pk_add_f32 v[24:25], v[24:25], 1.0 op_sel_hi:[1,0]
	s_nop 0
	v_rcp_f32_e32 v58, v25
	s_nop 0
	v_mul_f32_e32 v25, v53, v58
	v_rcp_f32_e32 v53, v24
	s_nop 0
	v_mul_f32_e32 v24, v52, v53
	v_pk_mul_f32 v[28:29], v[28:29], v[24:25]
	v_lshlrev_b32_e32 v24, 16, v30
	v_and_b32_e32 v25, 0xffff0000, v30
	v_rcp_f32_e32 v52, v35
	s_nop 0
	v_mul_f32_e32 v35, v51, v52
	v_lshlrev_b32_e32 v30, 16, v31
	v_and_b32_e32 v31, 0xffff0000, v31
	v_rcp_f32_e32 v51, v34
	s_nop 0
	v_mul_f32_e32 v34, v50, v51
	v_pk_mul_f32 v[32:33], v[32:33], v[34:35]
	v_pk_mul_f32 v[34:35], v[64:65], v[56:57] op_sel_hi:[0,1]
	v_pk_mul_f32 v[50:51], v[64:65], v[60:61] op_sel_hi:[0,1]
	v_pk_fma_f32 v[34:35], v[34:35], v[42:43], v[46:47]
	v_lshlrev_b32_e32 v42, 16, v26
	v_pk_fma_f32 v[44:45], v[50:51], v[44:45], v[48:49]
	v_and_b32_e32 v43, 0xffff0000, v26
	v_mul_f32_e32 v26, 0xbfb8aa3b, v42
	v_pk_fma_f32 v[24:25], v[106:107], v[24:25], v[34:35] op_sel_hi:[0,1,1]
	v_pk_fma_f32 v[30:31], v[106:107], v[30:31], v[44:45] op_sel_hi:[0,1,1]
	v_exp_f32_e32 v34, v26
	v_mul_f32_e32 v26, 0xbfb8aa3b, v43
	v_lshlrev_b32_e32 v44, 16, v27
	v_and_b32_e32 v45, 0xffff0000, v27
	v_exp_f32_e32 v35, v26
	v_mul_f32_e32 v26, 0xbfb8aa3b, v44
	v_mul_f32_e32 v27, 0xbfb8aa3b, v45
	v_exp_f32_e32 v26, v26
	v_exp_f32_e32 v27, v27
	v_pk_add_f32 v[34:35], v[34:35], 1.0 op_sel_hi:[1,0]
	v_pk_add_f32 v[26:27], v[26:27], 1.0 op_sel_hi:[1,0]
	s_nop 0
	v_rcp_f32_e32 v46, v27
	s_nop 0
	v_mul_f32_e32 v27, v45, v46
	v_rcp_f32_e32 v45, v26
	s_nop 0
	v_mul_f32_e32 v26, v44, v45
	v_pk_mul_f32 v[30:31], v[30:31], v[26:27]
	v_rcp_f32_e32 v44, v35
	s_nop 0
	v_mul_f32_e32 v35, v43, v44
	v_rcp_f32_e32 v43, v34
	s_nop 0
	v_mul_f32_e32 v34, v42, v43
	v_pk_mul_f32 v[34:35], v[24:25], v[34:35]
	v_cvt_pk_bf16_f32 v24, v40, v41
	v_cvt_pk_bf16_f32 v25, v36, v37
	v_add_co_u32_e32 v36, vcc, s5, v100
	v_cvt_pk_bf16_f32 v26, v54, v55
	v_cvt_pk_bf16_f32 v27, v38, v39
	v_lshlrev_b32_e32 v46, 16, v16
	s_nop 0
	v_addc_co_u32_e32 v37, vcc, 0, v101, vcc
	global_store_dwordx4 v[36:37], v[24:27], off
	v_and_b32_e32 v47, 0xffff0000, v16
	v_lshlrev_b32_e32 v16, 16, v17
	v_cvt_pk_bf16_f32 v24, v32, v33
	v_cvt_pk_bf16_f32 v25, v28, v29
	v_cvt_pk_bf16_f32 v26, v34, v35
	v_cvt_pk_bf16_f32 v27, v30, v31
	global_store_dwordx4 v[36:37], v[24:27], off offset:1024
	v_lshlrev_b32_e32 v29, 16, v23
	v_lshlrev_b32_e32 v28, 16, v21
	v_lshlrev_b32_e32 v25, 16, v22
	v_lshlrev_b32_e32 v24, 16, v20
	v_and_b32_e32 v27, 0xffff0000, v22
	v_and_b32_e32 v26, 0xffff0000, v20
	v_and_b32_e32 v23, 0xffff0000, v23
	v_and_b32_e32 v22, 0xffff0000, v21
	v_pk_add_f32 v[20:21], v[24:25], v[26:27]
	v_pk_add_f32 v[30:31], v[28:29], v[22:23]
	v_and_b32_e32 v17, 0xffff0000, v17
	v_pk_add_f32 v[20:21], v[20:21], v[30:31]
	s_nop 0
	v_add_f32_e32 v20, v20, v21
	s_nop 1
	v_add_f32_dpp v20, v20, v20 quad_perm:[1,0,3,2] row_mask:0xf bank_mask:0xf bound_ctrl:1
	s_nop 1
	v_add_f32_dpp v20, v20, v20 quad_perm:[2,3,0,1] row_mask:0xf bank_mask:0xf bound_ctrl:1
	s_nop 1
	v_add_f32_dpp v20, v20, v20 row_half_mirror row_mask:0xf bank_mask:0xf bound_ctrl:1
	v_fmac_f32_e32 v22, 0xbc800000, v20
	v_fmac_f32_e32 v26, 0xbc800000, v20
	v_fmac_f32_e32 v23, 0xbc800000, v20
	v_fmac_f32_e32 v27, 0xbc800000, v20
	v_fmac_f32_e32 v28, 0xbc800000, v20
	v_fmac_f32_e32 v24, 0xbc800000, v20
	v_fmac_f32_e32 v29, 0xbc800000, v20
	v_fmac_f32_e32 v25, 0xbc800000, v20
	v_pk_mul_f32 v[20:21], v[26:27], v[26:27]
	v_mov_b32_e32 v41, v23
	v_mov_b32_e32 v43, v22
	v_pk_mul_f32 v[22:23], v[22:23], v[22:23]
	v_pk_fma_f32 v[20:21], v[24:25], v[24:25], v[20:21]
	v_pk_fma_f32 v[22:23], v[28:29], v[28:29], v[22:23]
	v_mov_b32_e32 v36, v25
	v_pk_add_f32 v[20:21], v[20:21], v[22:23]
	v_mov_b32_e32 v37, v27
	v_add_f32_e32 v20, v20, v21
	v_mov_b32_e32 v38, v24
	v_mov_b32_e32 v39, v26
	v_add_f32_dpp v20, v20, v20 quad_perm:[1,0,3,2] row_mask:0xf bank_mask:0xf bound_ctrl:1
	v_mov_b32_e32 v40, v29
	v_mov_b32_e32 v42, v28
	v_add_f32_dpp v20, v20, v20 quad_perm:[2,3,0,1] row_mask:0xf bank_mask:0xf bound_ctrl:1
	s_nop 1
	v_add_f32_dpp v20, v20, v20 row_half_mirror row_mask:0xf bank_mask:0xf bound_ctrl:1
	v_fmamk_f32 v20, v20, 0x3c800000, v103
	v_rsq_f32_e32 v44, v20
	global_load_dwordx4 v[20:23], v[94:95], off offset:16
	global_load_dwordx4 v[24:27], v[94:95], off
	global_load_dwordx4 v[28:31], v[96:97], off offset:16
	global_load_dwordx4 v[32:35], v[96:97], off
	v_pk_mul_f32 v[38:39], v[44:45], v[38:39] op_sel_hi:[0,1]
	v_pk_mul_f32 v[42:43], v[44:45], v[42:43] op_sel_hi:[0,1]
	s_waitcnt vmcnt(0)
	v_pk_fma_f32 v[24:25], v[38:39], v[24:25], v[32:33]
	v_lshlrev_b32_e32 v32, 16, v12
	v_pk_fma_f32 v[26:27], v[42:43], v[26:27], v[34:35]
	v_and_b32_e32 v33, 0xffff0000, v12
	v_mul_f32_e32 v12, 0xbfb8aa3b, v32
	v_pk_fma_f32 v[16:17], v[104:105], v[16:17], v[26:27] op_sel_hi:[0,1,1]
	v_exp_f32_e32 v26, v12
	v_mul_f32_e32 v12, 0xbfb8aa3b, v33
	v_lshlrev_b32_e32 v34, 16, v13
	v_and_b32_e32 v35, 0xffff0000, v13
	v_exp_f32_e32 v27, v12
	v_mul_f32_e32 v12, 0xbfb8aa3b, v34
	v_mul_f32_e32 v13, 0xbfb8aa3b, v35
	v_exp_f32_e32 v12, v12
	v_exp_f32_e32 v13, v13
	v_pk_add_f32 v[26:27], v[26:27], 1.0 op_sel_hi:[1,0]
	v_pk_fma_f32 v[24:25], v[104:105], v[46:47], v[24:25] op_sel_hi:[0,1,1]
	v_pk_add_f32 v[12:13], v[12:13], 1.0 op_sel_hi:[1,0]
	s_nop 0
	v_rcp_f32_e32 v38, v13
	s_nop 0
	v_mul_f32_e32 v13, v35, v38
	v_rcp_f32_e32 v35, v12
	s_nop 0
	v_mul_f32_e32 v12, v34, v35
	v_pk_mul_f32 v[12:13], v[16:17], v[12:13]
	v_and_b32_e32 v43, 0xffff0000, v4
	v_rcp_f32_e32 v34, v27
	s_nop 0
	v_mul_f32_e32 v27, v33, v34
	v_lshlrev_b32_e32 v42, 16, v4
	v_lshlrev_b32_e32 v4, 16, v5
	v_and_b32_e32 v5, 0xffff0000, v5
	v_rcp_f32_e32 v33, v26
	s_nop 0
	v_mul_f32_e32 v26, v32, v33
	v_pk_mul_f32 v[16:17], v[24:25], v[26:27]
	v_pk_mul_f32 v[26:27], v[44:45], v[36:37] op_sel_hi:[0,1]
	v_lshlrev_b32_e32 v24, 16, v18
	v_and_b32_e32 v25, 0xffff0000, v18
	v_pk_fma_f32 v[20:21], v[26:27], v[20:21], v[28:29]
	v_pk_mul_f32 v[32:33], v[44:45], v[40:41] op_sel_hi:[0,1]
	v_pk_fma_f32 v[20:21], v[104:105], v[24:25], v[20:21] op_sel_hi:[0,1,1]
	v_lshlrev_b32_e32 v24, 16, v14
	v_lshlrev_b32_e32 v18, 16, v19
	v_and_b32_e32 v19, 0xffff0000, v19
	v_pk_fma_f32 v[22:23], v[32:33], v[22:23], v[30:31]
	v_and_b32_e32 v25, 0xffff0000, v14
	v_mul_f32_e32 v14, 0xbfb8aa3b, v24
	v_pk_fma_f32 v[18:19], v[104:105], v[18:19], v[22:23] op_sel_hi:[0,1,1]
	v_exp_f32_e32 v22, v14
	v_mul_f32_e32 v14, 0xbfb8aa3b, v25
	v_lshlrev_b32_e32 v26, 16, v15
	v_and_b32_e32 v27, 0xffff0000, v15
	v_exp_f32_e32 v23, v14
	v_mul_f32_e32 v14, 0xbfb8aa3b, v26
	v_mul_f32_e32 v15, 0xbfb8aa3b, v27
	v_exp_f32_e32 v14, v14
	v_exp_f32_e32 v15, v15
	v_pk_add_f32 v[22:23], v[22:23], 1.0 op_sel_hi:[1,0]
	v_pk_add_f32 v[14:15], v[14:15], 1.0 op_sel_hi:[1,0]
	s_nop 0
	v_rcp_f32_e32 v28, v15
	s_nop 0
	v_mul_f32_e32 v15, v27, v28
	v_rcp_f32_e32 v27, v14
	s_nop 0
	v_mul_f32_e32 v14, v26, v27
	v_pk_mul_f32 v[14:15], v[18:19], v[14:15]
	v_lshlrev_b32_e32 v19, 16, v10
	v_lshlrev_b32_e32 v18, 16, v8
	v_rcp_f32_e32 v26, v23
	s_nop 0
	v_mul_f32_e32 v23, v25, v26
	v_rcp_f32_e32 v25, v22
	s_nop 0
	v_mul_f32_e32 v22, v24, v25
	v_pk_mul_f32 v[30:31], v[20:21], v[22:23]
	v_and_b32_e32 v21, 0xffff0000, v10
	v_and_b32_e32 v20, 0xffff0000, v8
	v_lshlrev_b32_e32 v23, 16, v11
	v_lshlrev_b32_e32 v22, 16, v9
	v_and_b32_e32 v11, 0xffff0000, v11
	v_and_b32_e32 v10, 0xffff0000, v9
	v_pk_add_f32 v[8:9], v[18:19], v[20:21]
	v_pk_add_f32 v[24:25], v[22:23], v[10:11]
	s_nop 0
	v_pk_add_f32 v[8:9], v[8:9], v[24:25]
	s_nop 0
	v_add_f32_e32 v8, v8, v9
	s_nop 1
	v_add_f32_dpp v8, v8, v8 quad_perm:[1,0,3,2] row_mask:0xf bank_mask:0xf bound_ctrl:1
	s_nop 1
	v_add_f32_dpp v8, v8, v8 quad_perm:[2,3,0,1] row_mask:0xf bank_mask:0xf bound_ctrl:1
	s_nop 1
	v_add_f32_dpp v8, v8, v8 row_half_mirror row_mask:0xf bank_mask:0xf bound_ctrl:1
	v_fmac_f32_e32 v10, 0xbc800000, v8
	v_fmac_f32_e32 v20, 0xbc800000, v8
	v_fmac_f32_e32 v11, 0xbc800000, v8
	v_fmac_f32_e32 v21, 0xbc800000, v8
	v_fmac_f32_e32 v22, 0xbc800000, v8
	v_fmac_f32_e32 v18, 0xbc800000, v8
	v_fmac_f32_e32 v23, 0xbc800000, v8
	v_fmac_f32_e32 v19, 0xbc800000, v8
	v_pk_mul_f32 v[8:9], v[20:21], v[20:21]
	v_mov_b32_e32 v37, v11
	v_mov_b32_e32 v39, v10
	v_pk_mul_f32 v[10:11], v[10:11], v[10:11]
	v_pk_fma_f32 v[8:9], v[18:19], v[18:19], v[8:9]
	v_pk_fma_f32 v[10:11], v[22:23], v[22:23], v[10:11]
	v_mov_b32_e32 v32, v19
	v_pk_add_f32 v[8:9], v[8:9], v[10:11]
	v_mov_b32_e32 v33, v21
	v_add_f32_e32 v8, v8, v9
	v_mov_b32_e32 v34, v18
	v_mov_b32_e32 v35, v20
	v_add_f32_dpp v8, v8, v8 quad_perm:[1,0,3,2] row_mask:0xf bank_mask:0xf bound_ctrl:1
	v_mov_b32_e32 v36, v23
	v_mov_b32_e32 v38, v22
	v_add_f32_dpp v8, v8, v8 quad_perm:[2,3,0,1] row_mask:0xf bank_mask:0xf bound_ctrl:1
	s_nop 1
	v_add_f32_dpp v8, v8, v8 row_half_mirror row_mask:0xf bank_mask:0xf bound_ctrl:1
	v_fmamk_f32 v8, v8, 0x3c800000, v103
	v_rsq_f32_e32 v40, v8
	global_load_dwordx4 v[18:21], v[94:95], off offset:2064
	global_load_dwordx4 v[8:11], v[94:95], off offset:2048
	global_load_dwordx4 v[22:25], v[96:97], off offset:2064
	global_load_dwordx4 v[26:29], v[96:97], off offset:2048
	v_pk_mul_f32 v[34:35], v[40:41], v[34:35] op_sel_hi:[0,1]
	v_pk_mul_f32 v[38:39], v[40:41], v[38:39] op_sel_hi:[0,1]
	s_waitcnt vmcnt(0)
	v_pk_fma_f32 v[8:9], v[34:35], v[8:9], v[26:27]
	v_lshlrev_b32_e32 v26, 16, v0
	v_pk_fma_f32 v[10:11], v[38:39], v[10:11], v[28:29]
	v_and_b32_e32 v27, 0xffff0000, v0
	v_mul_f32_e32 v0, 0xbfb8aa3b, v26
	v_pk_fma_f32 v[4:5], v[102:103], v[4:5], v[10:11] op_sel_hi:[0,1,1]
	v_exp_f32_e32 v10, v0
	v_mul_f32_e32 v0, 0xbfb8aa3b, v27
	v_lshlrev_b32_e32 v28, 16, v1
	v_and_b32_e32 v29, 0xffff0000, v1
	v_exp_f32_e32 v11, v0
	v_mul_f32_e32 v0, 0xbfb8aa3b, v28
	v_mul_f32_e32 v1, 0xbfb8aa3b, v29
	v_exp_f32_e32 v0, v0
	v_exp_f32_e32 v1, v1
	v_pk_add_f32 v[10:11], v[10:11], 1.0 op_sel_hi:[1,0]
	v_pk_fma_f32 v[8:9], v[102:103], v[42:43], v[8:9] op_sel_hi:[0,1,1]
	v_pk_add_f32 v[0:1], v[0:1], 1.0 op_sel_hi:[1,0]
	s_nop 0
	v_rcp_f32_e32 v34, v1
	s_nop 0
	v_mul_f32_e32 v1, v29, v34
	v_rcp_f32_e32 v29, v0
	s_nop 0
	v_mul_f32_e32 v0, v28, v29
	v_pk_mul_f32 v[4:5], v[4:5], v[0:1]
	v_lshlrev_b32_e32 v0, 16, v6
	v_and_b32_e32 v1, 0xffff0000, v6
	v_rcp_f32_e32 v28, v11
	s_nop 0
	v_mul_f32_e32 v11, v27, v28
	v_lshlrev_b32_e32 v6, 16, v7
	v_and_b32_e32 v7, 0xffff0000, v7
	v_rcp_f32_e32 v27, v10
	s_nop 0
	v_mul_f32_e32 v10, v26, v27
	v_pk_mul_f32 v[8:9], v[8:9], v[10:11]
	v_pk_mul_f32 v[10:11], v[40:41], v[32:33] op_sel_hi:[0,1]
	v_pk_mul_f32 v[26:27], v[40:41], v[36:37] op_sel_hi:[0,1]
	v_pk_fma_f32 v[10:11], v[10:11], v[18:19], v[22:23]
	v_lshlrev_b32_e32 v18, 16, v2
	v_pk_fma_f32 v[20:21], v[26:27], v[20:21], v[24:25]
	v_and_b32_e32 v19, 0xffff0000, v2
	v_mul_f32_e32 v2, 0xbfb8aa3b, v18
	v_pk_fma_f32 v[0:1], v[102:103], v[0:1], v[10:11] op_sel_hi:[0,1,1]
	v_pk_fma_f32 v[6:7], v[102:103], v[6:7], v[20:21] op_sel_hi:[0,1,1]
	v_exp_f32_e32 v10, v2
	v_mul_f32_e32 v2, 0xbfb8aa3b, v19
	v_lshlrev_b32_e32 v20, 16, v3
	v_and_b32_e32 v21, 0xffff0000, v3
	v_exp_f32_e32 v11, v2
	v_mul_f32_e32 v2, 0xbfb8aa3b, v20
	v_mul_f32_e32 v3, 0xbfb8aa3b, v21
	v_exp_f32_e32 v2, v2
	v_exp_f32_e32 v3, v3
	v_pk_add_f32 v[10:11], v[10:11], 1.0 op_sel_hi:[1,0]
	v_pk_add_f32 v[2:3], v[2:3], 1.0 op_sel_hi:[1,0]
	s_nop 0
	v_rcp_f32_e32 v22, v3
	s_nop 0
	v_mul_f32_e32 v3, v21, v22
	v_rcp_f32_e32 v21, v2
	s_nop 0
	v_mul_f32_e32 v2, v20, v21
	v_pk_mul_f32 v[6:7], v[6:7], v[2:3]
	v_rcp_f32_e32 v20, v11
	s_nop 0
	v_mul_f32_e32 v11, v19, v20
	v_rcp_f32_e32 v19, v10
	s_nop 0
	v_mul_f32_e32 v10, v18, v19
	v_pk_mul_f32 v[10:11], v[0:1], v[10:11]
	v_cvt_pk_bf16_f32 v0, v16, v17
	v_cvt_pk_bf16_f32 v1, v12, v13
	v_add_co_u32_e32 v12, vcc, s12, v100
	v_cvt_pk_bf16_f32 v2, v30, v31
	v_cvt_pk_bf16_f32 v3, v14, v15
	s_nop 1
	v_addc_co_u32_e32 v13, vcc, 0, v101, vcc
	global_store_dwordx4 v[12:13], v[0:3], off
	s_nop 1
	v_cvt_pk_bf16_f32 v0, v8, v9
	v_cvt_pk_bf16_f32 v1, v4, v5
	v_cvt_pk_bf16_f32 v2, v10, v11
	v_cvt_pk_bf16_f32 v3, v6, v7
	global_store_dwordx4 v[12:13], v[0:3], off offset:1024
	s_cbranch_scc0 .LBB0_904

.LBB0_1031:
	v_add_co_u32_e32 v62, vcc, 0xffe80000, v58
	v_add_co_u32_e64 v42, s[0:1], s4, v60
	v_lshl_add_u64 v[40:41], v[60:61], 0, s[16:17]
	s_nop 0
	v_addc_co_u32_e64 v43, s[0:1], -1, v61, s[0:1]
	v_addc_co_u32_e32 v63, vcc, -1, v59, vcc
	v_lshl_add_u64 v[74:75], v[60:61], 0, s[18:19]
	global_load_dwordx4 v[36:39], v[58:59], off offset:-1024 nt
	global_load_dwordx4 v[16:19], v[58:59], off nt
	global_load_dwordx4 v[4:7], v[60:61], off offset:-2048 nt
	global_load_dwordx4 v[12:15], v[60:61], off offset:-2064 nt
	global_load_dwordx4 v[0:3], v[60:61], off nt
	global_load_dwordx4 v[8:11], v[60:61], off offset:-16 nt
	global_load_dwordx4 v[20:23], v[56:57], off offset:16
	global_load_dwordx4 v[24:27], v[56:57], off
	global_load_dwordx4 v[28:31], v[56:57], off offset:2064
	global_load_dwordx4 v[32:35], v[56:57], off offset:2048
	global_load_dwordx4 v[52:55], v[42:43], off offset:-2064 nt
	global_load_dwordx4 v[48:51], v[40:41], off offset:16 nt
	global_load_dwordx4 v[44:47], v[42:43], off offset:-16 nt
	s_nop 0
	global_load_dwordx4 v[40:43], v[74:75], off offset:16 nt
	global_load_dwordx4 v[84:87], v[62:63], off offset:-1024 nt
	global_load_dwordx4 v[88:91], v[62:63], off nt
	v_add_co_u32_e32 v100, vcc, 0xffd00000, v60
	v_lshl_add_u64 v[64:65], v[60:61], 0, s[8:9]
	s_nop 0
	v_addc_co_u32_e32 v101, vcc, -1, v61, vcc
	v_lshl_add_u64 v[68:69], v[60:61], 0, s[10:11]
	global_load_dwordx4 v[92:95], v[100:101], off offset:-2064 nt
	global_load_dwordx4 v[96:99], v[64:65], off offset:16 nt
	s_nop 0
	global_load_dwordx4 v[100:103], v[100:101], off offset:-16 nt
	s_nop 0
	global_load_dwordx4 v[104:107], v[68:69], off offset:16 nt
	v_add_co_u32_e32 v62, vcc, 0xfff00000, v58
	v_lshl_add_u64 v[66:67], v[60:61], 0, s[12:13]
	s_nop 0
	v_addc_co_u32_e32 v63, vcc, -1, v59, vcc
	v_add_co_u32_e32 v64, vcc, 0xffe00000, v60
	v_lshl_add_u64 v[70:71], v[60:61], 0, s[14:15]
	s_nop 0
	v_addc_co_u32_e32 v65, vcc, -1, v61, vcc
	global_load_dwordx4 v[108:111], v[62:63], off offset:-1024 nt
	global_load_dwordx4 v[112:115], v[62:63], off nt
	global_load_dwordx4 v[116:119], v[64:65], off offset:-2064 nt
	s_nop 0
	global_load_dwordx4 v[66:69], v[66:67], off offset:16 nt
	s_nop 0
	global_load_dwordx4 v[120:123], v[64:65], off offset:-16 nt
	global_load_dwordx4 v[124:127], v[70:71], off offset:16 nt
	v_add_co_u32_e64 v72, s[0:1], s5, v58
	v_add_co_u32_e32 v62, vcc, 0xfff80000, v58
	s_nop 0
	v_addc_co_u32_e64 v73, s[0:1], -1, v59, s[0:1]
	v_add_co_u32_e64 v76, s[0:1], s7, v58
	v_addc_co_u32_e32 v63, vcc, -1, v59, vcc
	s_nop 0
	v_addc_co_u32_e64 v77, s[0:1], -1, v59, s[0:1]
	v_add_co_u32_e64 v78, s[0:1], s24, v58
	global_load_dwordx4 v[128:131], v[62:63], off offset:-1024 nt
	global_load_dwordx4 v[132:135], v[62:63], off nt
	v_addc_co_u32_e64 v79, s[0:1], -1, v59, s[0:1]
	v_add_co_u32_e64 v80, s[0:1], s25, v58
	s_addk_i32 s6, 0xfc00
	s_nop 0
	v_addc_co_u32_e64 v81, s[0:1], -1, v59, s[0:1]
	s_cmp_lt_i32 s6, s73
	v_lshl_add_u64 v[60:61], v[60:61], 0, s[22:23]
	v_lshl_add_u64 v[58:59], v[58:59], 0, s[20:21]
	s_waitcnt vmcnt(27)
	v_lshlrev_b32_e32 v62, 16, v36
	v_and_b32_e32 v63, 0xffff0000, v36
	v_lshlrev_b32_e32 v36, 16, v37
	v_and_b32_e32 v37, 0xffff0000, v37
	v_lshlrev_b32_e32 v65, 16, v39
	v_lshlrev_b32_e32 v64, 16, v38
	v_and_b32_e32 v39, 0xffff0000, v39
	v_and_b32_e32 v38, 0xffff0000, v38
	s_waitcnt vmcnt(13)
	v_lshlrev_b32_e32 v70, 16, v84
	v_and_b32_e32 v71, 0xffff0000, v84
	v_lshlrev_b32_e32 v74, 16, v85
	v_and_b32_e32 v75, 0xffff0000, v85
	v_lshlrev_b32_e32 v85, 16, v87
	v_lshlrev_b32_e32 v84, 16, v86
	v_and_b32_e32 v87, 0xffff0000, v87
	v_and_b32_e32 v86, 0xffff0000, v86
	s_waitcnt vmcnt(12)
	v_lshlrev_b32_e32 v139, 16, v90
	v_mul_f32_e32 v138, v75, v75
	v_pk_mul_f32 v[142:143], v[86:87], v[86:87]
	v_mul_f32_e32 v144, v71, v71
	v_mov_b32_e32 v145, v139
	v_lshlrev_b32_e32 v136, 16, v88
	v_and_b32_e32 v137, 0xffff0000, v88
	v_lshlrev_b32_e32 v88, 16, v89
	v_and_b32_e32 v89, 0xffff0000, v89
	v_mov_b32_e32 v150, v84
	v_mov_b32_e32 v151, v86
	v_mov_b32_e32 v86, v85
	v_pk_fma_f32 v[152:153], v[74:75], v[74:75], v[138:139] op_sel_hi:[1,1,0]
	v_pk_fma_f32 v[84:85], v[84:85], v[84:85], v[142:143]
	v_pk_fma_f32 v[142:143], v[70:71], v[70:71], v[144:145] op_sel_hi:[1,1,0]
	v_and_b32_e32 v141, 0xffff0000, v90
	v_lshlrev_b32_e32 v90, 16, v91
	v_and_b32_e32 v91, 0xffff0000, v91
	v_mul_f32_e32 v146, v137, v137
	v_mul_f32_e32 v148, v89, v89
	v_mov_b32_e32 v138, v142
	v_mov_b32_e32 v144, v152
	v_mul_f32_e32 v83, v141, v141
	v_mul_f32_e32 v160, v90, v90
	v_mul_f32_e32 v162, v91, v91
	v_mov_b32_e32 v140, v139
	v_pk_fma_f32 v[146:147], v[136:137], v[136:137], v[146:147] op_sel_hi:[1,1,0]
	v_pk_fma_f32 v[148:149], v[88:89], v[88:89], v[148:149] op_sel_hi:[1,1,0]
	v_pk_add_f32 v[142:143], v[142:143], v[152:153]
	v_pk_add_f32 v[84:85], v[84:85], v[84:85] op_sel:[0,1] op_sel_hi:[1,0]
	v_pk_mul_f32 v[138:139], v[138:139], v[144:145]
	v_mov_b32_e32 v147, v160
	v_mov_b32_e32 v149, v162
	v_mov_b32_e32 v85, v83
	v_mov_b32_e32 v143, v139
	v_pk_add_f32 v[144:145], v[146:147], v[148:149]
	v_pk_add_f32 v[84:85], v[142:143], v[84:85]
	s_waitcnt vmcnt(7)
	v_lshlrev_b32_e32 v154, 16, v108
	v_pk_add_f32 v[84:85], v[84:85], v[144:145]
	v_and_b32_e32 v155, 0xffff0000, v108
	v_add_f32_e32 v83, v84, v85
	v_lshlrev_b32_e32 v108, 16, v109
	v_and_b32_e32 v109, 0xffff0000, v109
	v_add_f32_dpp v83, v83, v83 quad_perm:[1,0,3,2] row_mask:0xf bank_mask:0xf bound_ctrl:1
	v_lshlrev_b32_e32 v157, 16, v111
	v_lshlrev_b32_e32 v156, 16, v110
	v_add_f32_dpp v83, v83, v83 quad_perm:[2,3,0,1] row_mask:0xf bank_mask:0xf bound_ctrl:1
	v_and_b32_e32 v111, 0xffff0000, v111
	v_and_b32_e32 v110, 0xffff0000, v110
	v_add_f32_dpp v83, v83, v83 row_half_mirror row_mask:0xf bank_mask:0xf bound_ctrl:1
	s_waitcnt vmcnt(6)
	v_lshlrev_b32_e32 v161, 16, v114
	v_mul_f32_e32 v152, v109, v109
	v_add_f32_dpp v83, v83, v83 row_mirror row_mask:0xf bank_mask:0xf bound_ctrl:1
	v_pk_mul_f32 v[164:165], v[110:111], v[110:111]
	v_readlane_b32 s26, v83, 16
	v_readlane_b32 s27, v83, 48
	v_readlane_b32 s0, v83, 0
	v_readlane_b32 s1, v83, 32
	v_mov_b32_e32 v84, s26
	v_mov_b32_e32 v85, s27
	v_pk_add_f32 v[84:85], s[0:1], v[84:85]
	v_mul_f32_e32 v160, v155, v155
	v_add_f32_e32 v83, v84, v85
	v_fmamk_f32 v83, v83, 0x3a800000, v82
	v_rsq_f32_e32 v84, v83
	v_mov_b32_e32 v153, v161
	v_lshlrev_b32_e32 v158, 16, v112
	v_and_b32_e32 v159, 0xffff0000, v112
	v_pk_mul_f32 v[70:71], v[84:85], v[70:71] op_sel_hi:[0,1]
	v_pk_mul_f32 v[142:143], v[84:85], v[150:151] op_sel_hi:[0,1]
	v_pk_mul_f32 v[86:87], v[84:85], v[86:87] op_sel_hi:[0,1]
	v_pk_mul_f32 v[74:75], v[84:85], v[74:75] op_sel_hi:[0,1]
	v_pk_fma_f32 v[24:25], v[70:71], v[24:25], v[92:93]
	v_pk_fma_f32 v[70:71], v[86:87], v[22:23], v[98:99]
	v_pk_fma_f32 v[22:23], v[142:143], v[20:21], v[96:97]
	v_pk_mul_f32 v[136:137], v[84:85], v[136:137] op_sel_hi:[0,1]
	v_pk_mul_f32 v[88:89], v[84:85], v[88:89] op_sel_hi:[0,1]
	v_pk_mul_f32 v[140:141], v[84:85], v[140:141] op_sel_hi:[0,1]
	v_pk_mul_f32 v[84:85], v[84:85], v[90:91] op_sel_hi:[0,1]
	v_pk_fma_f32 v[26:27], v[74:75], v[26:27], v[94:95]
	v_cvt_pk_bf16_f32 v20, v24, v25
	v_pk_fma_f32 v[34:35], v[88:89], v[34:35], v[102:103]
	v_cvt_pk_bf16_f32 v21, v26, v27
	v_cvt_pk_bf16_f32 v22, v22, v23
	v_cvt_pk_bf16_f32 v23, v70, v71
	v_pk_fma_f32 v[32:33], v[136:137], v[32:33], v[100:101]
	v_pk_fma_f32 v[30:31], v[84:85], v[30:31], v[106:107]
	v_pk_fma_f32 v[28:29], v[140:141], v[28:29], v[104:105]
	global_store_dwordx4 v[72:73], v[20:23], off offset:-1024
	v_lshlrev_b32_e32 v112, 16, v113
	v_and_b32_e32 v113, 0xffff0000, v113
	v_cvt_pk_bf16_f32 v20, v32, v33
	v_cvt_pk_bf16_f32 v21, v34, v35
	v_cvt_pk_bf16_f32 v22, v28, v29
	v_cvt_pk_bf16_f32 v23, v30, v31
	global_store_dwordx4 v[72:73], v[20:23], off
	global_load_dwordx4 v[20:23], v[56:57], off
	s_nop 0
	global_load_dwordx4 v[24:27], v[56:57], off offset:16
	global_load_dwordx4 v[28:31], v[56:57], off offset:2048
	global_load_dwordx4 v[32:35], v[56:57], off offset:2064
	v_mov_b32_e32 v170, v156
	v_mov_b32_e32 v171, v110
	v_mov_b32_e32 v110, v157
	v_pk_fma_f32 v[146:147], v[108:109], v[108:109], v[152:153] op_sel_hi:[1,1,0]
	v_pk_fma_f32 v[148:149], v[156:157], v[156:157], v[164:165]
	v_pk_fma_f32 v[156:157], v[154:155], v[154:155], v[160:161] op_sel_hi:[1,1,0]
	v_and_b32_e32 v163, 0xffff0000, v114
	v_lshlrev_b32_e32 v114, 16, v115
	v_and_b32_e32 v115, 0xffff0000, v115
	v_mul_f32_e32 v166, v159, v159
	v_mul_f32_e32 v168, v113, v113
	v_mov_b32_e32 v160, v156
	v_mov_b32_e32 v152, v146
	v_mul_f32_e32 v176, v163, v163
	v_mul_f32_e32 v178, v114, v114
	v_mul_f32_e32 v180, v115, v115
	v_pk_fma_f32 v[164:165], v[158:159], v[158:159], v[166:167] op_sel_hi:[1,1,0]
	v_pk_fma_f32 v[166:167], v[112:113], v[112:113], v[168:169] op_sel_hi:[1,1,0]
	v_pk_add_f32 v[138:139], v[156:157], v[146:147]
	v_pk_add_f32 v[146:147], v[148:149], v[148:149] op_sel:[0,1] op_sel_hi:[1,0]
	v_pk_mul_f32 v[72:73], v[160:161], v[152:153]
	v_mov_b32_e32 v165, v178
	v_mov_b32_e32 v167, v180
	v_mov_b32_e32 v147, v176
	v_mov_b32_e32 v139, v73
	v_pk_add_f32 v[74:75], v[164:165], v[166:167]
	v_pk_add_f32 v[72:73], v[138:139], v[146:147]
	v_mov_b32_e32 v162, v161
	v_pk_add_f32 v[72:73], v[72:73], v[74:75]
	s_waitcnt vmcnt(7)
	v_lshlrev_b32_e32 v168, 16, v128
	v_add_f32_e32 v71, v72, v73
	v_and_b32_e32 v169, 0xffff0000, v128
	v_lshlrev_b32_e32 v128, 16, v129
	v_add_f32_dpp v71, v71, v71 quad_perm:[1,0,3,2] row_mask:0xf bank_mask:0xf bound_ctrl:1
	v_and_b32_e32 v129, 0xffff0000, v129
	v_lshlrev_b32_e32 v173, 16, v131
	v_add_f32_dpp v71, v71, v71 quad_perm:[2,3,0,1] row_mask:0xf bank_mask:0xf bound_ctrl:1
	v_lshlrev_b32_e32 v172, 16, v130
	v_and_b32_e32 v131, 0xffff0000, v131
	v_add_f32_dpp v71, v71, v71 row_half_mirror row_mask:0xf bank_mask:0xf bound_ctrl:1
	v_and_b32_e32 v130, 0xffff0000, v130
	s_waitcnt vmcnt(6)
	v_and_b32_e32 v175, 0xffff0000, v132
	v_add_f32_dpp v71, v71, v71 row_mirror row_mask:0xf bank_mask:0xf bound_ctrl:1
	v_lshlrev_b32_e32 v177, 16, v134
	v_readlane_b32 s26, v71, 16
	v_readlane_b32 s27, v71, 48
	v_readlane_b32 s0, v71, 0
	v_readlane_b32 s1, v71, 32
	v_mov_b32_e32 v72, s26
	v_mov_b32_e32 v73, s27
	v_pk_add_f32 v[72:73], s[0:1], v[72:73]
	v_mul_f32_e32 v148, v129, v129
	v_add_f32_e32 v71, v72, v73
	v_fmamk_f32 v71, v71, 0x3a800000, v82
	v_rsq_f32_e32 v72, v71
	v_mul_f32_e32 v70, v169, v169
	v_lshlrev_b32_e32 v174, 16, v132
	v_lshlrev_b32_e32 v132, 16, v133
	v_pk_mul_f32 v[74:75], v[72:73], v[154:155] op_sel_hi:[0,1]
	v_pk_mul_f32 v[84:85], v[72:73], v[108:109] op_sel_hi:[0,1]
	v_pk_mul_f32 v[86:87], v[72:73], v[170:171] op_sel_hi:[0,1]
	v_pk_mul_f32 v[88:89], v[72:73], v[110:111] op_sel_hi:[0,1]
	v_pk_mul_f32 v[90:91], v[72:73], v[158:159] op_sel_hi:[0,1]
	v_pk_mul_f32 v[92:93], v[72:73], v[112:113] op_sel_hi:[0,1]
	v_pk_mul_f32 v[94:95], v[72:73], v[162:163] op_sel_hi:[0,1]
	v_pk_mul_f32 v[72:73], v[72:73], v[114:115] op_sel_hi:[0,1]
	v_and_b32_e32 v133, 0xffff0000, v133
	v_pk_mul_f32 v[156:157], v[130:131], v[130:131]
	v_pk_fma_f32 v[70:71], v[168:169], v[168:169], v[70:71] op_sel_hi:[1,1,0]
	v_and_b32_e32 v179, 0xffff0000, v134
	v_lshlrev_b32_e32 v134, 16, v135
	v_and_b32_e32 v135, 0xffff0000, v135
	v_mov_b32_e32 v176, v70
	v_mul_f32_e32 v83, v179, v179
	v_mul_f32_e32 v96, v134, v134
	v_mul_f32_e32 v97, v135, v135
	s_waitcnt vmcnt(3)
	v_pk_fma_f32 v[22:23], v[84:85], v[22:23], v[118:119]
	v_pk_fma_f32 v[20:21], v[74:75], v[20:21], v[116:117]
	s_waitcnt vmcnt(2)
	v_pk_fma_f32 v[26:27], v[88:89], v[26:27], v[68:69]
	v_pk_fma_f32 v[24:25], v[86:87], v[24:25], v[66:67]
	v_cvt_pk_bf16_f32 v20, v20, v21
	v_cvt_pk_bf16_f32 v21, v22, v23
	s_waitcnt vmcnt(1)
	v_pk_fma_f32 v[30:31], v[92:93], v[30:31], v[122:123]
	v_cvt_pk_bf16_f32 v22, v24, v25
	v_cvt_pk_bf16_f32 v23, v26, v27
	v_pk_fma_f32 v[28:29], v[90:91], v[28:29], v[120:121]
	s_waitcnt vmcnt(0)
	v_pk_fma_f32 v[34:35], v[72:73], v[34:35], v[126:127]
	v_pk_fma_f32 v[32:33], v[94:95], v[32:33], v[124:125]
	global_store_dwordx4 v[76:77], v[20:23], off offset:-1024
	v_mov_b32_e32 v67, v177
	v_mul_f32_e32 v66, v175, v175
	v_cvt_pk_bf16_f32 v20, v28, v29
	v_cvt_pk_bf16_f32 v21, v30, v31
	v_cvt_pk_bf16_f32 v22, v32, v33
	v_cvt_pk_bf16_f32 v23, v34, v35
	global_store_dwordx4 v[76:77], v[20:23], off
	global_load_dwordx4 v[20:23], v[56:57], off
	s_nop 0
	global_load_dwordx4 v[24:27], v[56:57], off offset:16
	global_load_dwordx4 v[28:31], v[56:57], off offset:2048
	global_load_dwordx4 v[32:35], v[56:57], off offset:2064
	v_pk_fma_f32 v[74:75], v[128:129], v[128:129], v[148:149] op_sel_hi:[1,1,0]
	v_mul_f32_e32 v68, v133, v133
	v_pk_fma_f32 v[76:77], v[172:173], v[172:173], v[156:157]
	v_pk_fma_f32 v[84:85], v[174:175], v[174:175], v[66:67] op_sel_hi:[1,1,0]
	v_mov_b32_e32 v66, v74
	v_pk_fma_f32 v[68:69], v[132:133], v[132:133], v[68:69] op_sel_hi:[1,1,0]
	v_pk_add_f32 v[70:71], v[70:71], v[74:75]
	v_pk_add_f32 v[74:75], v[76:77], v[76:77] op_sel:[0,1] op_sel_hi:[1,0]
	v_pk_mul_f32 v[66:67], v[176:177], v[66:67]
	v_mov_b32_e32 v85, v96
	v_mov_b32_e32 v69, v97
	v_mov_b32_e32 v75, v83
	v_mov_b32_e32 v71, v67
	v_pk_add_f32 v[68:69], v[84:85], v[68:69]
	v_pk_add_f32 v[66:67], v[70:71], v[74:75]
	v_mov_b32_e32 v72, v172
	v_pk_add_f32 v[66:67], v[66:67], v[68:69]
	v_mov_b32_e32 v73, v130
	v_add_f32_e32 v66, v66, v67
	v_mov_b32_e32 v130, v173
	v_mov_b32_e32 v178, v177
	v_add_f32_dpp v66, v66, v66 quad_perm:[1,0,3,2] row_mask:0xf bank_mask:0xf bound_ctrl:1
	s_nop 1
	v_add_f32_dpp v66, v66, v66 quad_perm:[2,3,0,1] row_mask:0xf bank_mask:0xf bound_ctrl:1
	s_nop 1
	v_add_f32_dpp v66, v66, v66 row_half_mirror row_mask:0xf bank_mask:0xf bound_ctrl:1
	s_nop 1
	v_add_f32_dpp v66, v66, v66 row_mirror row_mask:0xf bank_mask:0xf bound_ctrl:1
	s_nop 0
	v_readlane_b32 s26, v66, 16
	v_readlane_b32 s27, v66, 48
	v_readlane_b32 s0, v66, 0
	v_readlane_b32 s1, v66, 32
	v_mov_b32_e32 v66, s26
	v_mov_b32_e32 v67, s27
	v_pk_add_f32 v[66:67], s[0:1], v[66:67]
	s_nop 0
	v_add_f32_e32 v66, v66, v67
	v_fmamk_f32 v66, v66, 0x3a800000, v82
	v_rsq_f32_e32 v66, v66
	s_nop 0
	v_pk_mul_f32 v[68:69], v[66:67], v[168:169] op_sel_hi:[0,1]
	v_pk_mul_f32 v[70:71], v[66:67], v[128:129] op_sel_hi:[0,1]
	v_pk_mul_f32 v[72:73], v[66:67], v[72:73] op_sel_hi:[0,1]
	v_pk_mul_f32 v[74:75], v[66:67], v[130:131] op_sel_hi:[0,1]
	v_pk_mul_f32 v[76:77], v[66:67], v[174:175] op_sel_hi:[0,1]
	v_pk_mul_f32 v[84:85], v[66:67], v[132:133] op_sel_hi:[0,1]
	v_pk_mul_f32 v[86:87], v[66:67], v[178:179] op_sel_hi:[0,1]
	v_pk_mul_f32 v[66:67], v[66:67], v[134:135] op_sel_hi:[0,1]
	s_waitcnt vmcnt(3)
	v_pk_fma_f32 v[22:23], v[70:71], v[22:23], v[54:55]
	v_pk_fma_f32 v[20:21], v[68:69], v[20:21], v[52:53]
	s_waitcnt vmcnt(2)
	v_pk_fma_f32 v[26:27], v[74:75], v[26:27], v[50:51]
	v_pk_fma_f32 v[24:25], v[72:73], v[24:25], v[48:49]
	v_cvt_pk_bf16_f32 v20, v20, v21
	v_cvt_pk_bf16_f32 v21, v22, v23
	s_waitcnt vmcnt(1)
	v_pk_fma_f32 v[30:31], v[84:85], v[30:31], v[46:47]
	v_cvt_pk_bf16_f32 v22, v24, v25
	v_cvt_pk_bf16_f32 v23, v26, v27
	v_pk_fma_f32 v[28:29], v[76:77], v[28:29], v[44:45]
	s_waitcnt vmcnt(0)
	v_pk_fma_f32 v[34:35], v[66:67], v[34:35], v[42:43]
	v_pk_fma_f32 v[32:33], v[86:87], v[32:33], v[40:41]
	global_store_dwordx4 v[78:79], v[20:23], off offset:-1024
	v_lshlrev_b32_e32 v43, 16, v18
	v_mul_f32_e32 v42, v37, v37
	v_cvt_pk_bf16_f32 v20, v28, v29
	v_cvt_pk_bf16_f32 v21, v30, v31
	v_cvt_pk_bf16_f32 v22, v32, v33
	v_cvt_pk_bf16_f32 v23, v34, v35
	global_store_dwordx4 v[78:79], v[20:23], off
	global_load_dwordx4 v[20:23], v[56:57], off
	s_nop 0
	global_load_dwordx4 v[24:27], v[56:57], off offset:16
	global_load_dwordx4 v[28:31], v[56:57], off offset:2048
	global_load_dwordx4 v[32:35], v[56:57], off offset:2064
	v_pk_mul_f32 v[46:47], v[38:39], v[38:39]
	v_mul_f32_e32 v48, v63, v63
	v_mov_b32_e32 v49, v43
	v_lshlrev_b32_e32 v40, 16, v16
	v_and_b32_e32 v41, 0xffff0000, v16
	v_lshlrev_b32_e32 v16, 16, v17
	v_and_b32_e32 v17, 0xffff0000, v17
	v_mov_b32_e32 v54, v64
	v_mov_b32_e32 v55, v38
	v_mov_b32_e32 v38, v65
	v_pk_fma_f32 v[66:67], v[36:37], v[36:37], v[42:43] op_sel_hi:[1,1,0]
	v_pk_fma_f32 v[46:47], v[64:65], v[64:65], v[46:47]
	v_pk_fma_f32 v[64:65], v[62:63], v[62:63], v[48:49] op_sel_hi:[1,1,0]
	v_and_b32_e32 v45, 0xffff0000, v18
	v_lshlrev_b32_e32 v18, 16, v19
	v_and_b32_e32 v19, 0xffff0000, v19
	v_mul_f32_e32 v50, v41, v41
	v_mul_f32_e32 v52, v17, v17
	v_mov_b32_e32 v42, v64
	v_mov_b32_e32 v48, v66
	v_mul_f32_e32 v68, v45, v45
	v_mul_f32_e32 v69, v18, v18
	v_mul_f32_e32 v70, v19, v19
	v_mov_b32_e32 v44, v43
	v_pk_fma_f32 v[50:51], v[40:41], v[40:41], v[50:51] op_sel_hi:[1,1,0]
	v_pk_fma_f32 v[52:53], v[16:17], v[16:17], v[52:53] op_sel_hi:[1,1,0]
	v_pk_add_f32 v[64:65], v[64:65], v[66:67]
	v_pk_add_f32 v[46:47], v[46:47], v[46:47] op_sel:[0,1] op_sel_hi:[1,0]
	v_pk_mul_f32 v[42:43], v[42:43], v[48:49]
	v_mov_b32_e32 v51, v69
	v_mov_b32_e32 v53, v70
	v_mov_b32_e32 v47, v68
	v_mov_b32_e32 v65, v43
	v_pk_add_f32 v[48:49], v[50:51], v[52:53]
	v_pk_add_f32 v[42:43], v[64:65], v[46:47]
	s_nop 0
	v_pk_add_f32 v[42:43], v[42:43], v[48:49]
	s_nop 0
	v_add_f32_e32 v42, v42, v43
	s_nop 1
	v_add_f32_dpp v42, v42, v42 quad_perm:[1,0,3,2] row_mask:0xf bank_mask:0xf bound_ctrl:1
	s_nop 1
	v_add_f32_dpp v42, v42, v42 quad_perm:[2,3,0,1] row_mask:0xf bank_mask:0xf bound_ctrl:1
	s_nop 1
	v_add_f32_dpp v42, v42, v42 row_half_mirror row_mask:0xf bank_mask:0xf bound_ctrl:1
	s_nop 1
	v_add_f32_dpp v42, v42, v42 row_mirror row_mask:0xf bank_mask:0xf bound_ctrl:1
	s_nop 0
	v_readlane_b32 s26, v42, 16
	v_readlane_b32 s27, v42, 48
	v_readlane_b32 s0, v42, 0
	v_readlane_b32 s1, v42, 32
	v_mov_b32_e32 v42, s26
	v_mov_b32_e32 v43, s27
	v_pk_add_f32 v[42:43], s[0:1], v[42:43]
	s_nop 0
	v_add_f32_e32 v42, v42, v43
	v_fmamk_f32 v42, v42, 0x3a800000, v82
	v_rsq_f32_e32 v42, v42
	s_nop 0
	v_pk_mul_f32 v[46:47], v[42:43], v[62:63] op_sel_hi:[0,1]
	v_pk_mul_f32 v[36:37], v[42:43], v[36:37] op_sel_hi:[0,1]
	v_pk_mul_f32 v[48:49], v[42:43], v[54:55] op_sel_hi:[0,1]
	v_pk_mul_f32 v[38:39], v[42:43], v[38:39] op_sel_hi:[0,1]
	v_pk_mul_f32 v[16:17], v[42:43], v[16:17] op_sel_hi:[0,1]
	v_pk_mul_f32 v[44:45], v[42:43], v[44:45] op_sel_hi:[0,1]
	v_pk_mul_f32 v[18:19], v[42:43], v[18:19] op_sel_hi:[0,1]
	v_pk_mul_f32 v[40:41], v[42:43], v[40:41] op_sel_hi:[0,1]
	s_waitcnt vmcnt(3)
	v_pk_fma_f32 v[14:15], v[36:37], v[22:23], v[14:15]
	v_pk_fma_f32 v[12:13], v[46:47], v[20:21], v[12:13]
	s_waitcnt vmcnt(2)
	v_pk_fma_f32 v[6:7], v[38:39], v[26:27], v[6:7]
	v_pk_fma_f32 v[4:5], v[48:49], v[24:25], v[4:5]
	s_waitcnt vmcnt(1)
	v_pk_fma_f32 v[10:11], v[16:17], v[30:31], v[10:11]
	s_waitcnt vmcnt(0)
	v_pk_fma_f32 v[16:17], v[18:19], v[34:35], v[2:3]
	v_pk_fma_f32 v[18:19], v[44:45], v[32:33], v[0:1]
	v_cvt_pk_bf16_f32 v0, v12, v13
	v_cvt_pk_bf16_f32 v1, v14, v15
	v_cvt_pk_bf16_f32 v2, v4, v5
	v_cvt_pk_bf16_f32 v3, v6, v7
	v_pk_fma_f32 v[8:9], v[40:41], v[28:29], v[8:9]
	global_store_dwordx4 v[80:81], v[0:3], off offset:-1024
	s_nop 1
	v_cvt_pk_bf16_f32 v0, v8, v9
	v_cvt_pk_bf16_f32 v1, v10, v11
	v_cvt_pk_bf16_f32 v2, v18, v19
	v_cvt_pk_bf16_f32 v3, v16, v17
	global_store_dwordx4 v[80:81], v[0:3], off
	s_cbranch_scc0 .LBB0_1031

.LBB0_1159:
	v_lshl_add_u64 v[62:63], s[92:93], 0, v[58:59]
	v_add_co_u32_e32 v0, vcc, 0x7900000, v62
	v_lshl_add_u64 v[4:5], s[92:93], 0, v[60:61]
	s_nop 0
	v_addc_co_u32_e32 v1, vcc, 0, v63, vcc
	v_add_co_u32_e32 v2, vcc, 0x17b00000, v4
	global_load_dwordx4 v[80:83], v[0:1], off nt
	s_nop 0
	v_addc_co_u32_e32 v3, vcc, 0, v5, vcc
	global_load_dwordx2 v[92:93], v[2:3], off nt
	v_add_co_u32_e32 v6, vcc, 0x2fe00000, v62
	s_waitcnt vmcnt(1)
	v_lshlrev_b32_e32 v78, 16, v80
	v_addc_co_u32_e32 v7, vcc, 0, v63, vcc
	global_load_dwordx4 v[88:91], v[6:7], off nt
	global_load_dwordx4 v[48:51], v[0:1], off offset:1024 nt
	global_load_dwordx2 v[76:77], v[2:3], off offset:512 nt
	global_load_dwordx4 v[52:55], v[6:7], off offset:1024 nt
	v_add_co_u32_e32 v0, vcc, 0x7980000, v62
	s_waitcnt vmcnt(4)
	v_cvt_f32_ubyte1_e32 v95, v92
	v_addc_co_u32_e32 v1, vcc, 0, v63, vcc
	global_load_dwordx4 v[44:47], v[0:1], off nt
	global_load_dwordx4 v[32:35], v[0:1], off offset:1024 nt
	v_add_co_u32_e32 v0, vcc, 0x17b40000, v4
	v_cvt_f32_ubyte0_e32 v94, v92
	s_nop 0
	v_addc_co_u32_e32 v1, vcc, 0, v5, vcc
	global_load_dwordx2 v[74:75], v[0:1], off nt
	global_load_dwordx2 v[72:73], v[0:1], off offset:512 nt
	v_add_co_u32_e32 v0, vcc, 0x2fe80000, v62
	v_cvt_f32_ubyte3_e32 v97, v92
	s_nop 0
	v_addc_co_u32_e32 v1, vcc, 0, v63, vcc
	global_load_dwordx4 v[40:43], v[0:1], off nt
	global_load_dwordx4 v[36:39], v[0:1], off offset:1024 nt
	v_add_co_u32_e32 v0, vcc, 0x7a00000, v62
	v_cvt_f32_ubyte2_e32 v96, v92
	s_nop 0
	v_addc_co_u32_e32 v1, vcc, 0, v63, vcc
	global_load_dwordx4 v[28:31], v[0:1], off nt
	global_load_dwordx4 v[16:19], v[0:1], off offset:1024 nt
	v_add_co_u32_e32 v0, vcc, 0x17b80000, v4
	v_pk_mul_f32 v[96:97], v[96:97], s[12:13] op_sel_hi:[1,0]
	s_nop 0
	v_addc_co_u32_e32 v1, vcc, 0, v5, vcc
	global_load_dwordx2 v[70:71], v[0:1], off nt
	global_load_dwordx2 v[68:69], v[0:1], off offset:512 nt
	v_add_co_u32_e32 v0, vcc, 0x2ff00000, v62
	v_pk_mul_f32 v[94:95], v[94:95], s[12:13] op_sel_hi:[1,0]
	s_nop 0
	v_addc_co_u32_e32 v1, vcc, 0, v63, vcc
	global_load_dwordx4 v[24:27], v[0:1], off nt
	global_load_dwordx4 v[20:23], v[0:1], off offset:1024 nt
	v_add_co_u32_e32 v0, vcc, 0x7a80000, v62
	v_and_b32_e32 v79, 0xffff0000, v80
	s_nop 0
	v_addc_co_u32_e32 v1, vcc, 0, v63, vcc
	v_add_co_u32_e32 v4, vcc, 0x17bc0000, v4
	global_load_dwordx4 v[12:15], v[0:1], off nt
	s_nop 0
	global_load_dwordx4 v[0:3], v[0:1], off offset:1024 nt
	v_addc_co_u32_e32 v5, vcc, 0, v5, vcc
	global_load_dwordx2 v[66:67], v[4:5], off nt
	global_load_dwordx2 v[64:65], v[4:5], off offset:512 nt
	v_add_co_u32_e32 v4, vcc, 0x2ff80000, v62
	v_lshlrev_b32_e32 v80, 16, v81
	s_nop 0
	v_addc_co_u32_e32 v5, vcc, 0, v63, vcc
	global_load_dwordx4 v[8:11], v[4:5], off nt
	s_nop 0
	global_load_dwordx4 v[4:7], v[4:5], off offset:1024 nt
	v_and_b32_e32 v81, 0xffff0000, v81
	v_lshlrev_b32_e32 v110, 16, v82
	v_and_b32_e32 v111, 0xffff0000, v82
	v_lshlrev_b32_e32 v82, 16, v83
	v_and_b32_e32 v83, 0xffff0000, v83
	s_waitcnt vmcnt(21)
	v_lshlrev_b32_e32 v98, 16, v88
	v_and_b32_e32 v99, 0xffff0000, v88
	v_lshlrev_b32_e32 v88, 16, v89
	v_and_b32_e32 v89, 0xffff0000, v89
	v_pk_mul_f32 v[104:105], v[94:95], v[98:99]
	v_pk_mul_f32 v[106:107], v[96:97], v[88:89]
	v_pk_mul_f32 v[94:95], v[104:105], v[104:105]
	v_pk_mul_f32 v[88:89], v[106:107], v[106:107]
	v_lshlrev_b32_e32 v102, 16, v90
	v_pk_mov_b32 v[96:97], v[94:95], v[88:89] op_sel:[1,0]
	v_mov_b32_e32 v95, v89
	v_pk_add_f32 v[108:109], v[96:97], v[94:95]
	v_cvt_f32_ubyte3_e32 v95, v93
	v_cvt_f32_ubyte2_e32 v94, v93
	v_cvt_f32_ubyte1_e32 v89, v93
	v_cvt_f32_ubyte0_e32 v88, v93
	v_pk_mul_f32 v[100:101], v[94:95], s[12:13] op_sel_hi:[1,0]
	global_load_dwordx4 v[92:95], v[56:57], off offset:16
	global_load_dwordx4 v[96:99], v[56:57], off
	v_pk_mul_f32 v[88:89], v[88:89], s[12:13] op_sel_hi:[1,0]
	v_and_b32_e32 v103, 0xffff0000, v90
	v_lshlrev_b32_e32 v90, 16, v91
	v_and_b32_e32 v91, 0xffff0000, v91
	v_pk_mul_f32 v[112:113], v[88:89], v[102:103]
	v_pk_mul_f32 v[114:115], v[100:101], v[90:91]
	v_pk_mul_f32 v[90:91], v[112:113], v[112:113]
	v_pk_mul_f32 v[88:89], v[114:115], v[114:115]
	s_waitcnt vmcnt(22)
	v_lshlrev_b32_e32 v118, 16, v48
	v_pk_mov_b32 v[100:101], v[90:91], v[88:89] op_sel:[1,0]
	v_mov_b32_e32 v91, v89
	v_pk_add_f32 v[116:117], v[100:101], v[90:91]
	global_load_dwordx4 v[88:91], v[56:57], off offset:2064
	global_load_dwordx4 v[100:103], v[56:57], off offset:2048
	v_and_b32_e32 v119, 0xffff0000, v48
	v_lshlrev_b32_e32 v120, 16, v49
	v_and_b32_e32 v121, 0xffff0000, v49
	s_waitcnt vmcnt(23)
	v_cvt_f32_ubyte3_e32 v49, v76
	v_cvt_f32_ubyte2_e32 v48, v76
	v_pk_mul_f32 v[48:49], v[48:49], s[12:13] op_sel_hi:[1,0]
	s_waitcnt vmcnt(22)
	v_lshlrev_b32_e32 v124, 16, v52
	v_and_b32_e32 v125, 0xffff0000, v52
	v_lshlrev_b32_e32 v52, 16, v53
	v_and_b32_e32 v53, 0xffff0000, v53
	v_pk_mul_f32 v[126:127], v[48:49], v[52:53]
	v_cvt_f32_ubyte1_e32 v53, v77
	v_cvt_f32_ubyte0_e32 v52, v77
	v_cvt_f32_ubyte1_e32 v123, v76
	v_cvt_f32_ubyte0_e32 v122, v76
	v_cvt_f32_ubyte3_e32 v49, v77
	v_cvt_f32_ubyte2_e32 v48, v77
	v_pk_mul_f32 v[52:53], v[52:53], s[12:13] op_sel_hi:[1,0]
	v_lshlrev_b32_e32 v76, 16, v54
	v_and_b32_e32 v77, 0xffff0000, v54
	v_pk_mul_f32 v[48:49], v[48:49], s[12:13] op_sel_hi:[1,0]
	v_lshlrev_b32_e32 v54, 16, v55
	v_and_b32_e32 v55, 0xffff0000, v55
	v_pk_mul_f32 v[130:131], v[52:53], v[76:77]
	v_pk_mul_f32 v[128:129], v[48:49], v[54:55]
	v_mul_f32_e32 v52, v130, v130
	v_pk_add_f32 v[48:49], v[108:109], v[108:109] op_sel:[0,1] op_sel_hi:[1,0]
	v_pk_mul_f32 v[122:123], v[122:123], s[12:13] op_sel_hi:[1,0]
	v_mul_f32_e32 v54, v131, v131
	v_mov_b32_e32 v49, v52
	v_pk_add_f32 v[52:53], v[116:117], v[116:117] op_sel:[0,1] op_sel_hi:[1,0]
	v_pk_mul_f32 v[122:123], v[122:123], v[124:125]
	v_mov_b32_e32 v53, v54
	v_pk_add_f32 v[48:49], v[48:49], v[52:53]
	v_mul_f32_e32 v52, v123, v123
	v_mul_f32_e32 v55, v128, v128
	v_pk_fma_f32 v[52:53], v[122:123], v[122:123], v[52:53] op_sel_hi:[1,1,0]
	v_mul_f32_e32 v54, v127, v127
	v_mul_f32_e32 v76, v129, v129
	v_mov_b32_e32 v53, v55
	v_pk_fma_f32 v[54:55], v[126:127], v[126:127], v[54:55] op_sel_hi:[1,1,0]
	v_lshlrev_b32_e32 v124, 16, v50
	v_mov_b32_e32 v55, v76
	v_pk_add_f32 v[52:53], v[52:53], v[54:55]
	v_and_b32_e32 v125, 0xffff0000, v50
	v_pk_add_f32 v[48:49], v[48:49], v[52:53]
	v_lshlrev_b32_e32 v116, 16, v51
	v_add_f32_e32 v48, v48, v49
	v_and_b32_e32 v117, 0xffff0000, v51
	s_nop 0
	v_add_f32_dpp v48, v48, v48 quad_perm:[1,0,3,2] row_mask:0xf bank_mask:0xf bound_ctrl:1
	s_nop 1
	v_add_f32_dpp v48, v48, v48 quad_perm:[2,3,0,1] row_mask:0xf bank_mask:0xf bound_ctrl:1
	s_nop 1
	v_add_f32_dpp v48, v48, v48 row_half_mirror row_mask:0xf bank_mask:0xf bound_ctrl:1
	s_nop 1
	v_add_f32_dpp v48, v48, v48 row_mirror row_mask:0xf bank_mask:0xf bound_ctrl:1
	s_nop 0
	v_readlane_b32 s4, v48, 16
	v_readlane_b32 s5, v48, 48
	v_readlane_b32 s0, v48, 0
	v_readlane_b32 s1, v48, 32
	v_mov_b32_e32 v48, s4
	v_mov_b32_e32 v49, s5
	v_pk_add_f32 v[48:49], s[0:1], v[48:49]
	s_nop 0
	v_add_f32_e32 v48, v48, v49
	v_fmamk_f32 v48, v48, 0x3a800000, v84
	v_rsq_f32_e32 v108, v48
	s_nop 0
	v_pk_mul_f32 v[50:51], v[108:109], v[104:105] op_sel_hi:[0,1]
	v_pk_mul_f32 v[48:49], v[108:109], v[106:107] op_sel_hi:[0,1]
	s_waitcnt vmcnt(2)
	v_pk_fma_f32 v[48:49], v[48:49], v[98:99], v[80:81]
	v_pk_fma_f32 v[50:51], v[50:51], v[96:97], v[78:79]
	v_mul_f32_e32 v53, v49, v49
	v_mul_f32_e32 v52, v51, v51
	v_fmac_f32_e32 v52, v50, v50
	v_fmac_f32_e32 v53, v48, v48
	v_add_f32_e32 v76, v52, v53
	v_pk_mul_f32 v[54:55], v[108:109], v[112:113] op_sel_hi:[0,1]
	v_pk_mul_f32 v[52:53], v[108:109], v[114:115] op_sel_hi:[0,1]
	v_pk_fma_f32 v[52:53], v[52:53], v[94:95], v[82:83]
	v_pk_fma_f32 v[54:55], v[54:55], v[92:93], v[110:111]
	v_mul_f32_e32 v78, v53, v53
	v_mul_f32_e32 v77, v55, v55
	v_fmac_f32_e32 v77, v54, v54
	v_fmac_f32_e32 v78, v52, v52
	v_add_f32_e32 v77, v77, v78
	v_add_f32_e32 v80, v76, v77
	v_pk_mul_f32 v[78:79], v[108:109], v[122:123] op_sel_hi:[0,1]
	v_pk_mul_f32 v[76:77], v[108:109], v[126:127] op_sel_hi:[0,1]
	s_waitcnt vmcnt(0)
	v_pk_fma_f32 v[76:77], v[76:77], v[102:103], v[120:121]
	v_pk_fma_f32 v[78:79], v[78:79], v[100:101], v[118:119]
	v_mul_f32_e32 v82, v77, v77
	v_mul_f32_e32 v81, v79, v79
	v_fmac_f32_e32 v81, v78, v78
	v_fmac_f32_e32 v82, v76, v76
	v_add_f32_e32 v81, v81, v82
	v_add_f32_e32 v87, v80, v81
	v_pk_mul_f32 v[82:83], v[108:109], v[130:131] op_sel_hi:[0,1]
	v_pk_mul_f32 v[80:81], v[108:109], v[128:129] op_sel_hi:[0,1]
	v_pk_fma_f32 v[80:81], v[80:81], v[90:91], v[116:117]
	v_pk_fma_f32 v[82:83], v[82:83], v[88:89], v[124:125]
	v_mul_f32_e32 v89, v81, v81
	v_mul_f32_e32 v88, v83, v83
	v_fmac_f32_e32 v88, v82, v82
	v_fmac_f32_e32 v89, v80, v80
	v_add_f32_e32 v88, v88, v89
	v_add_f32_e32 v87, v87, v88
	s_nop 1
	v_add_f32_dpp v87, v87, v87 quad_perm:[1,0,3,2] row_mask:0xf bank_mask:0xf bound_ctrl:1
	s_nop 1
	v_add_f32_dpp v87, v87, v87 quad_perm:[2,3,0,1] row_mask:0xf bank_mask:0xf bound_ctrl:1
	s_nop 1
	v_add_f32_dpp v87, v87, v87 row_half_mirror row_mask:0xf bank_mask:0xf bound_ctrl:1
	s_nop 1
	v_add_f32_dpp v87, v87, v87 row_mirror row_mask:0xf bank_mask:0xf bound_ctrl:1
	s_nop 0
	v_readlane_b32 s1, v87, 16
	v_readlane_b32 s0, v87, 0
	s_nop 0
	v_mov_b32_e32 v88, s1
	v_readlane_b32 s1, v87, 48
	v_add_f32_e32 v88, s0, v88
	v_readlane_b32 s0, v87, 32
	v_mov_b32_e32 v87, s1
	s_nop 0
	v_add_f32_e32 v87, s0, v87
	v_add_f32_e32 v87, v88, v87
	v_fmamk_f32 v87, v87, 0x3a800000, v84
	s_and_saveexec_b64 s[4:5], s[6:7]
	s_cbranch_execz .LBB0_1161
	v_mul_f32_e32 v88, 0x4f800000, v87
	v_cmp_gt_f32_e32 vcc, s9, v87
	s_add_u32 s22, s92, s10
	s_addc_u32 s23, s93, s11
	v_cndmask_b32_e32 v88, v87, v88, vcc
	v_sqrt_f32_e32 v89, v88
	s_nop 0
	v_add_u32_e32 v90, -1, v89
	v_fma_f32 v91, -v90, v89, v88
	v_cmp_ge_f32_e64 s[0:1], 0, v91
	v_add_u32_e32 v91, 1, v89
	s_nop 0
	v_cndmask_b32_e64 v90, v89, v90, s[0:1]
	v_fma_f32 v89, -v91, v89, v88
	v_cmp_lt_f32_e64 s[0:1], 0, v89
	s_nop 1
	v_cndmask_b32_e64 v89, v90, v91, s[0:1]
	v_mul_f32_e32 v90, 0x37800000, v89
	v_cndmask_b32_e32 v89, v89, v90, vcc
	v_cmp_class_f32_e32 vcc, v88, v85
	s_nop 1
	v_cndmask_b32_e32 v88, v89, v88, vcc
	global_store_dword v86, v88, s[22:23]

.LBB0_1614:
	v_lshl_add_u64 v[16:17], s[92:93], 0, v[26:27]
	v_add_co_u32_e32 v18, vcc, 0x7900000, v16
	s_add_u32 s12, s92, s8
	s_nop 0
	v_addc_co_u32_e32 v19, vcc, 0, v17, vcc
	s_addc_u32 s13, s93, s9
	v_add_co_u32_e32 v20, vcc, 0x37f00000, v16
	global_load_dwordx4 v[0:3], v[24:25], off offset:16
	global_load_dwordx4 v[4:7], v[24:25], off
	global_load_dwordx4 v[8:11], v[24:25], off offset:2064
	global_load_dwordx4 v[12:15], v[24:25], off offset:2048
	global_load_dword v94, v37, s[12:13]
	global_load_dwordx4 v[38:41], v[18:19], off nt
	global_load_dwordx4 v[42:45], v[18:19], off offset:1024 nt
	v_addc_co_u32_e32 v21, vcc, 0, v17, vcc
	v_add_co_u32_e32 v18, vcc, 0x7980000, v16
	global_load_dwordx4 v[46:49], v[20:21], off nt
	global_load_dwordx4 v[50:53], v[20:21], off offset:1024 nt
	v_addc_co_u32_e32 v19, vcc, 0, v17, vcc
	global_load_dwordx4 v[54:57], v[18:19], off nt
	global_load_dwordx4 v[58:61], v[18:19], off offset:1024 nt
	v_add_co_u32_e32 v20, vcc, 0x37f80000, v16
	v_add_co_u32_e64 v34, s[0:1], s4, v16
	s_nop 0
	v_addc_co_u32_e32 v21, vcc, 0, v17, vcc
	v_add_co_u32_e32 v18, vcc, 0x7a00000, v16
	v_addc_co_u32_e64 v35, s[0:1], 0, v17, s[0:1]
	s_nop 0
	v_addc_co_u32_e32 v19, vcc, 0, v17, vcc
	global_load_dwordx4 v[62:65], v[20:21], off nt
	global_load_dwordx4 v[66:69], v[20:21], off offset:1024 nt
	v_add_co_u32_e32 v20, vcc, 0x38000000, v16
	v_add_co_u32_e64 v32, s[0:1], s5, v16
	s_nop 0
	v_addc_co_u32_e32 v21, vcc, 0, v17, vcc
	v_addc_co_u32_e64 v33, s[0:1], 0, v17, s[0:1]
	global_load_dwordx4 v[70:73], v[18:19], off nt
	global_load_dwordx4 v[74:77], v[18:19], off offset:1024 nt
	v_add_co_u32_e32 v18, vcc, 0x7a80000, v16
	v_add_co_u32_e64 v30, s[0:1], s7, v16
	s_nop 0
	v_addc_co_u32_e32 v19, vcc, 0, v17, vcc
	v_addc_co_u32_e64 v31, s[0:1], 0, v17, s[0:1]
	v_add_co_u32_e32 v96, vcc, 0x38080000, v16
	v_add_co_u32_e64 v28, s[0:1], s14, v16
	s_nop 0
	v_addc_co_u32_e32 v97, vcc, 0, v17, vcc
	v_addc_co_u32_e64 v29, s[0:1], 0, v17, s[0:1]
	global_load_dwordx4 v[78:81], v[20:21], off nt
	global_load_dwordx4 v[82:85], v[20:21], off offset:1024 nt
	global_load_dwordx4 v[86:89], v[18:19], off nt
	global_load_dwordx4 v[90:93], v[18:19], off offset:1024 nt
	s_nop 0
	global_load_dwordx4 v[20:23], v[96:97], off nt
	global_load_dwordx4 v[16:19], v[96:97], off offset:1024 nt
	s_addk_i32 s6, 0xfc00
	s_add_u32 s8, s8, 0xfffff000
	s_addc_u32 s9, s9, -1
	v_lshl_add_u64 v[26:27], v[26:27], 0, s[10:11]
	s_cmp_lt_i32 s6, s73
	s_waitcnt vmcnt(15)
	v_lshlrev_b32_e32 v96, 16, v38
	v_and_b32_e32 v97, 0xffff0000, v38
	v_lshlrev_b32_e32 v38, 16, v39
	v_and_b32_e32 v39, 0xffff0000, v39
	v_lshlrev_b32_e32 v99, 16, v41
	v_lshlrev_b32_e32 v98, 16, v40
	v_and_b32_e32 v41, 0xffff0000, v41
	v_and_b32_e32 v40, 0xffff0000, v40
	s_waitcnt vmcnt(14)
	v_lshlrev_b32_e32 v95, 16, v44
	v_lshlrev_b32_e32 v100, 16, v42
	v_and_b32_e32 v101, 0xffff0000, v42
	v_lshlrev_b32_e32 v42, 16, v43
	v_and_b32_e32 v43, 0xffff0000, v43
	v_mul_f32_e32 v104, v39, v39
	v_pk_mul_f32 v[106:107], v[40:41], v[40:41]
	v_mul_f32_e32 v108, v97, v97
	v_mov_b32_e32 v105, v95
	v_and_b32_e32 v103, 0xffff0000, v44
	v_lshlrev_b32_e32 v44, 16, v45
	v_and_b32_e32 v45, 0xffff0000, v45
	v_mul_f32_e32 v110, v101, v101
	v_mul_f32_e32 v112, v43, v43
	s_waitcnt vmcnt(13)
	v_lshlrev_b32_e32 v114, 16, v46
	v_and_b32_e32 v115, 0xffff0000, v46
	v_lshlrev_b32_e32 v46, 16, v47
	v_and_b32_e32 v47, 0xffff0000, v47
	v_lshlrev_b32_e32 v116, 16, v48
	v_and_b32_e32 v117, 0xffff0000, v48
	v_lshlrev_b32_e32 v48, 16, v49
	v_and_b32_e32 v49, 0xffff0000, v49
	v_mov_b32_e32 v118, v98
	v_mov_b32_e32 v119, v40
	v_mov_b32_e32 v40, v99
	s_waitcnt vmcnt(12)
	v_lshlrev_b32_e32 v120, 16, v50
	v_and_b32_e32 v121, 0xffff0000, v50
	v_lshlrev_b32_e32 v50, 16, v51
	v_and_b32_e32 v51, 0xffff0000, v51
	v_lshlrev_b32_e32 v122, 16, v52
	v_and_b32_e32 v123, 0xffff0000, v52
	v_lshlrev_b32_e32 v52, 16, v53
	v_and_b32_e32 v53, 0xffff0000, v53
	v_pk_fma_f32 v[124:125], v[38:39], v[38:39], v[104:105] op_sel_hi:[1,1,0]
	v_pk_fma_f32 v[98:99], v[98:99], v[98:99], v[106:107]
	v_pk_fma_f32 v[106:107], v[96:97], v[96:97], v[108:109] op_sel_hi:[1,1,0]
	v_mul_f32_e32 v130, v44, v44
	v_mul_f32_e32 v132, v45, v45
	v_pk_fma_f32 v[108:109], v[100:101], v[100:101], v[110:111] op_sel_hi:[1,1,0]
	v_pk_fma_f32 v[110:111], v[42:43], v[42:43], v[112:113] op_sel_hi:[1,1,0]
	v_pk_mul_f32 v[112:113], v[94:95], v[114:115] op_sel_hi:[0,1]
	v_pk_mul_f32 v[46:47], v[94:95], v[46:47] op_sel_hi:[0,1]
	v_pk_mul_f32 v[114:115], v[94:95], v[116:117] op_sel_hi:[0,1]
	v_pk_mul_f32 v[48:49], v[94:95], v[48:49] op_sel_hi:[0,1]
	v_pk_mul_f32 v[116:117], v[94:95], v[120:121] op_sel_hi:[0,1]
	v_pk_mul_f32 v[50:51], v[94:95], v[50:51] op_sel_hi:[0,1]
	v_pk_mul_f32 v[120:121], v[94:95], v[122:123] op_sel_hi:[0,1]
	v_pk_mul_f32 v[52:53], v[94:95], v[52:53] op_sel_hi:[0,1]
	s_waitcnt vmcnt(11)
	v_lshlrev_b32_e32 v122, 16, v54
	v_and_b32_e32 v123, 0xffff0000, v54
	v_lshlrev_b32_e32 v54, 16, v55
	v_and_b32_e32 v55, 0xffff0000, v55
	v_lshlrev_b32_e32 v127, 16, v57
	v_lshlrev_b32_e32 v126, 16, v56
	v_and_b32_e32 v57, 0xffff0000, v57
	v_and_b32_e32 v56, 0xffff0000, v56
	s_waitcnt vmcnt(10)
	v_lshlrev_b32_e32 v131, 16, v60
	v_mov_b32_e32 v94, v106
	v_mov_b32_e32 v104, v124
	v_mul_f32_e32 v137, v103, v103
	v_mov_b32_e32 v102, v95
	v_pk_add_f32 v[106:107], v[106:107], v[124:125]
	v_pk_add_f32 v[98:99], v[98:99], v[98:99] op_sel:[0,1] op_sel_hi:[1,0]
	v_mov_b32_e32 v109, v130
	v_mov_b32_e32 v111, v132
	v_mul_f32_e32 v124, v55, v55
	v_pk_mul_f32 v[134:135], v[56:57], v[56:57]
	v_mul_f32_e32 v130, v123, v123
	v_mov_b32_e32 v125, v131
	v_pk_mul_f32 v[94:95], v[94:95], v[104:105]
	v_lshlrev_b32_e32 v128, 16, v58
	v_and_b32_e32 v129, 0xffff0000, v58
	v_lshlrev_b32_e32 v58, 16, v59
	v_and_b32_e32 v59, 0xffff0000, v59
	v_mov_b32_e32 v144, v126
	v_mov_b32_e32 v145, v56
	v_mov_b32_e32 v56, v127
	v_mov_b32_e32 v99, v137
	v_pk_add_f32 v[104:105], v[108:109], v[110:111]
	v_pk_fma_f32 v[108:109], v[54:55], v[54:55], v[124:125] op_sel_hi:[1,1,0]
	v_pk_fma_f32 v[110:111], v[126:127], v[126:127], v[134:135]
	v_pk_fma_f32 v[126:127], v[122:123], v[122:123], v[130:131] op_sel_hi:[1,1,0]
	v_mov_b32_e32 v107, v95
	v_and_b32_e32 v133, 0xffff0000, v60
	v_lshlrev_b32_e32 v60, 16, v61
	v_and_b32_e32 v61, 0xffff0000, v61
	v_mul_f32_e32 v136, v129, v129
	v_mul_f32_e32 v138, v59, v59
	v_mov_b32_e32 v130, v126
	v_mov_b32_e32 v124, v108
	v_pk_add_f32 v[98:99], v[106:107], v[98:99]
	v_mul_f32_e32 v159, v133, v133
	v_mul_f32_e32 v154, v60, v60
	v_mul_f32_e32 v156, v61, v61
	v_pk_fma_f32 v[134:135], v[128:129], v[128:129], v[136:137] op_sel_hi:[1,1,0]
	v_pk_fma_f32 v[136:137], v[58:59], v[58:59], v[138:139] op_sel_hi:[1,1,0]
	v_pk_add_f32 v[94:95], v[126:127], v[108:109]
	v_pk_add_f32 v[108:109], v[110:111], v[110:111] op_sel:[0,1] op_sel_hi:[1,0]
	v_pk_mul_f32 v[106:107], v[130:131], v[124:125]
	v_pk_add_f32 v[98:99], v[98:99], v[104:105]
	v_mov_b32_e32 v135, v154
	v_mov_b32_e32 v137, v156
	v_mov_b32_e32 v109, v159
	v_mov_b32_e32 v95, v107
	v_add_f32_e32 v98, v98, v99
	v_pk_add_f32 v[124:125], v[134:135], v[136:137]
	v_pk_add_f32 v[94:95], v[94:95], v[108:109]
	v_add_f32_dpp v98, v98, v98 quad_perm:[1,0,3,2] row_mask:0xf bank_mask:0xf bound_ctrl:1
	v_pk_add_f32 v[94:95], v[94:95], v[124:125]
	s_waitcnt vmcnt(9)
	v_lshlrev_b32_e32 v140, 16, v62
	v_add_f32_dpp v98, v98, v98 quad_perm:[2,3,0,1] row_mask:0xf bank_mask:0xf bound_ctrl:1
	v_add_f32_e32 v94, v94, v95
	v_and_b32_e32 v141, 0xffff0000, v62
	v_add_f32_dpp v95, v98, v98 row_half_mirror row_mask:0xf bank_mask:0xf bound_ctrl:1
	v_add_f32_dpp v94, v94, v94 quad_perm:[1,0,3,2] row_mask:0xf bank_mask:0xf bound_ctrl:1
	v_lshlrev_b32_e32 v62, 16, v63
	v_add_f32_dpp v95, v95, v95 row_mirror row_mask:0xf bank_mask:0xf bound_ctrl:1
	v_add_f32_dpp v94, v94, v94 quad_perm:[2,3,0,1] row_mask:0xf bank_mask:0xf bound_ctrl:1
	v_readlane_b32 s15, v95, 16
	v_readlane_b32 s16, v95, 48
	v_readlane_b32 s0, v95, 0
	v_readlane_b32 s1, v95, 32
	v_add_f32_dpp v98, v94, v94 row_half_mirror row_mask:0xf bank_mask:0xf bound_ctrl:1
	v_mov_b32_e32 v94, s15
	v_mov_b32_e32 v95, s16
	v_add_f32_dpp v98, v98, v98 row_mirror row_mask:0xf bank_mask:0xf bound_ctrl:1
	v_pk_add_f32 v[94:95], s[0:1], v[94:95]
	v_readlane_b32 s0, v98, 0
	v_readlane_b32 s15, v98, 16
	v_readlane_b32 s1, v98, 32
	v_readlane_b32 s16, v98, 48
	v_add_f32_e32 v98, v94, v95
	v_fmamk_f32 v98, v98, 0x3a800000, v36
	v_rsq_f32_e32 v98, v98
	v_mov_b32_e32 v94, s15
	v_mov_b32_e32 v95, s16
	v_pk_add_f32 v[94:95], s[0:1], v[94:95]
	v_pk_mul_f32 v[38:39], v[98:99], v[38:39] op_sel_hi:[0,1]
	v_pk_mul_f32 v[108:109], v[98:99], v[118:119] op_sel_hi:[0,1]
	v_pk_mul_f32 v[40:41], v[98:99], v[40:41] op_sel_hi:[0,1]
	v_pk_mul_f32 v[96:97], v[98:99], v[96:97] op_sel_hi:[0,1]
	v_pk_fma_f32 v[6:7], v[38:39], v[6:7], v[46:47]
	v_pk_fma_f32 v[38:39], v[40:41], v[2:3], v[48:49]
	v_pk_fma_f32 v[2:3], v[108:109], v[0:1], v[114:115]
	v_pk_mul_f32 v[100:101], v[98:99], v[100:101] op_sel_hi:[0,1]
	v_pk_mul_f32 v[42:43], v[98:99], v[42:43] op_sel_hi:[0,1]
	v_pk_mul_f32 v[102:103], v[98:99], v[102:103] op_sel_hi:[0,1]
	v_pk_mul_f32 v[44:45], v[98:99], v[44:45] op_sel_hi:[0,1]
	v_pk_fma_f32 v[4:5], v[96:97], v[4:5], v[112:113]
	v_pk_fma_f32 v[14:15], v[42:43], v[14:15], v[50:51]
	v_cvt_pk_bf16_f32 v0, v4, v5
	v_cvt_pk_bf16_f32 v1, v6, v7
	v_cvt_pk_bf16_f32 v2, v2, v3
	v_cvt_pk_bf16_f32 v3, v38, v39
	v_pk_fma_f32 v[12:13], v[100:101], v[12:13], v[116:117]
	v_pk_fma_f32 v[10:11], v[44:45], v[10:11], v[52:53]
	v_pk_fma_f32 v[8:9], v[102:103], v[8:9], v[120:121]
	global_store_dwordx4 v[34:35], v[0:3], off
	v_and_b32_e32 v63, 0xffff0000, v63
	v_lshlrev_b32_e32 v142, 16, v64
	v_cvt_pk_bf16_f32 v0, v12, v13
	v_cvt_pk_bf16_f32 v1, v14, v15
	v_cvt_pk_bf16_f32 v2, v8, v9
	v_cvt_pk_bf16_f32 v3, v10, v11
	global_store_dwordx4 v[34:35], v[0:3], off offset:1024
	global_load_dword v34, v37, s[12:13] offset:1024
	s_nop 0
	global_load_dwordx4 v[0:3], v[24:25], off
	global_load_dwordx4 v[4:7], v[24:25], off offset:16
	global_load_dwordx4 v[8:11], v[24:25], off offset:2048
	global_load_dwordx4 v[12:15], v[24:25], off offset:2064
	v_add_f32_e32 v35, v94, v95
	v_fmamk_f32 v35, v35, 0x3a800000, v36
	v_rsq_f32_e32 v38, v35
	v_and_b32_e32 v143, 0xffff0000, v64
	v_lshlrev_b32_e32 v64, 16, v65
	v_and_b32_e32 v65, 0xffff0000, v65
	v_mov_b32_e32 v132, v131
	v_pk_mul_f32 v[40:41], v[38:39], v[122:123] op_sel_hi:[0,1]
	v_pk_mul_f32 v[42:43], v[38:39], v[54:55] op_sel_hi:[0,1]
	v_pk_mul_f32 v[46:47], v[38:39], v[56:57] op_sel_hi:[0,1]
	s_waitcnt vmcnt(15)
	v_lshlrev_b32_e32 v146, 16, v66
	v_and_b32_e32 v147, 0xffff0000, v66
	v_lshlrev_b32_e32 v66, 16, v67
	v_and_b32_e32 v67, 0xffff0000, v67
	v_lshlrev_b32_e32 v148, 16, v68
	v_and_b32_e32 v149, 0xffff0000, v68
	v_lshlrev_b32_e32 v68, 16, v69
	v_and_b32_e32 v69, 0xffff0000, v69
	v_pk_mul_f32 v[44:45], v[38:39], v[144:145] op_sel_hi:[0,1]
	v_pk_mul_f32 v[48:49], v[38:39], v[128:129] op_sel_hi:[0,1]
	v_pk_mul_f32 v[50:51], v[38:39], v[58:59] op_sel_hi:[0,1]
	v_pk_mul_f32 v[52:53], v[38:39], v[132:133] op_sel_hi:[0,1]
	v_pk_mul_f32 v[38:39], v[38:39], v[60:61] op_sel_hi:[0,1]
	s_waitcnt vmcnt(14)
	v_lshlrev_b32_e32 v138, 16, v70
	v_and_b32_e32 v139, 0xffff0000, v70
	v_lshlrev_b32_e32 v70, 16, v71
	v_and_b32_e32 v71, 0xffff0000, v71
	s_waitcnt vmcnt(13)
	v_lshlrev_b32_e32 v155, 16, v76
	v_lshlrev_b32_e32 v151, 16, v73
	v_lshlrev_b32_e32 v150, 16, v72
	v_and_b32_e32 v73, 0xffff0000, v73
	v_and_b32_e32 v72, 0xffff0000, v72
	v_mul_f32_e32 v110, v71, v71
	v_mul_f32_e32 v154, v139, v139
	v_mov_b32_e32 v111, v155
	v_lshlrev_b32_e32 v152, 16, v74
	v_and_b32_e32 v153, 0xffff0000, v74
	v_lshlrev_b32_e32 v74, 16, v75
	v_and_b32_e32 v75, 0xffff0000, v75
	v_pk_mul_f32 v[126:127], v[72:73], v[72:73]
	v_pk_fma_f32 v[130:131], v[70:71], v[70:71], v[110:111] op_sel_hi:[1,1,0]
	v_pk_fma_f32 v[134:135], v[138:139], v[138:139], v[154:155] op_sel_hi:[1,1,0]
	v_and_b32_e32 v157, 0xffff0000, v76
	v_lshlrev_b32_e32 v76, 16, v77
	v_and_b32_e32 v77, 0xffff0000, v77
	v_mul_f32_e32 v158, v153, v153
	v_mul_f32_e32 v160, v75, v75
	v_pk_fma_f32 v[126:127], v[150:151], v[150:151], v[126:127]
	v_mov_b32_e32 v154, v134
	v_mov_b32_e32 v110, v130
	v_mul_f32_e32 v176, v157, v157
	v_mul_f32_e32 v174, v76, v76
	v_mul_f32_e32 v178, v77, v77
	v_mov_b32_e32 v166, v150
	v_mov_b32_e32 v167, v72
	v_mov_b32_e32 v72, v151
	v_pk_fma_f32 v[136:137], v[152:153], v[152:153], v[158:159] op_sel_hi:[1,1,0]
	v_pk_fma_f32 v[150:151], v[74:75], v[74:75], v[160:161] op_sel_hi:[1,1,0]
	v_pk_add_f32 v[104:105], v[134:135], v[130:131]
	v_pk_add_f32 v[106:107], v[126:127], v[126:127] op_sel:[0,1] op_sel_hi:[1,0]
	v_mov_b32_e32 v137, v174
	v_mov_b32_e32 v151, v178
	v_mov_b32_e32 v107, v176
	s_waitcnt vmcnt(12)
	v_lshlrev_b32_e32 v162, 16, v78
	v_and_b32_e32 v163, 0xffff0000, v78
	v_lshlrev_b32_e32 v78, 16, v79
	v_and_b32_e32 v79, 0xffff0000, v79
	v_lshlrev_b32_e32 v164, 16, v80
	v_and_b32_e32 v165, 0xffff0000, v80
	v_lshlrev_b32_e32 v80, 16, v81
	v_and_b32_e32 v81, 0xffff0000, v81
	s_waitcnt vmcnt(11)
	v_lshlrev_b32_e32 v168, 16, v82
	v_and_b32_e32 v169, 0xffff0000, v82
	v_lshlrev_b32_e32 v82, 16, v83
	v_and_b32_e32 v83, 0xffff0000, v83
	s_waitcnt vmcnt(4)
	v_pk_mul_f32 v[54:55], v[34:35], v[140:141] op_sel_hi:[0,1]
	v_pk_mul_f32 v[56:57], v[34:35], v[62:63] op_sel_hi:[0,1]
	v_pk_mul_f32 v[58:59], v[34:35], v[142:143] op_sel_hi:[0,1]
	v_pk_mul_f32 v[60:61], v[34:35], v[64:65] op_sel_hi:[0,1]
	s_waitcnt vmcnt(3)
	v_pk_fma_f32 v[2:3], v[42:43], v[2:3], v[56:57]
	v_pk_fma_f32 v[0:1], v[40:41], v[0:1], v[54:55]
	v_pk_mul_f32 v[62:63], v[34:35], v[146:147] op_sel_hi:[0,1]
	v_pk_mul_f32 v[64:65], v[34:35], v[66:67] op_sel_hi:[0,1]
	v_pk_mul_f32 v[66:67], v[34:35], v[148:149] op_sel_hi:[0,1]
	v_pk_mul_f32 v[34:35], v[34:35], v[68:69] op_sel_hi:[0,1]
	s_waitcnt vmcnt(2)
	v_pk_fma_f32 v[6:7], v[46:47], v[6:7], v[60:61]
	v_pk_fma_f32 v[4:5], v[44:45], v[4:5], v[58:59]
	v_cvt_pk_bf16_f32 v0, v0, v1
	v_cvt_pk_bf16_f32 v1, v2, v3
	s_waitcnt vmcnt(1)
	v_pk_fma_f32 v[10:11], v[50:51], v[10:11], v[64:65]
	v_cvt_pk_bf16_f32 v2, v4, v5
	v_cvt_pk_bf16_f32 v3, v6, v7
	v_pk_fma_f32 v[8:9], v[48:49], v[8:9], v[62:63]
	s_waitcnt vmcnt(0)
	v_pk_fma_f32 v[14:15], v[38:39], v[14:15], v[34:35]
	v_pk_fma_f32 v[12:13], v[52:53], v[12:13], v[66:67]
	global_store_dwordx4 v[32:33], v[0:3], off
	v_pk_mul_f32 v[38:39], v[154:155], v[110:111]
	v_pk_add_f32 v[40:41], v[136:137], v[150:151]
	v_cvt_pk_bf16_f32 v0, v8, v9
	v_cvt_pk_bf16_f32 v1, v10, v11
	v_cvt_pk_bf16_f32 v2, v12, v13
	v_cvt_pk_bf16_f32 v3, v14, v15
	global_store_dwordx4 v[32:33], v[0:3], off offset:1024
	global_load_dword v32, v37, s[12:13] offset:2048
	s_nop 0
	global_load_dwordx4 v[0:3], v[24:25], off
	global_load_dwordx4 v[4:7], v[24:25], off offset:16
	global_load_dwordx4 v[8:11], v[24:25], off offset:2048
	global_load_dwordx4 v[12:15], v[24:25], off offset:2064
	v_mov_b32_e32 v105, v39
	v_pk_add_f32 v[38:39], v[104:105], v[106:107]
	v_lshlrev_b32_e32 v170, 16, v84
	v_pk_add_f32 v[38:39], v[38:39], v[40:41]
	v_and_b32_e32 v171, 0xffff0000, v84
	v_add_f32_e32 v33, v38, v39
	v_lshlrev_b32_e32 v84, 16, v85
	v_and_b32_e32 v85, 0xffff0000, v85
	v_add_f32_dpp v33, v33, v33 quad_perm:[1,0,3,2] row_mask:0xf bank_mask:0xf bound_ctrl:1
	v_mov_b32_e32 v156, v155
	v_lshlrev_b32_e32 v158, 16, v86
	v_add_f32_dpp v33, v33, v33 quad_perm:[2,3,0,1] row_mask:0xf bank_mask:0xf bound_ctrl:1
	v_and_b32_e32 v159, 0xffff0000, v86
	v_lshlrev_b32_e32 v86, 16, v87
	v_add_f32_dpp v33, v33, v33 row_half_mirror row_mask:0xf bank_mask:0xf bound_ctrl:1
	v_and_b32_e32 v87, 0xffff0000, v87
	v_lshlrev_b32_e32 v175, 16, v92
	v_add_f32_dpp v33, v33, v33 row_mirror row_mask:0xf bank_mask:0xf bound_ctrl:1
	v_and_b32_e32 v177, 0xffff0000, v92
	v_readlane_b32 s15, v33, 16
	v_readlane_b32 s16, v33, 48
	v_readlane_b32 s0, v33, 0
	v_readlane_b32 s1, v33, 32
	v_mov_b32_e32 v38, s15
	v_mov_b32_e32 v39, s16
	v_pk_add_f32 v[38:39], s[0:1], v[38:39]
	v_lshlrev_b32_e32 v161, 16, v89
	v_add_f32_e32 v33, v38, v39
	v_fmamk_f32 v33, v33, 0x3a800000, v36
	v_rsq_f32_e32 v38, v33
	v_lshlrev_b32_e32 v160, 16, v88
	v_and_b32_e32 v89, 0xffff0000, v89
	v_and_b32_e32 v88, 0xffff0000, v88
	v_pk_mul_f32 v[40:41], v[38:39], v[138:139] op_sel_hi:[0,1]
	v_pk_mul_f32 v[42:43], v[38:39], v[70:71] op_sel_hi:[0,1]
	v_pk_mul_f32 v[44:45], v[38:39], v[166:167] op_sel_hi:[0,1]
	v_pk_mul_f32 v[46:47], v[38:39], v[72:73] op_sel_hi:[0,1]
	v_pk_mul_f32 v[48:49], v[38:39], v[152:153] op_sel_hi:[0,1]
	v_pk_mul_f32 v[50:51], v[38:39], v[74:75] op_sel_hi:[0,1]
	v_pk_mul_f32 v[52:53], v[38:39], v[156:157] op_sel_hi:[0,1]
	v_pk_mul_f32 v[38:39], v[38:39], v[76:77] op_sel_hi:[0,1]
	v_and_b32_e32 v173, 0xffff0000, v90
	v_mul_f32_e32 v126, v87, v87
	v_mul_f32_e32 v135, v177, v177
	v_mul_f32_e32 v134, v159, v159
	v_mov_b32_e32 v127, v175
	v_lshlrev_b32_e32 v172, 16, v90
	v_lshlrev_b32_e32 v90, 16, v91
	v_and_b32_e32 v91, 0xffff0000, v91
	v_lshlrev_b32_e32 v92, 16, v93
	v_pk_mul_f32 v[130:131], v[88:89], v[88:89]
	v_mul_f32_e32 v174, v173, v173
	v_and_b32_e32 v93, 0xffff0000, v93
	v_mul_f32_e32 v179, v92, v92
	v_mul_f32_e32 v178, v91, v91
	v_mul_f32_e32 v182, v93, v93
	v_lshlrev_b32_e32 v180, 16, v20
	v_and_b32_e32 v181, 0xffff0000, v20
	v_lshlrev_b32_e32 v20, 16, v21
	v_and_b32_e32 v21, 0xffff0000, v21
	v_lshlrev_b32_e32 v34, 16, v22
	v_and_b32_e32 v35, 0xffff0000, v22
	v_lshlrev_b32_e32 v22, 16, v23
	v_and_b32_e32 v23, 0xffff0000, v23
	v_mov_b32_e32 v176, v175
	s_waitcnt vmcnt(4)
	v_pk_mul_f32 v[54:55], v[32:33], v[162:163] op_sel_hi:[0,1]
	v_pk_mul_f32 v[56:57], v[32:33], v[78:79] op_sel_hi:[0,1]
	v_pk_mul_f32 v[58:59], v[32:33], v[164:165] op_sel_hi:[0,1]
	v_pk_mul_f32 v[60:61], v[32:33], v[80:81] op_sel_hi:[0,1]
	s_waitcnt vmcnt(3)
	v_pk_fma_f32 v[2:3], v[42:43], v[2:3], v[56:57]
	v_pk_fma_f32 v[0:1], v[40:41], v[0:1], v[54:55]
	v_pk_mul_f32 v[62:63], v[32:33], v[168:169] op_sel_hi:[0,1]
	v_pk_mul_f32 v[64:65], v[32:33], v[82:83] op_sel_hi:[0,1]
	v_pk_mul_f32 v[66:67], v[32:33], v[170:171] op_sel_hi:[0,1]
	v_pk_mul_f32 v[32:33], v[32:33], v[84:85] op_sel_hi:[0,1]
	s_waitcnt vmcnt(2)
	v_pk_fma_f32 v[6:7], v[46:47], v[6:7], v[60:61]
	v_pk_fma_f32 v[4:5], v[44:45], v[4:5], v[58:59]
	v_cvt_pk_bf16_f32 v0, v0, v1
	v_cvt_pk_bf16_f32 v1, v2, v3
	s_waitcnt vmcnt(1)
	v_pk_fma_f32 v[10:11], v[50:51], v[10:11], v[64:65]
	v_cvt_pk_bf16_f32 v2, v4, v5
	v_cvt_pk_bf16_f32 v3, v6, v7
	v_pk_fma_f32 v[8:9], v[48:49], v[8:9], v[62:63]
	s_waitcnt vmcnt(0)
	v_pk_fma_f32 v[14:15], v[38:39], v[14:15], v[32:33]
	v_pk_fma_f32 v[12:13], v[52:53], v[12:13], v[66:67]
	global_store_dwordx4 v[30:31], v[0:3], off
	v_pk_fma_f32 v[42:43], v[86:87], v[86:87], v[126:127] op_sel_hi:[1,1,0]
	v_pk_fma_f32 v[46:47], v[158:159], v[158:159], v[134:135] op_sel_hi:[1,1,0]
	v_cvt_pk_bf16_f32 v0, v8, v9
	v_cvt_pk_bf16_f32 v1, v10, v11
	v_cvt_pk_bf16_f32 v2, v12, v13
	v_cvt_pk_bf16_f32 v3, v14, v15
	global_store_dwordx4 v[30:31], v[0:3], off offset:1024
	global_load_dword v30, v37, s[12:13] offset:3072
	s_nop 0
	global_load_dwordx4 v[0:3], v[24:25], off
	global_load_dwordx4 v[4:7], v[24:25], off offset:16
	global_load_dwordx4 v[8:11], v[24:25], off offset:2048
	global_load_dwordx4 v[12:15], v[24:25], off offset:2064
	v_pk_fma_f32 v[44:45], v[160:161], v[160:161], v[130:131]
	v_pk_fma_f32 v[48:49], v[172:173], v[172:173], v[174:175] op_sel_hi:[1,1,0]
	v_mov_b32_e32 v174, v46
	v_mov_b32_e32 v126, v42
	v_pk_fma_f32 v[50:51], v[90:91], v[90:91], v[178:179] op_sel_hi:[1,1,0]
	v_pk_add_f32 v[42:43], v[46:47], v[42:43]
	v_pk_add_f32 v[44:45], v[44:45], v[44:45] op_sel:[0,1] op_sel_hi:[1,0]
	v_pk_mul_f32 v[46:47], v[174:175], v[126:127]
	v_mov_b32_e32 v49, v179
	v_mov_b32_e32 v51, v182
	v_mov_b32_e32 v45, v135
	v_mov_b32_e32 v43, v47
	v_pk_add_f32 v[48:49], v[48:49], v[50:51]
	v_pk_add_f32 v[42:43], v[42:43], v[44:45]
	v_mov_b32_e32 v32, v160
	v_pk_add_f32 v[42:43], v[42:43], v[48:49]
	v_mov_b32_e32 v33, v88
	v_add_f32_e32 v31, v42, v43
	v_mov_b32_e32 v88, v161
	v_lshlrev_b32_e32 v38, 16, v16
	v_add_f32_dpp v31, v31, v31 quad_perm:[1,0,3,2] row_mask:0xf bank_mask:0xf bound_ctrl:1
	v_and_b32_e32 v39, 0xffff0000, v16
	v_lshlrev_b32_e32 v16, 16, v17
	v_add_f32_dpp v31, v31, v31 quad_perm:[2,3,0,1] row_mask:0xf bank_mask:0xf bound_ctrl:1
	v_and_b32_e32 v17, 0xffff0000, v17
	v_lshlrev_b32_e32 v40, 16, v18
	v_add_f32_dpp v31, v31, v31 row_half_mirror row_mask:0xf bank_mask:0xf bound_ctrl:1
	v_and_b32_e32 v41, 0xffff0000, v18
	v_lshlrev_b32_e32 v18, 16, v19
	v_add_f32_dpp v31, v31, v31 row_mirror row_mask:0xf bank_mask:0xf bound_ctrl:1
	v_and_b32_e32 v19, 0xffff0000, v19
	v_readlane_b32 s12, v31, 16
	v_readlane_b32 s13, v31, 48
	v_readlane_b32 s0, v31, 0
	v_readlane_b32 s1, v31, 32
	v_mov_b32_e32 v42, s12
	v_mov_b32_e32 v43, s13
	v_pk_add_f32 v[42:43], s[0:1], v[42:43]
	s_nop 0
	v_add_f32_e32 v31, v42, v43
	v_fmamk_f32 v31, v31, 0x3a800000, v36
	v_rsq_f32_e32 v42, v31
	s_waitcnt vmcnt(4)
	v_pk_mul_f32 v[56:57], v[30:31], v[180:181] op_sel_hi:[0,1]
	v_pk_mul_f32 v[44:45], v[42:43], v[158:159] op_sel_hi:[0,1]
	v_pk_mul_f32 v[46:47], v[42:43], v[86:87] op_sel_hi:[0,1]
	v_pk_mul_f32 v[20:21], v[30:31], v[20:21] op_sel_hi:[0,1]
	v_pk_mul_f32 v[32:33], v[42:43], v[32:33] op_sel_hi:[0,1]
	v_pk_mul_f32 v[48:49], v[42:43], v[88:89] op_sel_hi:[0,1]
	v_pk_mul_f32 v[34:35], v[30:31], v[34:35] op_sel_hi:[0,1]
	v_pk_mul_f32 v[22:23], v[30:31], v[22:23] op_sel_hi:[0,1]
	s_waitcnt vmcnt(3)
	v_pk_fma_f32 v[2:3], v[46:47], v[2:3], v[20:21]
	v_pk_fma_f32 v[0:1], v[44:45], v[0:1], v[56:57]
	v_pk_mul_f32 v[50:51], v[42:43], v[172:173] op_sel_hi:[0,1]
	v_pk_mul_f32 v[52:53], v[42:43], v[90:91] op_sel_hi:[0,1]
	v_pk_mul_f32 v[54:55], v[42:43], v[176:177] op_sel_hi:[0,1]
	v_pk_mul_f32 v[42:43], v[42:43], v[92:93] op_sel_hi:[0,1]
	v_pk_mul_f32 v[38:39], v[30:31], v[38:39] op_sel_hi:[0,1]
	v_pk_mul_f32 v[16:17], v[30:31], v[16:17] op_sel_hi:[0,1]
	v_pk_mul_f32 v[40:41], v[30:31], v[40:41] op_sel_hi:[0,1]
	v_pk_mul_f32 v[18:19], v[30:31], v[18:19] op_sel_hi:[0,1]
	s_waitcnt vmcnt(2)
	v_pk_fma_f32 v[6:7], v[48:49], v[6:7], v[22:23]
	v_pk_fma_f32 v[4:5], v[32:33], v[4:5], v[34:35]
	v_cvt_pk_bf16_f32 v0, v0, v1
	v_cvt_pk_bf16_f32 v1, v2, v3
	s_waitcnt vmcnt(1)
	v_pk_fma_f32 v[10:11], v[52:53], v[10:11], v[16:17]
	v_cvt_pk_bf16_f32 v2, v4, v5
	v_cvt_pk_bf16_f32 v3, v6, v7
	v_pk_fma_f32 v[8:9], v[50:51], v[8:9], v[38:39]
	s_waitcnt vmcnt(0)
	v_pk_fma_f32 v[14:15], v[42:43], v[14:15], v[18:19]
	v_pk_fma_f32 v[12:13], v[54:55], v[12:13], v[40:41]
	global_store_dwordx4 v[28:29], v[0:3], off
	s_nop 1
	v_cvt_pk_bf16_f32 v0, v8, v9
	v_cvt_pk_bf16_f32 v1, v10, v11
	v_cvt_pk_bf16_f32 v2, v12, v13
	v_cvt_pk_bf16_f32 v3, v14, v15
	global_store_dwordx4 v[28:29], v[0:3], off offset:1024
	s_cbranch_scc0 .LBB0_1614

.LBB0_1761:
	v_lshl_add_u64 v[8:9], s[92:93], 0, v[60:61]
	v_add_co_u32_e32 v2, vcc, 0xfa00000, v8
	v_lshl_add_u64 v[10:11], s[92:93], 0, v[66:67]
	v_lshl_add_u64 v[0:1], s[92:93], 0, v[62:63]
	v_addc_co_u32_e32 v3, vcc, 0, v9, vcc
	global_load_dwordx4 v[86:89], v[52:53], off
	global_load_dwordx4 v[80:83], v[0:1], off nt
	global_load_dwordx4 v[90:93], v[0:1], off offset:1024 nt
	v_add_co_u32_e32 v0, vcc, 0x1fc00000, v10
	global_load_dwordx4 v[94:97], v[2:3], off nt
	global_load_dwordx4 v[48:51], v[2:3], off offset:1024 nt
	v_addc_co_u32_e32 v1, vcc, 0, v11, vcc
	global_load_dwordx2 v[98:99], v[0:1], off nt
	global_load_dwordx2 v[100:101], v[0:1], off offset:512 nt
	v_add_co_u32_e32 v2, vcc, 0xfa80000, v8
	s_addk_i32 s0, 0xfc00
	s_nop 0
	v_addc_co_u32_e32 v3, vcc, 0, v9, vcc
	v_add_co_u32_e32 v0, vcc, 0x1fc40000, v10
	global_load_dwordx4 v[36:39], v[2:3], off nt
	global_load_dwordx4 v[32:35], v[2:3], off offset:1024 nt
	v_addc_co_u32_e32 v1, vcc, 0, v11, vcc
	v_add_co_u32_e32 v2, vcc, 0x17b80000, v8
	global_load_dwordx2 v[78:79], v[0:1], off nt
	global_load_dwordx2 v[76:77], v[0:1], off offset:512 nt
	v_addc_co_u32_e32 v3, vcc, 0, v9, vcc
	v_add_co_u32_e32 v0, vcc, 0xfb00000, v8
	global_load_dwordx4 v[44:47], v[2:3], off nt
	global_load_dwordx4 v[40:43], v[2:3], off offset:1024 nt
	v_addc_co_u32_e32 v1, vcc, 0, v9, vcc
	v_add_co_u32_e32 v2, vcc, 0x1fc80000, v10
	global_load_dwordx4 v[20:23], v[0:1], off nt
	global_load_dwordx4 v[16:19], v[0:1], off offset:1024 nt
	v_addc_co_u32_e32 v3, vcc, 0, v11, vcc
	v_add_co_u32_e32 v0, vcc, 0x17c00000, v8
	global_load_dwordx2 v[74:75], v[2:3], off nt
	global_load_dwordx2 v[72:73], v[2:3], off offset:512 nt
	v_addc_co_u32_e32 v1, vcc, 0, v9, vcc
	v_add_co_u32_e32 v12, vcc, 0xfb80000, v8
	global_load_dwordx4 v[28:31], v[0:1], off nt
	global_load_dwordx4 v[24:27], v[0:1], off offset:1024 nt
	v_addc_co_u32_e32 v13, vcc, 0, v9, vcc
	v_add_co_u32_e32 v10, vcc, 0x1fcc0000, v10
	global_load_dwordx4 v[4:7], v[12:13], off nt
	global_load_dwordx4 v[0:3], v[12:13], off offset:1024 nt
	v_addc_co_u32_e32 v11, vcc, 0, v11, vcc
	v_add_co_u32_e32 v102, vcc, 0x17c80000, v8
	global_load_dwordx2 v[70:71], v[10:11], off nt
	global_load_dwordx2 v[68:69], v[10:11], off offset:512 nt
	v_addc_co_u32_e32 v103, vcc, 0, v9, vcc
	global_load_dwordx4 v[12:15], v[102:103], off nt
	global_load_dwordx4 v[8:11], v[102:103], off offset:1024 nt
	v_lshl_add_u64 v[62:63], v[62:63], 0, s[4:5]
	v_lshl_add_u64 v[60:61], v[60:61], 0, s[4:5]
	v_lshl_add_u64 v[66:67], v[66:67], 0, s[8:9]
	s_cmp_lt_i32 s0, s73
	s_waitcnt vmcnt(23)
	v_lshlrev_b32_e32 v102, 16, v80
	v_and_b32_e32 v103, 0xffff0000, v80
	v_lshlrev_b32_e32 v80, 16, v81
	v_and_b32_e32 v81, 0xffff0000, v81
	v_lshlrev_b32_e32 v104, 16, v82
	v_and_b32_e32 v105, 0xffff0000, v82
	s_waitcnt vmcnt(19)
	v_cvt_f32_ubyte1_e32 v113, v98
	v_cvt_f32_ubyte0_e32 v112, v98
	v_cvt_f32_ubyte3_e32 v115, v98
	v_cvt_f32_ubyte2_e32 v114, v98
	v_cvt_f32_ubyte1_e32 v117, v99
	v_cvt_f32_ubyte0_e32 v116, v99
	v_cvt_f32_ubyte3_e32 v119, v99
	v_cvt_f32_ubyte2_e32 v118, v99
	v_lshlrev_b32_e32 v82, 16, v83
	v_and_b32_e32 v83, 0xffff0000, v83
	s_waitcnt vmcnt(18)
	v_cvt_f32_ubyte3_e32 v99, v100
	v_cvt_f32_ubyte2_e32 v98, v100
	v_cvt_f32_ubyte1_e32 v121, v100
	v_cvt_f32_ubyte0_e32 v120, v100
	v_cvt_f32_ubyte3_e32 v123, v101
	v_cvt_f32_ubyte2_e32 v122, v101
	v_cvt_f32_ubyte1_e32 v125, v101
	v_cvt_f32_ubyte0_e32 v124, v101
	v_pk_mul_f32 v[100:101], v[114:115], s[2:3] op_sel_hi:[1,0]
	v_pk_mul_f32 v[112:113], v[112:113], s[2:3] op_sel_hi:[1,0]
	v_pk_mul_f32 v[114:115], v[118:119], s[2:3] op_sel_hi:[1,0]
	v_pk_mul_f32 v[116:117], v[116:117], s[2:3] op_sel_hi:[1,0]
	v_lshlrev_b32_e32 v106, 16, v90
	v_and_b32_e32 v107, 0xffff0000, v90
	v_lshlrev_b32_e32 v90, 16, v91
	v_and_b32_e32 v91, 0xffff0000, v91
	v_lshlrev_b32_e32 v108, 16, v92
	v_and_b32_e32 v109, 0xffff0000, v92
	v_lshlrev_b32_e32 v92, 16, v93
	v_and_b32_e32 v93, 0xffff0000, v93
	v_pk_mul_f32 v[118:119], v[120:121], s[2:3] op_sel_hi:[1,0]
	v_pk_mul_f32 v[98:99], v[98:99], s[2:3] op_sel_hi:[1,0]
	v_pk_mul_f32 v[120:121], v[124:125], s[2:3] op_sel_hi:[1,0]
	v_pk_mul_f32 v[122:123], v[122:123], s[2:3] op_sel_hi:[1,0]
	v_pk_mul_f32 v[102:103], v[112:113], v[102:103]
	v_pk_mul_f32 v[100:101], v[100:101], v[80:81]
	v_pk_mul_f32 v[104:105], v[116:117], v[104:105]
	v_pk_mul_f32 v[112:113], v[114:115], v[82:83]
	v_pk_mul_f32 v[90:91], v[98:99], v[90:91]
	v_pk_mul_f32 v[98:99], v[118:119], v[106:107]
	v_pk_mul_f32 v[80:81], v[122:123], v[92:93]
	v_pk_mul_f32 v[82:83], v[120:121], v[108:109]
	v_pk_mul_f32 v[92:93], v[100:101], v[100:101]
	v_pk_mul_f32 v[106:107], v[102:103], v[102:103]
	v_pk_mul_f32 v[108:109], v[112:113], v[112:113]
	v_pk_mul_f32 v[114:115], v[104:105], v[104:105]
	v_pk_mov_b32 v[118:119], v[106:107], v[92:93] op_sel:[1,0]
	v_mov_b32_e32 v107, v93
	v_pk_mov_b32 v[92:93], v[114:115], v[108:109] op_sel:[1,0]
	v_mov_b32_e32 v115, v109
	v_mul_f32_e32 v84, v99, v99
	v_mul_f32_e32 v116, v91, v91
	v_pk_add_f32 v[106:107], v[118:119], v[106:107]
	v_pk_add_f32 v[92:93], v[92:93], v[114:115]
	v_mul_f32_e32 v120, v82, v82
	v_mul_f32_e32 v121, v83, v83
	v_mul_f32_e32 v122, v80, v80
	v_mul_f32_e32 v123, v81, v81
	v_pk_fma_f32 v[108:109], v[98:99], v[98:99], v[84:85] op_sel_hi:[1,1,0]
	v_pk_fma_f32 v[116:117], v[90:91], v[90:91], v[116:117] op_sel_hi:[1,1,0]
	v_pk_add_f32 v[106:107], v[106:107], v[106:107] op_sel:[0,1] op_sel_hi:[1,0]
	v_pk_add_f32 v[92:93], v[92:93], v[92:93] op_sel:[0,1] op_sel_hi:[1,0]
	v_mov_b32_e32 v109, v122
	v_mov_b32_e32 v117, v123
	v_mov_b32_e32 v107, v120
	v_mov_b32_e32 v93, v121
	v_pk_add_f32 v[108:109], v[108:109], v[116:117]
	v_pk_add_f32 v[92:93], v[106:107], v[92:93]
	v_lshlrev_b32_e32 v110, 16, v94
	v_pk_add_f32 v[92:93], v[92:93], v[108:109]
	v_and_b32_e32 v111, 0xffff0000, v94
	v_add_f32_e32 v84, v92, v93
	v_lshlrev_b32_e32 v94, 16, v95
	v_and_b32_e32 v95, 0xffff0000, v95
	v_add_f32_dpp v84, v84, v84 quad_perm:[1,0,3,2] row_mask:0xf bank_mask:0xf bound_ctrl:1
	s_waitcnt vmcnt(14)
	v_cvt_f32_ubyte1_e32 v107, v77
	v_cvt_f32_ubyte0_e32 v106, v77
	v_add_f32_dpp v84, v84, v84 quad_perm:[2,3,0,1] row_mask:0xf bank_mask:0xf bound_ctrl:1
	s_waitcnt vmcnt(13)
	v_lshlrev_b32_e32 v108, 16, v45
	v_and_b32_e32 v109, 0xffff0000, v45
	v_add_f32_dpp v84, v84, v84 row_half_mirror row_mask:0xf bank_mask:0xf bound_ctrl:1
	s_nop 1
	v_add_f32_dpp v84, v84, v84 row_mirror row_mask:0xf bank_mask:0xf bound_ctrl:1
	s_nop 0
	v_readlane_b32 s11, v84, 16
	v_readlane_b32 s14, v84, 48
	v_readlane_b32 s12, v84, 0
	v_readlane_b32 s13, v84, 32
	v_mov_b32_e32 v92, s11
	v_mov_b32_e32 v93, s14
	v_pk_add_f32 v[92:93], s[12:13], v[92:93]
	s_nop 0
	v_add_f32_e32 v84, v92, v93
	v_fmamk_f32 v84, v84, 0x3a800000, v85
	v_rsq_f32_e32 v84, v84
	s_nop 0
	v_pk_mul_f32 v[92:93], v[84:85], v[102:103] op_sel_hi:[0,1]
	v_pk_mul_f32 v[100:101], v[84:85], v[100:101] op_sel_hi:[0,1]
	v_pk_fma_f32 v[88:89], v[100:101], v[88:89], v[94:95]
	v_pk_fma_f32 v[86:87], v[92:93], v[86:87], v[110:111]
	global_store_dwordx4 v[64:65], v[86:89], off
	global_load_dwordx4 v[86:89], v[54:55], off
	v_lshlrev_b32_e32 v92, 16, v96
	v_and_b32_e32 v93, 0xffff0000, v96
	v_lshlrev_b32_e32 v94, 16, v97
	v_and_b32_e32 v95, 0xffff0000, v97
	v_pk_mul_f32 v[96:97], v[84:85], v[112:113] op_sel_hi:[0,1]
	v_pk_mul_f32 v[100:101], v[84:85], v[104:105] op_sel_hi:[0,1]
	v_pk_mul_f32 v[90:91], v[84:85], v[90:91] op_sel_hi:[0,1]
	v_cvt_f32_ubyte1_e32 v103, v76
	v_cvt_f32_ubyte0_e32 v102, v76
	v_cvt_f32_ubyte3_e32 v105, v77
	v_cvt_f32_ubyte2_e32 v104, v77
	v_lshlrev_b32_e32 v110, 16, v46
	v_and_b32_e32 v111, 0xffff0000, v46
	v_lshlrev_b32_e32 v112, 16, v47
	v_and_b32_e32 v113, 0xffff0000, v47
	v_pk_mul_f32 v[46:47], v[84:85], v[80:81] op_sel_hi:[0,1]
	s_waitcnt vmcnt(14)
	v_lshlrev_b32_e32 v80, 16, v40
	v_and_b32_e32 v81, 0xffff0000, v40
	v_lshlrev_b32_e32 v40, 16, v41
	v_and_b32_e32 v41, 0xffff0000, v41
	s_waitcnt vmcnt(0)
	v_pk_fma_f32 v[86:87], v[100:101], v[86:87], v[92:93]
	v_pk_fma_f32 v[88:89], v[96:97], v[88:89], v[94:95]
	global_store_dwordx4 v[64:65], v[86:89], off offset:16
	global_load_dwordx4 v[86:89], v[56:57], off
	v_lshlrev_b32_e32 v92, 16, v48
	v_and_b32_e32 v93, 0xffff0000, v48
	v_lshlrev_b32_e32 v48, 16, v49
	v_and_b32_e32 v49, 0xffff0000, v49
	v_pk_mul_f32 v[94:95], v[84:85], v[98:99] op_sel_hi:[0,1]
	v_cvt_f32_ubyte3_e32 v97, v78
	v_cvt_f32_ubyte2_e32 v96, v78
	v_cvt_f32_ubyte1_e32 v99, v79
	v_cvt_f32_ubyte0_e32 v98, v79
	v_cvt_f32_ubyte3_e32 v101, v79
	v_cvt_f32_ubyte2_e32 v100, v79
	v_cvt_f32_ubyte3_e32 v79, v76
	v_pk_mul_f32 v[100:101], v[100:101], s[2:3] op_sel_hi:[1,0]
	v_pk_mul_f32 v[98:99], v[98:99], s[2:3] op_sel_hi:[1,0]
	s_waitcnt vmcnt(0)
	v_pk_fma_f32 v[86:87], v[94:95], v[86:87], v[92:93]
	v_pk_fma_f32 v[88:89], v[90:91], v[88:89], v[48:49]
	global_store_dwordx4 v[64:65], v[86:89], off offset:2048
	global_load_dwordx4 v[86:89], v[58:59], off
	v_lshlrev_b32_e32 v90, 16, v50
	v_and_b32_e32 v91, 0xffff0000, v50
	v_lshlrev_b32_e32 v50, 16, v51
	v_and_b32_e32 v51, 0xffff0000, v51
	v_lshlrev_b32_e32 v92, 16, v36
	v_and_b32_e32 v93, 0xffff0000, v36
	v_lshlrev_b32_e32 v94, 16, v37
	v_and_b32_e32 v95, 0xffff0000, v37
	v_cvt_f32_ubyte1_e32 v37, v78
	v_cvt_f32_ubyte0_e32 v36, v78
	v_cvt_f32_ubyte2_e32 v78, v76
	v_pk_mul_f32 v[76:77], v[96:97], s[2:3] op_sel_hi:[1,0]
	v_lshlrev_b32_e32 v96, 16, v44
	v_and_b32_e32 v97, 0xffff0000, v44
	v_pk_mul_f32 v[44:45], v[84:85], v[82:83] op_sel_hi:[0,1]
	v_pk_mul_f32 v[36:37], v[36:37], s[2:3] op_sel_hi:[1,0]
	v_pk_mul_f32 v[78:79], v[78:79], s[2:3] op_sel_hi:[1,0]
	v_pk_mul_f32 v[82:83], v[106:107], s[2:3] op_sel_hi:[1,0]
	v_pk_mul_f32 v[76:77], v[76:77], v[108:109]
	v_pk_mul_f32 v[78:79], v[78:79], v[40:41]
	v_add_co_u32_e32 v48, vcc, s1, v64
	s_waitcnt vmcnt(0)
	v_pk_fma_f32 v[44:45], v[44:45], v[86:87], v[90:91]
	v_pk_fma_f32 v[46:47], v[46:47], v[88:89], v[50:51]
	global_store_dwordx4 v[64:65], v[44:47], off offset:2064
	global_load_dwordx4 v[44:47], v[52:53], off
	v_pk_mul_f32 v[50:51], v[102:103], s[2:3] op_sel_hi:[1,0]
	v_pk_mul_f32 v[86:87], v[104:105], s[2:3] op_sel_hi:[1,0]
	v_lshlrev_b32_e32 v88, 16, v42
	v_and_b32_e32 v89, 0xffff0000, v42
	v_lshlrev_b32_e32 v42, 16, v43
	v_and_b32_e32 v43, 0xffff0000, v43
	v_pk_mul_f32 v[90:91], v[36:37], v[96:97]
	v_pk_mul_f32 v[96:97], v[98:99], v[110:111]
	v_pk_mul_f32 v[98:99], v[100:101], v[112:113]
	v_pk_mul_f32 v[50:51], v[50:51], v[80:81]
	v_pk_mul_f32 v[36:37], v[86:87], v[42:43]
	v_pk_mul_f32 v[40:41], v[82:83], v[88:89]
	v_pk_mul_f32 v[42:43], v[76:77], v[76:77]
	v_pk_mul_f32 v[80:81], v[90:91], v[90:91]
	v_pk_mul_f32 v[82:83], v[98:99], v[98:99]
	v_pk_mul_f32 v[86:87], v[96:97], v[96:97]
	v_pk_mov_b32 v[100:101], v[80:81], v[42:43] op_sel:[1,0]
	v_mov_b32_e32 v81, v43
	v_pk_mov_b32 v[42:43], v[86:87], v[82:83] op_sel:[1,0]
	v_mov_b32_e32 v87, v83
	v_mul_f32_e32 v84, v51, v51
	v_mul_f32_e32 v88, v79, v79
	v_pk_add_f32 v[80:81], v[100:101], v[80:81]
	v_pk_add_f32 v[42:43], v[42:43], v[86:87]
	v_mul_f32_e32 v102, v40, v40
	v_mul_f32_e32 v103, v41, v41
	v_mul_f32_e32 v104, v36, v36
	v_mul_f32_e32 v105, v37, v37
	v_pk_fma_f32 v[82:83], v[50:51], v[50:51], v[84:85] op_sel_hi:[1,1,0]
	v_pk_fma_f32 v[88:89], v[78:79], v[78:79], v[88:89] op_sel_hi:[1,1,0]
	v_pk_add_f32 v[80:81], v[80:81], v[80:81] op_sel:[0,1] op_sel_hi:[1,0]
	v_pk_add_f32 v[42:43], v[42:43], v[42:43] op_sel:[0,1] op_sel_hi:[1,0]
	v_mov_b32_e32 v83, v104
	v_mov_b32_e32 v89, v105
	v_mov_b32_e32 v81, v102
	v_mov_b32_e32 v43, v103
	v_pk_add_f32 v[82:83], v[82:83], v[88:89]
	v_pk_add_f32 v[42:43], v[80:81], v[42:43]
	v_addc_co_u32_e32 v49, vcc, 0, v65, vcc
	v_pk_add_f32 v[42:43], v[42:43], v[82:83]
	v_cvt_f32_ubyte1_e32 v87, v72
	v_add_f32_e32 v42, v42, v43
	v_cvt_f32_ubyte0_e32 v86, v72
	v_cvt_f32_ubyte3_e32 v89, v73
	v_add_f32_dpp v42, v42, v42 quad_perm:[1,0,3,2] row_mask:0xf bank_mask:0xf bound_ctrl:1
	v_cvt_f32_ubyte2_e32 v88, v73
	s_nop 0
	v_add_f32_dpp v42, v42, v42 quad_perm:[2,3,0,1] row_mask:0xf bank_mask:0xf bound_ctrl:1
	s_nop 1
	v_add_f32_dpp v42, v42, v42 row_half_mirror row_mask:0xf bank_mask:0xf bound_ctrl:1
	s_nop 1
	v_add_f32_dpp v42, v42, v42 row_mirror row_mask:0xf bank_mask:0xf bound_ctrl:1
	s_nop 0
	v_readlane_b32 s11, v42, 16
	v_readlane_b32 s14, v42, 48
	v_readlane_b32 s12, v42, 0
	v_readlane_b32 s13, v42, 32
	v_mov_b32_e32 v42, s11
	v_mov_b32_e32 v43, s14
	v_pk_add_f32 v[42:43], s[12:13], v[42:43]
	s_nop 0
	v_add_f32_e32 v42, v42, v43
	v_fmamk_f32 v42, v42, 0x3a800000, v85
	v_rsq_f32_e32 v42, v42
	s_nop 0
	v_pk_mul_f32 v[76:77], v[42:43], v[76:77] op_sel_hi:[0,1]
	v_pk_mul_f32 v[80:81], v[42:43], v[90:91] op_sel_hi:[0,1]
	v_pk_mul_f32 v[82:83], v[42:43], v[96:97] op_sel_hi:[0,1]
	v_pk_mul_f32 v[50:51], v[42:43], v[50:51] op_sel_hi:[0,1]
	v_cvt_f32_ubyte1_e32 v91, v73
	v_cvt_f32_ubyte0_e32 v90, v73
	v_pk_mul_f32 v[36:37], v[42:43], v[36:37] op_sel_hi:[0,1]
	s_waitcnt vmcnt(0)
	v_pk_fma_f32 v[44:45], v[80:81], v[44:45], v[92:93]
	v_pk_fma_f32 v[46:47], v[76:77], v[46:47], v[94:95]
	global_store_dwordx4 v[48:49], v[44:47], off
	global_load_dwordx4 v[44:47], v[54:55], off
	v_lshlrev_b32_e32 v76, 16, v38
	v_and_b32_e32 v77, 0xffff0000, v38
	v_lshlrev_b32_e32 v38, 16, v39
	v_and_b32_e32 v39, 0xffff0000, v39
	v_pk_mul_f32 v[80:81], v[42:43], v[98:99] op_sel_hi:[0,1]
	v_lshlrev_b32_e32 v92, 16, v28
	v_and_b32_e32 v93, 0xffff0000, v28
	v_lshlrev_b32_e32 v28, 16, v29
	v_and_b32_e32 v29, 0xffff0000, v29
	s_waitcnt vmcnt(0)
	v_pk_fma_f32 v[44:45], v[82:83], v[44:45], v[76:77]
	v_pk_fma_f32 v[46:47], v[80:81], v[46:47], v[38:39]
	global_store_dwordx4 v[48:49], v[44:47], off offset:16
	global_load_dwordx4 v[44:47], v[56:57], off
	v_lshlrev_b32_e32 v38, 16, v32
	v_and_b32_e32 v39, 0xffff0000, v32
	v_lshlrev_b32_e32 v32, 16, v33
	v_and_b32_e32 v33, 0xffff0000, v33
	v_pk_mul_f32 v[76:77], v[42:43], v[78:79] op_sel_hi:[0,1]
	v_lshlrev_b32_e32 v78, 16, v21
	v_and_b32_e32 v79, 0xffff0000, v21
	v_cvt_f32_ubyte1_e32 v21, v74
	v_cvt_f32_ubyte1_e32 v81, v75
	v_cvt_f32_ubyte0_e32 v80, v75
	v_cvt_f32_ubyte3_e32 v83, v75
	v_cvt_f32_ubyte2_e32 v82, v75
	v_cvt_f32_ubyte3_e32 v75, v72
	v_pk_mul_f32 v[82:83], v[82:83], s[2:3] op_sel_hi:[1,0]
	v_pk_mul_f32 v[80:81], v[80:81], s[2:3] op_sel_hi:[1,0]
	s_waitcnt vmcnt(0)
	v_pk_fma_f32 v[44:45], v[50:51], v[44:45], v[38:39]
	v_pk_fma_f32 v[46:47], v[76:77], v[46:47], v[32:33]
	global_store_dwordx4 v[48:49], v[44:47], off offset:2048
	global_load_dwordx4 v[44:47], v[58:59], off
	v_lshlrev_b32_e32 v38, 16, v34
	v_and_b32_e32 v39, 0xffff0000, v34
	v_lshlrev_b32_e32 v50, 16, v35
	v_and_b32_e32 v51, 0xffff0000, v35
	v_cvt_f32_ubyte3_e32 v35, v74
	v_cvt_f32_ubyte2_e32 v34, v74
	v_lshlrev_b32_e32 v76, 16, v20
	v_and_b32_e32 v77, 0xffff0000, v20
	v_cvt_f32_ubyte0_e32 v20, v74
	v_cvt_f32_ubyte2_e32 v74, v72
	v_pk_mul_f32 v[72:73], v[34:35], s[2:3] op_sel_hi:[1,0]
	v_pk_mul_f32 v[34:35], v[42:43], v[40:41] op_sel_hi:[0,1]
	v_pk_mul_f32 v[20:21], v[20:21], s[2:3] op_sel_hi:[1,0]
	v_pk_mul_f32 v[40:41], v[86:87], s[2:3] op_sel_hi:[1,0]
	v_pk_mul_f32 v[42:43], v[74:75], s[2:3] op_sel_hi:[1,0]
	v_pk_mul_f32 v[74:75], v[20:21], v[92:93]
	v_pk_mul_f32 v[28:29], v[72:73], v[28:29]
	v_add_co_u32_e32 v32, vcc, s3, v64
	s_waitcnt vmcnt(0)
	v_pk_fma_f32 v[34:35], v[34:35], v[44:45], v[38:39]
	v_pk_fma_f32 v[36:37], v[36:37], v[46:47], v[50:51]
	global_store_dwordx4 v[48:49], v[34:37], off offset:2064
	global_load_dwordx4 v[34:37], v[52:53], off
	v_lshlrev_b32_e32 v38, 16, v30
	v_and_b32_e32 v39, 0xffff0000, v30
	v_lshlrev_b32_e32 v30, 16, v31
	v_and_b32_e32 v31, 0xffff0000, v31
	v_lshlrev_b32_e32 v44, 16, v24
	v_and_b32_e32 v45, 0xffff0000, v24
	v_lshlrev_b32_e32 v24, 16, v25
	v_and_b32_e32 v25, 0xffff0000, v25
	v_pk_mul_f32 v[46:47], v[90:91], s[2:3] op_sel_hi:[1,0]
	v_pk_mul_f32 v[48:49], v[88:89], s[2:3] op_sel_hi:[1,0]
	v_lshlrev_b32_e32 v50, 16, v26
	v_and_b32_e32 v51, 0xffff0000, v26
	v_lshlrev_b32_e32 v26, 16, v27
	v_and_b32_e32 v27, 0xffff0000, v27
	v_pk_mul_f32 v[38:39], v[80:81], v[38:39]
	v_pk_mul_f32 v[72:73], v[82:83], v[30:31]
	v_pk_mul_f32 v[42:43], v[42:43], v[24:25]
	v_pk_mul_f32 v[40:41], v[40:41], v[44:45]
	v_pk_mul_f32 v[20:21], v[48:49], v[26:27]
	v_pk_mul_f32 v[24:25], v[46:47], v[50:51]
	v_pk_mul_f32 v[26:27], v[28:29], v[28:29]
	v_pk_mul_f32 v[30:31], v[74:75], v[74:75]
	v_pk_mul_f32 v[44:45], v[72:73], v[72:73]
	v_pk_mul_f32 v[46:47], v[38:39], v[38:39]
	v_pk_mov_b32 v[80:81], v[30:31], v[26:27] op_sel:[1,0]
	v_mov_b32_e32 v31, v27
	v_pk_mov_b32 v[26:27], v[46:47], v[44:45] op_sel:[1,0]
	v_mov_b32_e32 v47, v45
	v_mul_f32_e32 v51, v24, v24
	v_mul_f32_e32 v48, v41, v41
	v_mul_f32_e32 v50, v43, v43
	v_pk_add_f32 v[30:31], v[80:81], v[30:31]
	v_pk_add_f32 v[26:27], v[26:27], v[46:47]
	v_mul_f32_e32 v82, v25, v25
	v_mul_f32_e32 v83, v20, v20
	v_mul_f32_e32 v84, v21, v21
	v_pk_fma_f32 v[44:45], v[40:41], v[40:41], v[48:49] op_sel_hi:[1,1,0]
	v_pk_fma_f32 v[48:49], v[42:43], v[42:43], v[50:51] op_sel_hi:[1,1,0]
	v_pk_add_f32 v[30:31], v[30:31], v[30:31] op_sel:[0,1] op_sel_hi:[1,0]
	v_pk_add_f32 v[26:27], v[26:27], v[26:27] op_sel:[0,1] op_sel_hi:[1,0]
	v_mov_b32_e32 v45, v83
	v_mov_b32_e32 v49, v84
	v_mov_b32_e32 v31, v51
	v_mov_b32_e32 v27, v82
	v_pk_add_f32 v[44:45], v[44:45], v[48:49]
	v_pk_add_f32 v[26:27], v[30:31], v[26:27]
	v_addc_co_u32_e32 v33, vcc, 0, v65, vcc
	v_pk_add_f32 v[26:27], v[26:27], v[44:45]
	v_cvt_f32_ubyte3_e32 v45, v68
	v_add_f32_e32 v26, v26, v27
	v_cvt_f32_ubyte2_e32 v44, v68
	v_cvt_f32_ubyte1_e32 v47, v68
	v_add_f32_dpp v26, v26, v26 quad_perm:[1,0,3,2] row_mask:0xf bank_mask:0xf bound_ctrl:1
	v_cvt_f32_ubyte0_e32 v46, v68
	v_cvt_f32_ubyte3_e32 v49, v69
	v_add_f32_dpp v26, v26, v26 quad_perm:[2,3,0,1] row_mask:0xf bank_mask:0xf bound_ctrl:1
	v_cvt_f32_ubyte2_e32 v48, v69
	v_cvt_f32_ubyte1_e32 v51, v69
	v_add_f32_dpp v26, v26, v26 row_half_mirror row_mask:0xf bank_mask:0xf bound_ctrl:1
	v_cvt_f32_ubyte0_e32 v50, v69
	v_lshlrev_b32_e32 v68, 16, v12
	v_add_f32_dpp v26, v26, v26 row_mirror row_mask:0xf bank_mask:0xf bound_ctrl:1
	v_and_b32_e32 v69, 0xffff0000, v12
	v_readlane_b32 s11, v26, 16
	v_readlane_b32 s14, v26, 48
	v_readlane_b32 s12, v26, 0
	v_readlane_b32 s13, v26, 32
	v_mov_b32_e32 v26, s11
	v_mov_b32_e32 v27, s14
	v_pk_add_f32 v[26:27], s[12:13], v[26:27]
	v_lshlrev_b32_e32 v12, 16, v13
	v_add_f32_e32 v26, v26, v27
	v_fmamk_f32 v26, v26, 0x3a800000, v85
	v_rsq_f32_e32 v26, v26
	v_and_b32_e32 v13, 0xffff0000, v13
	v_pk_mul_f32 v[30:31], v[26:27], v[28:29] op_sel_hi:[0,1]
	v_pk_mul_f32 v[28:29], v[26:27], v[74:75] op_sel_hi:[0,1]
	s_waitcnt vmcnt(0)
	v_pk_fma_f32 v[28:29], v[28:29], v[34:35], v[76:77]
	v_pk_fma_f32 v[30:31], v[30:31], v[36:37], v[78:79]
	global_store_dwordx4 v[32:33], v[28:31], off
	global_load_dwordx4 v[28:31], v[54:55], off
	v_lshlrev_b32_e32 v34, 16, v22
	v_and_b32_e32 v35, 0xffff0000, v22
	v_lshlrev_b32_e32 v22, 16, v23
	v_and_b32_e32 v23, 0xffff0000, v23
	v_pk_mul_f32 v[36:37], v[26:27], v[72:73] op_sel_hi:[0,1]
	v_pk_mul_f32 v[38:39], v[26:27], v[38:39] op_sel_hi:[0,1]
	v_pk_mul_f32 v[20:21], v[26:27], v[20:21] op_sel_hi:[0,1]
	v_pk_mul_f32 v[24:25], v[26:27], v[24:25] op_sel_hi:[0,1]
	s_waitcnt vmcnt(0)
	v_pk_fma_f32 v[28:29], v[38:39], v[28:29], v[34:35]
	v_pk_fma_f32 v[30:31], v[36:37], v[30:31], v[22:23]
	global_store_dwordx4 v[32:33], v[28:31], off offset:16
	global_load_dwordx4 v[28:31], v[56:57], off
	v_lshlrev_b32_e32 v22, 16, v16
	v_and_b32_e32 v23, 0xffff0000, v16
	v_lshlrev_b32_e32 v16, 16, v17
	v_and_b32_e32 v17, 0xffff0000, v17
	v_pk_mul_f32 v[34:35], v[26:27], v[42:43] op_sel_hi:[0,1]
	v_pk_mul_f32 v[36:37], v[26:27], v[40:41] op_sel_hi:[0,1]
	v_cvt_f32_ubyte3_e32 v39, v70
	v_cvt_f32_ubyte2_e32 v38, v70
	v_cvt_f32_ubyte1_e32 v41, v71
	v_cvt_f32_ubyte0_e32 v40, v71
	v_cvt_f32_ubyte3_e32 v43, v71
	v_cvt_f32_ubyte2_e32 v42, v71
	v_pk_mul_f32 v[38:39], v[38:39], s[2:3] op_sel_hi:[1,0]
	v_lshlrev_b32_e32 v26, 16, v14
	v_and_b32_e32 v27, 0xffff0000, v14
	v_lshlrev_b32_e32 v14, 16, v15
	v_and_b32_e32 v15, 0xffff0000, v15
	v_pk_mul_f32 v[12:13], v[38:39], v[12:13]
	s_waitcnt vmcnt(0)
	v_pk_fma_f32 v[28:29], v[36:37], v[28:29], v[22:23]
	v_pk_fma_f32 v[30:31], v[34:35], v[30:31], v[16:17]
	global_store_dwordx4 v[32:33], v[28:31], off offset:2048
	global_load_dwordx4 v[28:31], v[58:59], off
	v_lshlrev_b32_e32 v16, 16, v18
	v_and_b32_e32 v17, 0xffff0000, v18
	v_lshlrev_b32_e32 v18, 16, v19
	v_and_b32_e32 v19, 0xffff0000, v19
	v_cvt_f32_ubyte1_e32 v37, v70
	v_cvt_f32_ubyte0_e32 v36, v70
	v_pk_mul_f32 v[36:37], v[36:37], s[2:3] op_sel_hi:[1,0]
	v_add_co_u32_e32 v22, vcc, s10, v64
	v_pk_mul_f32 v[36:37], v[36:37], v[68:69]
	v_lshlrev_b32_e32 v34, 16, v4
	v_and_b32_e32 v35, 0xffff0000, v4
	v_lshlrev_b32_e32 v4, 16, v5
	v_and_b32_e32 v5, 0xffff0000, v5
	v_addc_co_u32_e32 v23, vcc, 0, v65, vcc
	v_lshl_add_u64 v[64:65], v[64:65], 0, s[6:7]
	s_waitcnt vmcnt(0)
	v_pk_fma_f32 v[16:17], v[24:25], v[28:29], v[16:17]
	v_pk_fma_f32 v[18:19], v[20:21], v[30:31], v[18:19]
	global_store_dwordx4 v[32:33], v[16:19], off offset:2064
	global_load_dwordx4 v[16:19], v[52:53], off
	v_pk_mul_f32 v[20:21], v[42:43], s[2:3] op_sel_hi:[1,0]
	v_pk_mul_f32 v[24:25], v[40:41], s[2:3] op_sel_hi:[1,0]
	v_pk_mul_f32 v[28:29], v[46:47], s[2:3] op_sel_hi:[1,0]
	v_pk_mul_f32 v[30:31], v[44:45], s[2:3] op_sel_hi:[1,0]
	v_lshlrev_b32_e32 v32, 16, v8
	v_and_b32_e32 v33, 0xffff0000, v8
	v_lshlrev_b32_e32 v8, 16, v9
	v_and_b32_e32 v9, 0xffff0000, v9
	v_pk_mul_f32 v[42:43], v[48:49], s[2:3] op_sel_hi:[1,0]
	v_lshlrev_b32_e32 v44, 16, v10
	v_and_b32_e32 v45, 0xffff0000, v10
	v_lshlrev_b32_e32 v10, 16, v11
	v_and_b32_e32 v11, 0xffff0000, v11
	v_pk_mul_f32 v[24:25], v[24:25], v[26:27]
	v_pk_mul_f32 v[14:15], v[20:21], v[14:15]
	v_pk_mul_f32 v[40:41], v[50:51], s[2:3] op_sel_hi:[1,0]
	v_pk_mul_f32 v[20:21], v[30:31], v[8:9]
	v_pk_mul_f32 v[26:27], v[28:29], v[32:33]
	v_pk_mul_f32 v[28:29], v[42:43], v[10:11]
	v_pk_mul_f32 v[8:9], v[12:13], v[12:13]
	v_pk_mul_f32 v[10:11], v[36:37], v[36:37]
	v_pk_mul_f32 v[32:33], v[14:15], v[14:15]
	v_pk_mul_f32 v[38:39], v[24:25], v[24:25]
	v_pk_mul_f32 v[30:31], v[40:41], v[44:45]
	v_pk_mov_b32 v[44:45], v[10:11], v[8:9] op_sel:[1,0]
	v_mov_b32_e32 v11, v9
	v_pk_mov_b32 v[8:9], v[38:39], v[32:33] op_sel:[1,0]
	v_mov_b32_e32 v39, v33
	v_mul_f32_e32 v43, v30, v30
	v_mul_f32_e32 v40, v27, v27
	v_mul_f32_e32 v42, v21, v21
	v_pk_add_f32 v[10:11], v[44:45], v[10:11]
	v_pk_add_f32 v[8:9], v[8:9], v[38:39]
	v_mul_f32_e32 v46, v31, v31
	v_mul_f32_e32 v47, v28, v28
	v_mul_f32_e32 v48, v29, v29
	v_pk_fma_f32 v[32:33], v[26:27], v[26:27], v[40:41] op_sel_hi:[1,1,0]
	v_pk_fma_f32 v[40:41], v[20:21], v[20:21], v[42:43] op_sel_hi:[1,1,0]
	v_pk_add_f32 v[10:11], v[10:11], v[10:11] op_sel:[0,1] op_sel_hi:[1,0]
	v_pk_add_f32 v[8:9], v[8:9], v[8:9] op_sel:[0,1] op_sel_hi:[1,0]
	v_mov_b32_e32 v33, v47
	v_mov_b32_e32 v41, v48
	v_mov_b32_e32 v11, v43
	v_mov_b32_e32 v9, v46
	v_pk_add_f32 v[32:33], v[32:33], v[40:41]
	v_pk_add_f32 v[8:9], v[10:11], v[8:9]
	s_nop 0
	v_pk_add_f32 v[8:9], v[8:9], v[32:33]
	s_nop 0
	v_add_f32_e32 v8, v8, v9
	s_nop 1
	v_add_f32_dpp v8, v8, v8 quad_perm:[1,0,3,2] row_mask:0xf bank_mask:0xf bound_ctrl:1
	s_nop 1
	v_add_f32_dpp v8, v8, v8 quad_perm:[2,3,0,1] row_mask:0xf bank_mask:0xf bound_ctrl:1
	s_nop 1
	v_add_f32_dpp v8, v8, v8 row_half_mirror row_mask:0xf bank_mask:0xf bound_ctrl:1
	s_nop 1
	v_add_f32_dpp v8, v8, v8 row_mirror row_mask:0xf bank_mask:0xf bound_ctrl:1
	s_nop 0
	v_readlane_b32 s11, v8, 16
	v_readlane_b32 s14, v8, 48
	v_readlane_b32 s12, v8, 0
	v_readlane_b32 s13, v8, 32
	v_mov_b32_e32 v8, s11
	v_mov_b32_e32 v9, s14
	v_pk_add_f32 v[8:9], s[12:13], v[8:9]
	s_nop 0
	v_add_f32_e32 v8, v8, v9
	v_fmamk_f32 v8, v8, 0x3a800000, v85
	v_rsq_f32_e32 v32, v8
	s_nop 0
	v_pk_mul_f32 v[10:11], v[32:33], v[12:13] op_sel_hi:[0,1]
	v_pk_mul_f32 v[8:9], v[32:33], v[36:37] op_sel_hi:[0,1]
	s_waitcnt vmcnt(0)
	v_pk_fma_f32 v[8:9], v[8:9], v[16:17], v[34:35]
	v_pk_fma_f32 v[10:11], v[10:11], v[18:19], v[4:5]
	global_store_dwordx4 v[22:23], v[8:11], off
	global_load_dwordx4 v[8:11], v[54:55], off
	v_lshlrev_b32_e32 v4, 16, v6
	v_and_b32_e32 v5, 0xffff0000, v6
	v_lshlrev_b32_e32 v6, 16, v7
	v_and_b32_e32 v7, 0xffff0000, v7
	v_pk_mul_f32 v[12:13], v[32:33], v[14:15] op_sel_hi:[0,1]
	v_pk_mul_f32 v[14:15], v[32:33], v[24:25] op_sel_hi:[0,1]
	s_waitcnt vmcnt(0)
	v_pk_fma_f32 v[4:5], v[14:15], v[8:9], v[4:5]
	v_pk_fma_f32 v[6:7], v[12:13], v[10:11], v[6:7]
	global_store_dwordx4 v[22:23], v[4:7], off offset:16
	global_load_dwordx4 v[4:7], v[56:57], off
	v_lshlrev_b32_e32 v8, 16, v0
	v_and_b32_e32 v9, 0xffff0000, v0
	v_lshlrev_b32_e32 v0, 16, v1
	v_and_b32_e32 v1, 0xffff0000, v1
	v_pk_mul_f32 v[10:11], v[32:33], v[20:21] op_sel_hi:[0,1]
	v_pk_mul_f32 v[12:13], v[32:33], v[26:27] op_sel_hi:[0,1]
	s_waitcnt vmcnt(0)
	v_pk_fma_f32 v[4:5], v[12:13], v[4:5], v[8:9]
	v_pk_fma_f32 v[6:7], v[10:11], v[6:7], v[0:1]
	global_store_dwordx4 v[22:23], v[4:7], off offset:2048
	global_load_dwordx4 v[4:7], v[58:59], off
	v_lshlrev_b32_e32 v0, 16, v2
	v_and_b32_e32 v1, 0xffff0000, v2
	v_lshlrev_b32_e32 v2, 16, v3
	v_and_b32_e32 v3, 0xffff0000, v3
	v_pk_mul_f32 v[8:9], v[32:33], v[28:29] op_sel_hi:[0,1]
	v_pk_mul_f32 v[10:11], v[32:33], v[30:31] op_sel_hi:[0,1]
	s_waitcnt vmcnt(0)
	v_pk_fma_f32 v[0:1], v[10:11], v[4:5], v[0:1]
	v_pk_fma_f32 v[2:3], v[8:9], v[6:7], v[2:3]
	global_store_dwordx4 v[22:23], v[0:3], off offset:2064
	s_cbranch_scc0 .LBB0_1761
